# v12 + sample mLSTM step: thread owns state-row elements 16j+4part instead of 32part+4j so a row's four lanes access 64 contiguous bytes per load/store (f32 sums over the same elements, different assoc
# speedup vs baseline: 1.0154x; 1.0154x over previous
.LBB0_380:
	s_and_b64 vcc, exec, s[0:1]
	v_lshlrev_b32_e32 v111, 2, v109
	s_waitcnt vmcnt(26)
	v_lshlrev_b32_e32 v96, 4, v109
	s_cbranch_vccz .LBB0_398
	s_lshl_b32 s86, s69, 2
	s_add_u32 s0, s28, s86
	s_addc_u32 s1, s29, 0
	s_add_u32 s23, s0, 0x2fc3000
	s_addc_u32 s33, s1, 0
	s_lshl_b32 s74, s64, 2
	s_or_b32 s0, s74, s69
	s_ashr_i32 s1, s0, 31
	s_ashr_i32 s65, s64, 31
	s_lshl_b64 s[78:79], s[0:1], 16
	s_lshl_b64 s[2:3], s[64:65], 5
	v_readlane_b32 s36, v255, 1
	s_add_u32 s2, s23, s2
	v_readlane_b32 s50, v255, 15
	s_addc_u32 s3, s33, s3
	s_lshl_b64 s[20:21], s[0:1], 2
	v_lshrrev_b32_e32 v103, 2, v128
	v_readlane_b32 s51, v255, 16
	s_add_u32 s20, s50, s20
	v_mov_b32_e32 v65, 0
	v_lshlrev_b32_e32 v64, 9, v103
	v_readlane_b32 s46, v255, 11
	v_readlane_b32 s47, v255, 12
	s_addc_u32 s21, s51, s21
	s_lshl_b64 s[76:77], s[0:1], 9
	s_lshl_b32 s0, s72, 2
	s_waitcnt lgkmcnt(0)
	v_and_b32_e32 v2, 0x7f, v128
	v_lshl_add_u64 v[0:1], s[46:47], 0, v[64:65]
	v_mov_b32_e32 v97, v65
	s_or_b32 s58, s0, s69
	v_readlane_b32 s48, v255, 13
	v_readlane_b32 s49, v255, 14
	v_lshl_add_u64 v[0:1], v[0:1], 0, v[96:97]
	v_lshlrev_b32_e32 v64, 2, v2
	s_ashr_i32 s59, s58, 31
	s_ashr_i32 s73, s72, 31
	v_lshl_add_u64 v[66:67], s[48:49], 0, v[64:65]
	v_lshl_add_u64 v[2:3], v[0:1], 0, s[78:79]
	s_lshl_b64 s[70:71], s[58:59], 16
	s_lshl_b64 s[80:81], s[72:73], 5
	global_load_dwordx4 v[48:51], v[2:3], off offset:192
	global_load_dwordx4 v[52:55], v[2:3], off offset:128
	global_load_dwordx4 v[56:59], v[2:3], off offset:64
	global_load_dwordx4 v[60:63], v[2:3], off
	global_load_dwordx4 v[32:35], v[2:3], off offset:448
	global_load_dwordx4 v[36:39], v[2:3], off offset:384
	global_load_dwordx4 v[40:43], v[2:3], off offset:320
	global_load_dwordx4 v[44:47], v[2:3], off offset:256
	v_lshl_add_u64 v[2:3], v[66:67], 0, s[76:77]
	v_lshl_add_u64 v[12:13], v[0:1], 0, s[70:71]
	s_add_u32 s80, s23, s80
	global_load_dword v102, v[2:3], off
	global_load_dwordx4 v[16:19], v[12:13], off offset:192
	global_load_dwordx4 v[20:23], v[12:13], off offset:128
	global_load_dwordx4 v[24:27], v[12:13], off offset:64
	global_load_dwordx4 v[28:31], v[12:13], off
	s_nop 0
	global_load_dwordx4 v[0:3], v[12:13], off offset:448
	global_load_dwordx4 v[4:7], v[12:13], off offset:384
	global_load_dwordx4 v[8:11], v[12:13], off offset:320
	s_nop 0
	global_load_dwordx4 v[12:15], v[12:13], off offset:256
	s_addc_u32 s81, s33, s81
	s_lshl_b64 s[88:89], s[58:59], 2
	s_add_u32 s88, s50, s88
	s_addc_u32 s89, s51, s89
	global_load_dword v106, v65, s[2:3]
	global_load_dword v120, v65, s[2:3] offset:16
	global_load_dword v107, v65, s[20:21]
	global_load_dword v99, v65, s[80:81]
	global_load_dword v118, v65, s[80:81] offset:16
	global_load_dword v115, v65, s[88:89]
	s_lshl_b64 s[58:59], s[58:59], 9
	v_add_u32_e32 v64, s68, v103
	v_lshl_add_u64 v[66:67], v[66:67], 0, s[58:59]
	v_lshlrev_b32_e32 v97, 1, v64
	global_load_dword v98, v[66:67], off
	global_load_ushort v114, v97, s[4:5] offset:3072
	global_load_ushort v113, v97, s[6:7] offset:3072
	v_lshlrev_b32_e32 v64, 2, v64
	global_load_dword v112, v64, s[66:67]
	s_movk_i32 s1, 0x80
	s_mov_b32 s75, s93
	v_lshlrev_b32_e32 v66, 7, v103
	v_cmp_gt_u32_e64 s[2:3], s1, v128
	v_readlane_b32 s37, v255, 2
	v_readlane_b32 s38, v255, 3
	v_readlane_b32 s39, v255, 4
	v_readlane_b32 s40, v255, 5
	v_readlane_b32 s41, v255, 6
	v_readlane_b32 s42, v255, 7
	v_readlane_b32 s43, v255, 8
	v_readlane_b32 s44, v255, 9
	v_readlane_b32 s45, v255, 10
	s_and_saveexec_b64 s[80:81], s[2:3]
	s_cbranch_execz .LBB0_383
	v_or_b32_e32 v67, s68, v128
	v_lshlrev_b32_e32 v64, 2, v67
	v_lshl_add_u64 v[68:69], s[60:61], 0, v[64:65]
	v_readlane_b32 s36, v255, 1
	v_add_co_u32_e32 v70, vcc, 0x3000, v68
	s_mul_i32 s20, s72, 0x3000
	v_readlane_b32 s44, v255, 9
	v_addc_co_u32_e32 v71, vcc, 0, v69, vcc
	s_mul_hi_i32 s21, s72, 0x3000
	v_readlane_b32 s45, v255, 10
	s_add_u32 s20, s44, s20
	v_add_co_u32_e32 v72, vcc, 0x2000, v68
	s_addc_u32 s21, s45, s21
	s_mul_hi_i32 s33, s64, 0x3000
	s_mulk_i32 s64, 0x3000
	v_addc_co_u32_e32 v73, vcc, 0, v69, vcc
	s_add_u32 s64, s44, s64
	v_add_co_u32_e32 v68, vcc, 0x1000, v68
	s_addc_u32 s65, s45, s33
	s_movk_i32 s1, 0x2000
	v_addc_co_u32_e32 v69, vcc, 0, v69, vcc
	v_lshl_add_u64 v[74:75], s[64:65], 0, v[64:65]
	v_add_co_u32_e32 v76, vcc, s1, v74
	s_movk_i32 s23, 0x1000
	s_nop 0
	v_addc_co_u32_e32 v77, vcc, 0, v75, vcc
	v_add_co_u32_e32 v74, vcc, s23, v74
	v_lshlrev_b32_e32 v67, 1, v67
	s_nop 0
	v_addc_co_u32_e32 v75, vcc, 0, v75, vcc
	global_load_dword v78, v64, s[62:63] offset:2048
	global_load_dword v79, v64, s[60:61] offset:2048
	global_load_dword v80, v64, s[62:63]
	global_load_dword v81, v64, s[64:65] offset:2048
	global_load_dword v82, v64, s[64:65]
	global_load_dword v83, v64, s[20:21]
	global_load_dword v84, v64, s[60:61]
	global_load_ushort v85, v67, s[6:7] offset:2048
	global_load_ushort v86, v67, s[4:5] offset:1024
	global_load_ushort v87, v67, s[4:5]
	global_load_dword v88, v[76:77], off offset:2048
	global_load_dword v89, v[74:75], off offset:2048
	s_nop 0
	global_load_dword v74, v[74:75], off
	s_nop 0
	global_load_dword v75, v[76:77], off
	s_nop 0
	global_load_dword v76, v[68:69], off
	global_load_dword v77, v[68:69], off offset:2048
	global_load_dword v90, v[72:73], off
	s_nop 0
	global_load_dword v72, v[72:73], off offset:2048
	s_nop 0
	global_load_dword v73, v[70:71], off
	global_load_dword v91, v[70:71], off offset:2048
	global_load_ushort v92, v67, s[6:7] offset:1024
	global_load_ushort v93, v67, s[6:7]
	s_nop 0
	global_load_ushort v67, v67, s[4:5] offset:2048
	v_lshl_add_u64 v[68:69], s[20:21], 0, v[64:65]
	v_add_co_u32_e32 v70, vcc, s1, v68
	v_readlane_b32 s37, v255, 2
	s_nop 0
	v_addc_co_u32_e32 v71, vcc, 0, v69, vcc
	v_add_co_u32_e32 v68, vcc, s23, v68
	v_readlane_b32 s38, v255, 3
	s_nop 0
	v_addc_co_u32_e32 v69, vcc, 0, v69, vcc
	global_load_dword v94, v[68:69], off
	global_load_dword v95, v[70:71], off
	s_nop 0
	global_load_dword v64, v64, s[20:21] offset:2048
	s_nop 0
	global_load_dword v68, v[68:69], off offset:2048
	s_nop 0
	global_load_dword v69, v[70:71], off offset:2048
	v_lshl_add_u32 v70, v128, 2, 0
	v_readlane_b32 s39, v255, 4
	v_readlane_b32 s40, v255, 5
	v_readlane_b32 s41, v255, 6
	v_readlane_b32 s42, v255, 7
	v_readlane_b32 s43, v255, 8
	v_readlane_b32 s46, v255, 11
	v_readlane_b32 s47, v255, 12
	v_readlane_b32 s48, v255, 13
	v_readlane_b32 s49, v255, 14
	v_readlane_b32 s50, v255, 15
	v_readlane_b32 s51, v255, 16
	s_waitcnt vmcnt(20)
	v_lshlrev_b32_e32 v71, 16, v85
	s_waitcnt vmcnt(19)
	v_lshlrev_b32_e32 v85, 16, v86
	s_waitcnt vmcnt(18)
	v_lshlrev_b32_e32 v86, 16, v87
	v_fma_f32 v81, v79, v81, v78
	s_waitcnt vmcnt(12)
	v_fmac_f32_e32 v81, v77, v89
	s_waitcnt vmcnt(10)
	v_fmac_f32_e32 v81, v72, v88
	v_fma_f32 v82, v84, v82, v80
	v_fmac_f32_e32 v82, v76, v74
	v_fmac_f32_e32 v82, v90, v75
	s_waitcnt vmcnt(8)
	v_fmac_f32_e32 v81, v91, v85
	v_fmac_f32_e32 v80, v84, v83
	v_fmac_f32_e32 v82, v73, v86
	v_mul_f32_e32 v75, 0xbfb8aa3b, v81
	s_waitcnt vmcnt(7)
	v_lshlrev_b32_e32 v85, 16, v92
	v_mul_f32_e32 v74, 0xbfb8aa3b, v82
	s_waitcnt vmcnt(4)
	v_fmac_f32_e32 v80, v76, v94
	v_exp_f32_e32 v75, v75
	s_waitcnt vmcnt(2)
	v_fmac_f32_e32 v78, v79, v64
	s_waitcnt vmcnt(1)
	v_fmac_f32_e32 v78, v77, v68
	s_waitcnt vmcnt(0)
	v_fmac_f32_e32 v78, v72, v69
	v_lshlrev_b32_e32 v86, 16, v93
	v_fmac_f32_e32 v80, v90, v95
	v_fmac_f32_e32 v78, v91, v85
	v_exp_f32_e32 v74, v74
	v_fmac_f32_e32 v80, v73, v86
	v_mul_f32_e32 v68, 0xbfb8aa3b, v78
	v_mul_f32_e32 v64, 0xbfb8aa3b, v80
	v_exp_f32_e32 v68, v68
	v_exp_f32_e32 v64, v64
	v_add_f32_e32 v75, 1.0, v75
	v_add_f32_e32 v74, 1.0, v74
	v_rcp_f32_e32 v75, v75
	v_rcp_f32_e32 v74, v74
	v_add_f32_e32 v68, 1.0, v68
	v_add_f32_e32 v64, 1.0, v64
	v_rcp_f32_e32 v68, v68
	v_rcp_f32_e32 v64, v64
	v_mul_f32_e32 v75, v81, v75
	v_lshlrev_b32_e32 v67, 16, v67
	v_mul_f32_e32 v74, v82, v74
	v_mul_f32_e32 v69, 0x3db504f3, v75
	ds_write2st64_b32 v70, v74, v69 offset1:2
	ds_write2st64_b32 v70, v67, v102 offset0:4 offset1:6
	v_mul_f32_e32 v67, v78, v68
	v_mul_f32_e32 v64, v80, v64
	v_mul_f32_e32 v67, 0x3db504f3, v67
	ds_write2st64_b32 v70, v64, v67 offset0:8 offset1:10
	ds_write2st64_b32 v70, v71, v98 offset0:12 offset1:14
.LBB0_383:
	s_or_b64 exec, exec, s[80:81]
	v_lshlrev_b32_e32 v64, 2, v66
	v_lshl_add_u64 v[66:67], s[26:27], 0, v[64:65]
	v_lshlrev_b32_e32 v64, 2, v111
	v_lshl_add_u64 v[66:67], v[66:67], 0, v[64:65]
	v_mbcnt_lo_u32_b32 v65, -1, 0
	s_mov_b64 s[4:5], 0x561c080
	v_mbcnt_hi_u32_b32 v121, -1, v65
	v_lshl_add_u64 v[100:101], v[66:67], 0, s[4:5]
	v_and_b32_e32 v66, 64, v121
	v_xor_b32_e32 v65, 1, v121
	v_add_u32_e32 v122, 64, v66
	v_cmp_lt_i32_e32 vcc, v65, v122
	s_waitcnt lgkmcnt(0)
	s_barrier
	v_add_u32_e32 v119, 0, v64
	v_cndmask_b32_e32 v65, v121, v65, vcc
	v_lshlrev_b32_e32 v116, 2, v65
	v_xor_b32_e32 v65, 2, v121
	v_cmp_lt_i32_e32 vcc, v65, v122
	s_mov_b32 s1, 0xbfb8aa3b
	s_nop 0
	v_cndmask_b32_e32 v65, v121, v65, vcc
	v_lshlrev_b32_e32 v117, 2, v65
	ds_read_b128 v[72:75], v119
	ds_read_b128 v[76:79], v119 offset:64
	ds_read_b128 v[64:67], v119 offset:512
	s_waitcnt vmcnt(34)
	ds_read_b128 v[80:83], v119 offset:128
	s_waitcnt vmcnt(33)
	ds_read_b128 v[84:87], v119 offset:192
	ds_read_b128 v[88:91], v119 offset:1536
	ds_read_b128 v[68:71], v119 offset:576
	s_waitcnt lgkmcnt(4)
	v_mul_f32_e32 v92, v73, v65
	v_mul_f32_e32 v93, v75, v67
	v_fmac_f32_e32 v92, v72, v64
	v_fmac_f32_e32 v93, v74, v66
	s_waitcnt lgkmcnt(1)
	v_mul_f32_e32 v89, v73, v89
	s_waitcnt vmcnt(23)
	v_mul_f32_e32 v73, v61, v73
	v_add_f32_e32 v92, v92, v93
	v_fmac_f32_e32 v89, v72, v88
	v_fmac_f32_e32 v73, v60, v72
	v_mul_f32_e32 v72, v63, v75
	v_add_f32_e32 v104, 0, v92
	ds_read_b128 v[92:95], v119 offset:1600
	v_mul_f32_e32 v88, v75, v91
	v_fmac_f32_e32 v72, v62, v74
	v_fmac_f32_e32 v88, v74, v90
	v_add_f32_e32 v72, v73, v72
	v_add_f32_e32 v88, v89, v88
	v_add_f32_e32 v89, 0, v72
	s_waitcnt lgkmcnt(1)
	v_mul_f32_e32 v72, v77, v69
	v_mul_f32_e32 v73, v79, v71
	v_fmac_f32_e32 v72, v76, v68
	v_fmac_f32_e32 v73, v78, v70
	v_add_f32_e32 v72, v72, v73
	v_add_f32_e32 v104, v104, v72
	s_waitcnt lgkmcnt(0)
	v_mul_f32_e32 v72, v77, v93
	v_mul_f32_e32 v73, v79, v95
	v_fmac_f32_e32 v72, v76, v92
	v_fmac_f32_e32 v73, v78, v94
	v_mul_f32_e32 v77, v57, v77
	v_add_f32_e32 v88, 0, v88
	v_add_f32_e32 v72, v72, v73
	v_fmac_f32_e32 v77, v56, v76
	v_mul_f32_e32 v76, v59, v79
	v_add_f32_e32 v105, v88, v72
	v_fmac_f32_e32 v76, v58, v78
	ds_read_b128 v[72:75], v119 offset:640
	v_add_f32_e32 v76, v77, v76
	v_add_f32_e32 v123, v89, v76
	ds_read_b128 v[88:91], v119 offset:1664
	ds_read_b128 v[76:79], v119 offset:704
	s_waitcnt lgkmcnt(2)
	v_mul_f32_e32 v92, v81, v73
	v_mul_f32_e32 v93, v83, v75
	v_fmac_f32_e32 v92, v80, v72
	v_fmac_f32_e32 v93, v82, v74
	s_waitcnt lgkmcnt(1)
	v_mul_f32_e32 v89, v81, v89
	v_mul_f32_e32 v81, v53, v81
	v_add_f32_e32 v92, v92, v93
	v_fmac_f32_e32 v89, v80, v88
	v_mul_f32_e32 v88, v83, v91
	v_fmac_f32_e32 v81, v52, v80
	v_mul_f32_e32 v80, v55, v83
	v_add_f32_e32 v104, v104, v92
	ds_read_b128 v[92:95], v119 offset:1728
	v_fmac_f32_e32 v88, v82, v90
	v_fmac_f32_e32 v80, v54, v82
	v_add_f32_e32 v88, v89, v88
	v_add_f32_e32 v80, v81, v80
	v_add_f32_e32 v88, v105, v88
	v_add_f32_e32 v105, v123, v80
	s_waitcnt lgkmcnt(1)
	v_mul_f32_e32 v80, v85, v77
	v_mul_f32_e32 v81, v87, v79
	v_fmac_f32_e32 v80, v84, v76
	v_fmac_f32_e32 v81, v86, v78
	v_add_f32_e32 v80, v80, v81
	v_add_f32_e32 v104, v104, v80
	s_waitcnt lgkmcnt(0)
	v_mul_f32_e32 v80, v85, v93
	v_mul_f32_e32 v81, v87, v95
	v_fmac_f32_e32 v80, v84, v92
	v_fmac_f32_e32 v81, v86, v94
	v_add_f32_e32 v80, v80, v81
	v_add_f32_e32 v123, v88, v80
	v_mul_f32_e32 v80, v49, v85
	v_mul_f32_e32 v81, v51, v87
	v_fmac_f32_e32 v80, v48, v84
	v_fmac_f32_e32 v81, v50, v86
	v_add_f32_e32 v84, v80, v81
	ds_read_b128 v[88:91], v119 offset:256
	ds_read_b128 v[80:83], v119 offset:768
	v_add_f32_e32 v105, v105, v84
	ds_read_b128 v[92:95], v119 offset:1792
	ds_read_b128 v[124:127], v119 offset:320
	ds_read_b128 v[84:87], v119 offset:832
	s_waitcnt lgkmcnt(3)
	v_mul_f32_e32 v130, v89, v81
	v_mul_f32_e32 v131, v91, v83
	v_fmac_f32_e32 v130, v88, v80
	v_fmac_f32_e32 v131, v90, v82
	s_waitcnt lgkmcnt(2)
	v_mul_f32_e32 v93, v89, v93
	s_waitcnt vmcnt(19)
	v_mul_f32_e32 v89, v45, v89
	v_add_f32_e32 v130, v130, v131
	v_fmac_f32_e32 v93, v88, v92
	v_fmac_f32_e32 v89, v44, v88
	v_mul_f32_e32 v88, v47, v91
	v_add_f32_e32 v104, v104, v130
	ds_read_b128 v[130:133], v119 offset:1856
	v_mul_f32_e32 v92, v91, v95
	v_fmac_f32_e32 v88, v46, v90
	v_fmac_f32_e32 v92, v90, v94
	v_add_f32_e32 v88, v89, v88
	v_add_f32_e32 v92, v93, v92
	v_add_f32_e32 v93, v105, v88
	s_waitcnt lgkmcnt(1)
	v_mul_f32_e32 v88, v125, v85
	v_mul_f32_e32 v89, v127, v87
	v_fmac_f32_e32 v88, v124, v84
	v_fmac_f32_e32 v89, v126, v86
	v_add_f32_e32 v88, v88, v89
	v_add_f32_e32 v104, v104, v88
	s_waitcnt lgkmcnt(0)
	v_mul_f32_e32 v88, v125, v131
	v_mul_f32_e32 v89, v127, v133
	v_fmac_f32_e32 v88, v124, v130
	v_fmac_f32_e32 v89, v126, v132
	v_add_f32_e32 v92, v123, v92
	v_add_f32_e32 v88, v88, v89
	v_add_f32_e32 v105, v92, v88
	v_mul_f32_e32 v88, v41, v125
	v_mul_f32_e32 v89, v43, v127
	v_fmac_f32_e32 v88, v40, v124
	v_fmac_f32_e32 v89, v42, v126
	v_add_f32_e32 v92, v88, v89
	ds_read_b128 v[124:127], v119 offset:384
	ds_read_b128 v[88:91], v119 offset:896
	v_add_f32_e32 v123, v93, v92
	ds_read_b128 v[130:133], v119 offset:1920
	ds_read_b128 v[134:137], v119 offset:448
	ds_read_b128 v[92:95], v119 offset:960
	s_waitcnt lgkmcnt(3)
	v_mul_f32_e32 v138, v125, v89
	v_mul_f32_e32 v139, v127, v91
	v_fmac_f32_e32 v138, v124, v88
	v_fmac_f32_e32 v139, v126, v90
	s_waitcnt lgkmcnt(2)
	v_mul_f32_e32 v131, v125, v131
	v_mul_f32_e32 v125, v37, v125
	v_add_f32_e32 v138, v138, v139
	v_fmac_f32_e32 v131, v124, v130
	v_fmac_f32_e32 v125, v36, v124
	v_mul_f32_e32 v124, v39, v127
	v_add_f32_e32 v104, v104, v138
	ds_read_b128 v[138:141], v119 offset:1984
	v_fmac_f32_e32 v124, v38, v126
	v_add_f32_e32 v124, v125, v124
	v_add_f32_e32 v123, v123, v124
	s_waitcnt lgkmcnt(1)
	v_mul_f32_e32 v124, v135, v93
	v_mul_f32_e32 v125, v137, v95
	v_fmac_f32_e32 v124, v134, v92
	v_fmac_f32_e32 v125, v136, v94
	v_mul_f32_e32 v130, v127, v133
	v_add_f32_e32 v124, v124, v125
	v_fmac_f32_e32 v130, v126, v132
	v_add_f32_e32 v124, v104, v124
	s_waitcnt lgkmcnt(0)
	v_mul_f32_e32 v104, v135, v139
	v_mul_f32_e32 v125, v137, v141
	v_add_f32_e32 v130, v131, v130
	v_fmac_f32_e32 v104, v134, v138
	v_fmac_f32_e32 v125, v136, v140
	v_add_f32_e32 v105, v105, v130
	v_add_f32_e32 v104, v104, v125
	v_add_f32_e32 v125, v105, v104
	ds_bpermute_b32 v126, v116, v124
	ds_bpermute_b32 v131, v116, v125
	v_mul_f32_e32 v104, v33, v135
	v_mul_f32_e32 v105, v35, v137
	v_fmac_f32_e32 v104, v32, v134
	v_fmac_f32_e32 v105, v34, v136
	v_add_f32_e32 v104, v104, v105
	v_add_f32_e32 v123, v123, v104
	s_waitcnt lgkmcnt(1)
	v_add_f32_e32 v127, v124, v126
	s_waitcnt vmcnt(8)
	v_mul_f32_e64 v126, |v120|, s1
	ds_bpermute_b32 v132, v116, v123
	s_waitcnt lgkmcnt(1)
	v_add_f32_e32 v124, v125, v131
	v_exp_f32_e32 v131, v126
	s_mov_b32 s1, 0x3f2aaaab
	v_max_f32_e32 v120, v120, v120
	s_waitcnt lgkmcnt(0)
	v_add_f32_e32 v123, v123, v132
	v_add_f32_e32 v134, 1.0, v131
	v_add_f32_e32 v132, -1.0, v134
	v_sub_f32_e32 v133, v132, v134
	v_add_f32_e32 v133, 1.0, v133
	v_sub_f32_e32 v132, v131, v132
	v_add_f32_e32 v135, v132, v133
	v_frexp_mant_f32_e32 v136, v134
	v_cvt_f64_f32_e32 v[132:133], v134
	v_frexp_exp_i32_f64_e32 v132, v[132:133]
	v_cmp_gt_f32_e32 vcc, s1, v136
	s_mov_b32 s1, 0x3f317218
	v_min_f32_e32 v120, 0, v120
	v_subbrev_co_u32_e32 v140, vcc, 0, v132, vcc
	v_sub_u32_e32 v132, 0, v140
	v_ldexp_f32 v133, v134, v132
	v_add_f32_e32 v134, -1.0, v133
	v_add_f32_e32 v136, 1.0, v133
	v_ldexp_f32 v132, v135, v132
	v_add_f32_e32 v135, 1.0, v134
	v_add_f32_e32 v137, -1.0, v136
	v_sub_f32_e32 v135, v133, v135
	v_sub_f32_e32 v133, v133, v137
	v_add_f32_e32 v135, v132, v135
	v_add_f32_e32 v132, v132, v133
	v_add_f32_e32 v141, v136, v132
	v_rcp_f32_e32 v143, v141
	v_sub_f32_e32 v133, v141, v136
	v_sub_f32_e32 v142, v132, v133
	v_add_f32_e32 v133, v134, v135
	v_mul_f32_e32 v145, v133, v143
	v_sub_f32_e32 v132, v133, v134
	v_mul_f32_e32 v134, v141, v145
	v_fma_f32 v136, v145, v141, -v134
	v_fmac_f32_e32 v136, v145, v142
	v_sub_f32_e32 v144, v135, v132
	v_add_f32_e32 v132, v134, v136
	v_sub_f32_e32 v135, v133, v132
	v_pk_add_f32 v[138:139], v[132:133], v[134:135] neg_lo:[0,1] neg_hi:[0,1]
	v_mov_b32_e32 v137, v132
	v_pk_add_f32 v[132:133], v[138:139], v[136:137] neg_lo:[0,1] neg_hi:[0,1]
	v_lshl_add_u64 v[104:105], v[100:101], 0, s[78:79]
	v_add_f32_e32 v133, v144, v133
	v_add_f32_e32 v132, v132, v133
	v_add_f32_e32 v133, v135, v132
	v_mul_f32_e32 v144, v143, v133
	v_mul_f32_e32 v134, v141, v144
	v_fma_f32 v136, v144, v141, -v134
	v_fmac_f32_e32 v136, v144, v142
	v_sub_f32_e32 v135, v135, v133
	v_add_f32_e32 v141, v132, v135
	v_add_f32_e32 v132, v134, v136
	v_sub_f32_e32 v135, v133, v132
	v_pk_add_f32 v[138:139], v[132:133], v[134:135] neg_lo:[0,1] neg_hi:[0,1]
	v_mov_b32_e32 v137, v132
	v_pk_add_f32 v[132:133], v[138:139], v[136:137] neg_lo:[0,1] neg_hi:[0,1]
	v_cvt_f32_i32_e32 v134, v140
	v_add_f32_e32 v133, v141, v133
	v_add_f32_e32 v132, v132, v133
	v_add_f32_e32 v132, v135, v132
	v_add_f32_e32 v135, v145, v144
	v_sub_f32_e32 v133, v135, v145
	v_mul_f32_e32 v132, v143, v132
	v_sub_f32_e32 v133, v144, v133
	v_add_f32_e32 v132, v133, v132
	v_add_f32_e32 v136, v135, v132
	v_mul_f32_e32 v138, v136, v136
	v_mov_b32_e32 v133, 0x3ecc95a3
	v_sub_f32_e32 v135, v136, v135
	v_fmac_f32_e32 v133, 0x3e9b6dac, v138
	v_sub_f32_e32 v132, v132, v135
	v_fmaak_f32 v133, v138, v133, 0x3f2aaada
	v_ldexp_f32 v139, v132, 1
	v_mul_f32_e32 v135, v136, v138
	v_mov_b32_e32 v132, 0x3f317218
	v_pk_mul_f32 v[132:133], v[134:135], v[132:133]
	v_ldexp_f32 v137, v136, 1
	v_fma_f32 v135, v134, s1, -v132
	v_fmamk_f32 v136, v134, 0xb102e308, v135
	v_pk_add_f32 v[134:135], v[132:133], v[136:137]
	v_mov_b32_e32 v138, v132
	v_sub_f32_e32 v137, v135, v137
	v_sub_f32_e32 v137, v133, v137
	v_add_f32_e32 v139, v139, v137
	v_pk_add_f32 v[132:133], v[134:135], v[132:133] neg_lo:[0,1] neg_hi:[0,1]
	v_pk_add_f32 v[140:141], v[134:135], v[138:139]
	v_mov_b32_e32 v137, v134
	v_mov_b32_e32 v133, v141
	v_pk_add_f32 v[142:143], v[136:137], v[132:133] neg_lo:[0,1] neg_hi:[0,1]
	v_pk_add_f32 v[132:133], v[136:137], v[132:133]
	v_mov_b32_e32 v146, v135
	v_pk_add_f32 v[136:137], v[132:133], v[134:135] op_sel:[1,0] op_sel_hi:[0,1] neg_lo:[0,1] neg_hi:[0,1]
	v_pk_add_f32 v[144:145], v[140:141], v[136:137] op_sel_hi:[1,0] neg_lo:[0,1] neg_hi:[0,1]
	v_mov_b32_e32 v140, v141
	v_mov_b32_e32 v141, v133
	v_mov_b32_e32 v147, v136
	v_pk_add_f32 v[136:137], v[140:141], v[146:147] neg_lo:[0,1] neg_hi:[0,1]
	v_mov_b32_e32 v138, v139
	v_mov_b32_e32 v139, v134
	v_pk_add_f32 v[134:135], v[138:139], v[136:137] neg_lo:[0,1] neg_hi:[0,1]
	v_mov_b32_e32 v144, v142
	v_pk_add_f32 v[136:137], v[144:145], v[134:135]
	v_mov_b32_e32 v143, v133
	v_pk_add_f32 v[138:139], v[136:137], v[136:137] op_sel:[0,1] op_sel_hi:[1,0]
	s_mov_b32 s1, 0x7f800000
	v_pk_add_f32 v[132:133], v[132:133], v[138:139] op_sel:[1,0] op_sel_hi:[0,1]
	v_mov_b32_e32 v137, v132
	v_pk_add_f32 v[140:141], v[136:137], v[142:143] neg_lo:[0,1] neg_hi:[0,1]
	v_mov_b32_e32 v135, v138
	v_sub_f32_e32 v133, v136, v140
	v_pk_add_f32 v[134:135], v[134:135], v[140:141] neg_lo:[0,1] neg_hi:[0,1]
	v_sub_f32_e32 v133, v142, v133
	v_add_f32_e32 v133, v134, v133
	v_add_f32_e32 v133, v133, v135
	v_add_f32_e32 v132, v132, v133
	v_mov_b32_e32 v133, 0x7f800000
	v_cmp_neq_f32_e32 vcc, s1, v131
	s_mov_b32 s1, 0x33800000
	ds_bpermute_b32 v130, v117, v127
	v_cndmask_b32_e32 v132, v133, v132, vcc
	v_mov_b32_e32 v133, 0x7fc00000
	v_cmp_ngt_f32_e32 vcc, -1.0, v131
	ds_bpermute_b32 v125, v117, v124
	ds_bpermute_b32 v126, v117, v123
	v_cndmask_b32_e32 v132, v133, v132, vcc
	v_mov_b32_e32 v133, 0xff800000
	v_cmp_neq_f32_e32 vcc, -1.0, v131
	s_nop 1
	v_cndmask_b32_e32 v132, v133, v132, vcc
	v_cmp_lt_f32_e64 vcc, |v131|, s1
	s_nop 1
	v_cndmask_b32_e32 v131, v132, v131, vcc
	v_sub_f32_e32 v120, v120, v131
	s_waitcnt vmcnt(7)
	v_add_f32_e32 v107, v107, v120
	v_max_f32_e32 v120, v106, v106
	v_max_f32_e32 v132, v107, v120
	v_sub_f32_e32 v106, v106, v132
	v_lshl_add_u32 v120, v103, 2, 0
	v_mul_f32_e32 v106, 0x3fb8aa3b, v106
	ds_read_b32 v131, v120 offset:1024
	v_exp_f32_e32 v103, v106
	v_sub_f32_e32 v106, v107, v132
	v_mul_f32_e32 v106, 0x3fb8aa3b, v106
	v_exp_f32_e32 v106, v106
	s_waitcnt lgkmcnt(0)
	v_mul_f32_e32 v134, v103, v131
	v_pk_mul_f32 v[64:65], v[64:65], v[134:135] op_sel_hi:[1,0]
	v_pk_mul_f32 v[66:67], v[66:67], v[134:135] op_sel_hi:[1,0]
	v_pk_fma_f32 v[60:61], v[60:61], v[106:107], v[64:65] op_sel_hi:[1,0,1]
	v_pk_fma_f32 v[62:63], v[62:63], v[106:107], v[66:67] op_sel_hi:[1,0,1]
	global_store_dwordx4 v[104:105], v[60:63], off
	s_nop 1
	v_pk_mul_f32 v[60:61], v[68:69], v[134:135] op_sel_hi:[1,0]
	v_pk_mul_f32 v[62:63], v[70:71], v[134:135] op_sel_hi:[1,0]
	v_pk_fma_f32 v[56:57], v[56:57], v[106:107], v[60:61] op_sel_hi:[1,0,1]
	v_pk_fma_f32 v[58:59], v[58:59], v[106:107], v[62:63] op_sel_hi:[1,0,1]
	global_store_dwordx4 v[104:105], v[56:59], off offset:64
	s_nop 1
	v_pk_mul_f32 v[56:57], v[72:73], v[134:135] op_sel_hi:[1,0]
	v_pk_mul_f32 v[58:59], v[74:75], v[134:135] op_sel_hi:[1,0]
	v_pk_fma_f32 v[52:53], v[52:53], v[106:107], v[56:57] op_sel_hi:[1,0,1]
	v_pk_fma_f32 v[54:55], v[54:55], v[106:107], v[58:59] op_sel_hi:[1,0,1]
	global_store_dwordx4 v[104:105], v[52:55], off offset:128
	s_nop 1
	v_pk_mul_f32 v[52:53], v[76:77], v[134:135] op_sel_hi:[1,0]
	v_pk_mul_f32 v[54:55], v[78:79], v[134:135] op_sel_hi:[1,0]
	v_pk_fma_f32 v[48:49], v[48:49], v[106:107], v[52:53] op_sel_hi:[1,0,1]
	v_pk_fma_f32 v[50:51], v[50:51], v[106:107], v[54:55] op_sel_hi:[1,0,1]
	global_store_dwordx4 v[104:105], v[48:51], off offset:192
	s_nop 1
	v_pk_mul_f32 v[48:49], v[80:81], v[134:135] op_sel_hi:[1,0]
	v_pk_mul_f32 v[50:51], v[82:83], v[134:135] op_sel_hi:[1,0]
	v_pk_fma_f32 v[44:45], v[44:45], v[106:107], v[48:49] op_sel_hi:[1,0,1]
	v_pk_fma_f32 v[46:47], v[46:47], v[106:107], v[50:51] op_sel_hi:[1,0,1]
	global_store_dwordx4 v[104:105], v[44:47], off offset:256
	s_nop 1
	v_pk_mul_f32 v[44:45], v[84:85], v[134:135] op_sel_hi:[1,0]
	v_pk_mul_f32 v[46:47], v[86:87], v[134:135] op_sel_hi:[1,0]
	v_pk_fma_f32 v[40:41], v[40:41], v[106:107], v[44:45] op_sel_hi:[1,0,1]
	v_pk_fma_f32 v[42:43], v[42:43], v[106:107], v[46:47] op_sel_hi:[1,0,1]
	global_store_dwordx4 v[104:105], v[40:43], off offset:320
	s_nop 1
	v_pk_mul_f32 v[40:41], v[88:89], v[134:135] op_sel_hi:[1,0]
	v_pk_mul_f32 v[42:43], v[90:91], v[134:135] op_sel_hi:[1,0]
	v_pk_fma_f32 v[36:37], v[36:37], v[106:107], v[40:41] op_sel_hi:[1,0,1]
	v_pk_fma_f32 v[38:39], v[38:39], v[106:107], v[42:43] op_sel_hi:[1,0,1]
	global_store_dwordx4 v[104:105], v[36:39], off offset:384
	s_nop 1
	v_pk_mul_f32 v[36:37], v[92:93], v[134:135] op_sel_hi:[1,0]
	v_pk_mul_f32 v[38:39], v[94:95], v[134:135] op_sel_hi:[1,0]
	v_pk_fma_f32 v[32:33], v[32:33], v[106:107], v[36:37] op_sel_hi:[1,0,1]
	v_pk_fma_f32 v[34:35], v[34:35], v[106:107], v[38:39] op_sel_hi:[1,0,1]
	global_store_dwordx4 v[104:105], v[32:35], off offset:448
	s_and_saveexec_b64 s[4:5], s[2:3]
	s_cbranch_execz .LBB0_385
	v_lshl_add_u32 v32, v128, 2, 0
	ds_read_b32 v107, v32 offset:512
	s_add_u32 s6, s26, s76
	s_addc_u32 s7, s27, s77
	v_lshlrev_b32_e32 v32, 2, v128
	v_mov_b32_e32 v33, 0
	v_lshl_add_u64 v[32:33], s[6:7], 0, v[32:33]
	s_waitcnt lgkmcnt(0)
	v_pk_mul_f32 v[34:35], v[102:103], v[106:107]
	v_add_co_u32_e32 v32, vcc, 0x761c000, v32
	v_add_f32_e32 v34, v34, v35
	s_nop 0
	v_addc_co_u32_e32 v33, vcc, 0, v33, vcc
	global_store_dword v[32:33], v34, off offset:128

.LBB0_389:
	s_or_b64 exec, exec, s[20:21]
	ds_read_b128 v[40:43], v119 offset:2048
	ds_read_b128 v[44:47], v119 offset:2112
	s_waitcnt lgkmcnt(2)
	ds_read_b128 v[32:35], v119 offset:2560
	ds_read_b128 v[48:51], v119 offset:2176
	ds_read_b128 v[52:55], v119 offset:2240
	ds_read_b128 v[56:59], v119 offset:3584
	ds_read_b128 v[36:39], v119 offset:2624
	s_waitcnt lgkmcnt(4)
	v_mul_f32_e32 v60, v41, v33
	v_mul_f32_e32 v61, v43, v35
	v_fmac_f32_e32 v60, v40, v32
	v_fmac_f32_e32 v61, v42, v34
	s_waitcnt lgkmcnt(1)
	v_mul_f32_e32 v57, v41, v57
	v_mul_f32_e32 v41, v29, v41
	v_add_f32_e32 v60, v60, v61
	v_fmac_f32_e32 v57, v40, v56
	v_fmac_f32_e32 v41, v28, v40
	v_mul_f32_e32 v40, v31, v43
	v_add_f32_e32 v64, 0, v60
	ds_read_b128 v[60:63], v119 offset:3648
	v_mul_f32_e32 v56, v43, v59
	v_fmac_f32_e32 v40, v30, v42
	v_fmac_f32_e32 v56, v42, v58
	v_add_f32_e32 v40, v41, v40
	v_add_f32_e32 v56, v57, v56
	v_add_f32_e32 v57, 0, v40
	s_waitcnt lgkmcnt(1)
	v_mul_f32_e32 v40, v45, v37
	v_mul_f32_e32 v41, v47, v39
	v_fmac_f32_e32 v40, v44, v36
	v_fmac_f32_e32 v41, v46, v38
	v_add_f32_e32 v40, v40, v41
	v_add_f32_e32 v64, v64, v40
	s_waitcnt lgkmcnt(0)
	v_mul_f32_e32 v40, v45, v61
	v_mul_f32_e32 v41, v47, v63
	v_fmac_f32_e32 v40, v44, v60
	v_fmac_f32_e32 v41, v46, v62
	v_mul_f32_e32 v45, v25, v45
	v_add_f32_e32 v56, 0, v56
	v_add_f32_e32 v40, v40, v41
	v_fmac_f32_e32 v45, v24, v44
	v_mul_f32_e32 v44, v27, v47
	v_add_f32_e32 v65, v56, v40
	v_fmac_f32_e32 v44, v26, v46
	ds_read_b128 v[40:43], v119 offset:2688
	v_add_f32_e32 v44, v45, v44
	v_add_f32_e32 v66, v57, v44
	ds_read_b128 v[56:59], v119 offset:3712
	ds_read_b128 v[44:47], v119 offset:2752
	s_waitcnt lgkmcnt(2)
	v_mul_f32_e32 v60, v49, v41
	v_mul_f32_e32 v61, v51, v43
	v_fmac_f32_e32 v60, v48, v40
	v_fmac_f32_e32 v61, v50, v42
	s_waitcnt lgkmcnt(1)
	v_mul_f32_e32 v57, v49, v57
	v_mul_f32_e32 v49, v21, v49
	v_add_f32_e32 v60, v60, v61
	v_fmac_f32_e32 v57, v48, v56
	v_mul_f32_e32 v56, v51, v59
	v_fmac_f32_e32 v49, v20, v48
	v_mul_f32_e32 v48, v23, v51
	v_add_f32_e32 v64, v64, v60
	ds_read_b128 v[60:63], v119 offset:3776
	v_fmac_f32_e32 v56, v50, v58
	v_fmac_f32_e32 v48, v22, v50
	v_add_f32_e32 v56, v57, v56
	v_add_f32_e32 v48, v49, v48
	v_add_f32_e32 v56, v65, v56
	v_add_f32_e32 v65, v66, v48
	s_waitcnt lgkmcnt(1)
	v_mul_f32_e32 v48, v53, v45
	v_mul_f32_e32 v49, v55, v47
	v_fmac_f32_e32 v48, v52, v44
	v_fmac_f32_e32 v49, v54, v46
	v_add_f32_e32 v48, v48, v49
	v_add_f32_e32 v73, v64, v48
	s_waitcnt lgkmcnt(0)
	v_mul_f32_e32 v48, v53, v61
	v_mul_f32_e32 v49, v55, v63
	v_fmac_f32_e32 v48, v52, v60
	v_fmac_f32_e32 v49, v54, v62
	v_add_f32_e32 v48, v48, v49
	v_add_f32_e32 v78, v56, v48
	v_mul_f32_e32 v48, v17, v53
	v_mul_f32_e32 v49, v19, v55
	v_fmac_f32_e32 v48, v16, v52
	v_fmac_f32_e32 v49, v18, v54
	v_add_f32_e32 v52, v48, v49
	ds_read_b128 v[56:59], v119 offset:2304
	ds_read_b128 v[48:51], v119 offset:2816
	v_add_f32_e32 v79, v65, v52
	ds_read_b128 v[60:63], v119 offset:3840
	ds_read_b128 v[64:67], v119 offset:2368
	ds_read_b128 v[52:55], v119 offset:2880
	s_waitcnt lgkmcnt(3)
	v_mul_f32_e32 v74, v57, v49
	v_mul_f32_e32 v75, v59, v51
	v_fmac_f32_e32 v74, v56, v48
	v_fmac_f32_e32 v75, v58, v50
	s_waitcnt lgkmcnt(2)
	v_mul_f32_e32 v61, v57, v61
	v_mul_f32_e32 v57, v13, v57
	v_add_f32_e32 v74, v74, v75
	v_fmac_f32_e32 v61, v56, v60
	v_fmac_f32_e32 v57, v12, v56
	v_mul_f32_e32 v56, v15, v59
	v_add_f32_e32 v73, v73, v74
	ds_read_b128 v[74:77], v119 offset:3904
	v_mul_f32_e32 v60, v59, v63
	v_fmac_f32_e32 v56, v14, v58
	v_fmac_f32_e32 v60, v58, v62
	v_add_f32_e32 v56, v57, v56
	v_add_f32_e32 v60, v61, v60
	v_add_f32_e32 v61, v79, v56
	s_waitcnt lgkmcnt(1)
	v_mul_f32_e32 v56, v65, v53
	v_mul_f32_e32 v57, v67, v55
	v_fmac_f32_e32 v56, v64, v52
	v_fmac_f32_e32 v57, v66, v54
	v_add_f32_e32 v56, v56, v57
	v_add_f32_e32 v73, v73, v56
	s_waitcnt lgkmcnt(0)
	v_mul_f32_e32 v56, v65, v75
	v_mul_f32_e32 v57, v67, v77
	v_fmac_f32_e32 v56, v64, v74
	v_fmac_f32_e32 v57, v66, v76
	v_add_f32_e32 v60, v78, v60
	v_add_f32_e32 v56, v56, v57
	v_add_f32_e32 v86, v60, v56
	v_mul_f32_e32 v56, v9, v65
	v_mul_f32_e32 v57, v11, v67
	v_fmac_f32_e32 v56, v8, v64
	v_fmac_f32_e32 v57, v10, v66
	v_add_f32_e32 v60, v56, v57
	ds_read_b128 v[64:67], v119 offset:2432
	ds_read_b128 v[56:59], v119 offset:2944
	v_add_f32_e32 v87, v61, v60
	ds_read_b128 v[74:77], v119 offset:3968
	ds_read_b128 v[78:81], v119 offset:2496
	ds_read_b128 v[60:63], v119 offset:3008
	s_waitcnt lgkmcnt(3)
	v_mul_f32_e32 v82, v65, v57
	v_mul_f32_e32 v83, v67, v59
	v_fmac_f32_e32 v82, v64, v56
	v_fmac_f32_e32 v83, v66, v58
	v_add_f32_e32 v82, v82, v83
	s_waitcnt lgkmcnt(2)
	v_mul_f32_e32 v75, v65, v75
	v_mul_f32_e32 v65, v5, v65
	v_add_f32_e32 v73, v73, v82
	ds_read_b128 v[82:85], v119 offset:4032
	v_fmac_f32_e32 v75, v64, v74
	v_fmac_f32_e32 v65, v4, v64
	v_mul_f32_e32 v64, v7, v67
	v_mul_f32_e32 v74, v67, v77
	v_fmac_f32_e32 v64, v6, v66
	v_fmac_f32_e32 v74, v66, v76
	v_add_f32_e32 v64, v65, v64
	s_waitcnt lgkmcnt(1)
	v_mul_f32_e32 v65, v79, v61
	v_mul_f32_e32 v66, v81, v63
	v_fmac_f32_e32 v65, v78, v60
	v_fmac_f32_e32 v66, v80, v62
	v_add_f32_e32 v65, v65, v66
	v_add_f32_e32 v66, v73, v65
	s_waitcnt lgkmcnt(0)
	v_mul_f32_e32 v65, v79, v83
	v_mul_f32_e32 v67, v81, v85
	v_add_f32_e32 v74, v75, v74
	v_fmac_f32_e32 v65, v78, v82
	v_fmac_f32_e32 v67, v80, v84
	v_add_f32_e32 v74, v86, v74
	v_add_f32_e32 v65, v65, v67
	v_add_f32_e32 v67, v74, v65
	v_mul_f32_e32 v65, v1, v79
	v_mul_f32_e32 v73, v3, v81
	v_fmac_f32_e32 v65, v0, v78
	v_fmac_f32_e32 v73, v2, v80
	v_add_f32_e32 v64, v87, v64
	v_add_f32_e32 v65, v65, v73
	ds_bpermute_b32 v73, v116, v66
	v_add_f32_e32 v76, v64, v65
	ds_bpermute_b32 v79, v116, v76
	ds_bpermute_b32 v74, v116, v67
	v_lshl_add_u64 v[64:65], v[100:101], 0, s[70:71]
	s_waitcnt lgkmcnt(2)
	v_add_f32_e32 v77, v66, v73
	s_waitcnt vmcnt(13)
	v_mul_f32_e64 v66, |v118|, s1
	s_waitcnt lgkmcnt(1)
	v_add_f32_e32 v73, v76, v79
	v_exp_f32_e32 v79, v66
	v_max_f32_e32 v66, v118, v118
	v_min_f32_e32 v94, 0, v66
	s_waitcnt lgkmcnt(0)
	v_add_f32_e32 v74, v67, v74
	v_add_f32_e32 v80, 1.0, v79
	v_add_f32_e32 v66, -1.0, v80
	v_sub_f32_e32 v67, v66, v80
	v_add_f32_e32 v67, 1.0, v67
	v_sub_f32_e32 v66, v79, v66
	v_add_f32_e32 v81, v66, v67
	v_frexp_mant_f32_e32 v82, v80
	s_mov_b32 s1, 0x3f2aaaab
	v_cvt_f64_f32_e32 v[66:67], v80
	v_frexp_exp_i32_f64_e32 v66, v[66:67]
	v_cmp_gt_f32_e32 vcc, s1, v82
	s_mov_b32 s1, 0x3f317218
	ds_bpermute_b32 v78, v117, v77
	v_subbrev_co_u32_e32 v86, vcc, 0, v66, vcc
	v_sub_u32_e32 v66, 0, v86
	v_ldexp_f32 v67, v80, v66
	v_add_f32_e32 v80, -1.0, v67
	v_add_f32_e32 v82, 1.0, v67
	v_ldexp_f32 v66, v81, v66
	v_add_f32_e32 v81, 1.0, v80
	v_add_f32_e32 v83, -1.0, v82
	v_sub_f32_e32 v81, v67, v81
	v_sub_f32_e32 v67, v67, v83
	v_add_f32_e32 v81, v66, v81
	v_add_f32_e32 v66, v66, v67
	v_add_f32_e32 v87, v82, v66
	v_rcp_f32_e32 v89, v87
	v_sub_f32_e32 v67, v87, v82
	v_sub_f32_e32 v88, v66, v67
	v_add_f32_e32 v67, v80, v81
	v_mul_f32_e32 v91, v67, v89
	v_sub_f32_e32 v66, v67, v80
	v_mul_f32_e32 v80, v87, v91
	v_fma_f32 v82, v91, v87, -v80
	v_fmac_f32_e32 v82, v91, v88
	v_sub_f32_e32 v90, v81, v66
	v_add_f32_e32 v66, v80, v82
	v_sub_f32_e32 v81, v67, v66
	v_pk_add_f32 v[84:85], v[66:67], v[80:81] neg_lo:[0,1] neg_hi:[0,1]
	v_mov_b32_e32 v83, v66
	v_pk_add_f32 v[66:67], v[84:85], v[82:83] neg_lo:[0,1] neg_hi:[0,1]
	ds_bpermute_b32 v75, v117, v74
	v_add_f32_e32 v67, v90, v67
	v_add_f32_e32 v66, v66, v67
	v_add_f32_e32 v67, v81, v66
	v_mul_f32_e32 v90, v89, v67
	v_mul_f32_e32 v80, v87, v90
	v_fma_f32 v82, v90, v87, -v80
	v_fmac_f32_e32 v82, v90, v88
	v_sub_f32_e32 v81, v81, v67
	v_add_f32_e32 v87, v66, v81
	v_add_f32_e32 v66, v80, v82
	v_sub_f32_e32 v81, v67, v66
	v_pk_add_f32 v[84:85], v[66:67], v[80:81] neg_lo:[0,1] neg_hi:[0,1]
	v_mov_b32_e32 v83, v66
	v_pk_add_f32 v[66:67], v[84:85], v[82:83] neg_lo:[0,1] neg_hi:[0,1]
	v_cvt_f32_i32_e32 v80, v86
	v_add_f32_e32 v67, v87, v67
	v_add_f32_e32 v66, v66, v67
	v_add_f32_e32 v66, v81, v66
	v_add_f32_e32 v81, v91, v90
	v_sub_f32_e32 v67, v81, v91
	v_mul_f32_e32 v66, v89, v66
	v_sub_f32_e32 v67, v90, v67
	v_add_f32_e32 v66, v67, v66
	v_add_f32_e32 v82, v81, v66
	v_mul_f32_e32 v84, v82, v82
	v_mov_b32_e32 v67, 0x3ecc95a3
	v_sub_f32_e32 v81, v82, v81
	v_fmac_f32_e32 v67, 0x3e9b6dac, v84
	v_sub_f32_e32 v66, v66, v81
	v_fmaak_f32 v67, v84, v67, 0x3f2aaada
	v_ldexp_f32 v85, v66, 1
	v_mul_f32_e32 v81, v82, v84
	v_mov_b32_e32 v66, 0x3f317218
	v_pk_mul_f32 v[66:67], v[80:81], v[66:67]
	v_ldexp_f32 v83, v82, 1
	v_fma_f32 v81, v80, s1, -v66
	v_fmamk_f32 v82, v80, 0xb102e308, v81
	v_pk_add_f32 v[80:81], v[66:67], v[82:83]
	v_mov_b32_e32 v84, v66
	v_sub_f32_e32 v83, v81, v83
	v_sub_f32_e32 v83, v67, v83
	v_add_f32_e32 v85, v85, v83
	v_pk_add_f32 v[66:67], v[80:81], v[66:67] neg_lo:[0,1] neg_hi:[0,1]
	v_pk_add_f32 v[86:87], v[80:81], v[84:85]
	v_mov_b32_e32 v83, v80
	v_mov_b32_e32 v67, v87
	v_pk_add_f32 v[88:89], v[82:83], v[66:67] neg_lo:[0,1] neg_hi:[0,1]
	v_pk_add_f32 v[66:67], v[82:83], v[66:67]
	v_mov_b32_e32 v92, v81
	v_pk_add_f32 v[82:83], v[66:67], v[80:81] op_sel:[1,0] op_sel_hi:[0,1] neg_lo:[0,1] neg_hi:[0,1]
	v_pk_add_f32 v[90:91], v[86:87], v[82:83] op_sel_hi:[1,0] neg_lo:[0,1] neg_hi:[0,1]
	v_mov_b32_e32 v86, v87
	v_mov_b32_e32 v87, v67
	v_mov_b32_e32 v93, v82
	v_pk_add_f32 v[82:83], v[86:87], v[92:93] neg_lo:[0,1] neg_hi:[0,1]
	v_mov_b32_e32 v84, v85
	v_mov_b32_e32 v85, v80
	v_pk_add_f32 v[80:81], v[84:85], v[82:83] neg_lo:[0,1] neg_hi:[0,1]
	v_mov_b32_e32 v90, v88
	v_pk_add_f32 v[82:83], v[90:91], v[80:81]
	v_mov_b32_e32 v89, v67
	v_pk_add_f32 v[84:85], v[82:83], v[82:83] op_sel:[0,1] op_sel_hi:[1,0]
	s_mov_b32 s1, 0x7f800000
	v_pk_add_f32 v[66:67], v[66:67], v[84:85] op_sel:[1,0] op_sel_hi:[0,1]
	v_mov_b32_e32 v83, v66
	v_pk_add_f32 v[86:87], v[82:83], v[88:89] neg_lo:[0,1] neg_hi:[0,1]
	v_mov_b32_e32 v81, v84
	v_sub_f32_e32 v67, v82, v86
	v_pk_add_f32 v[80:81], v[80:81], v[86:87] neg_lo:[0,1] neg_hi:[0,1]
	v_sub_f32_e32 v67, v88, v67
	v_add_f32_e32 v67, v80, v67
	v_add_f32_e32 v67, v67, v81
	v_add_f32_e32 v66, v66, v67
	v_mov_b32_e32 v67, 0x7f800000
	v_cmp_neq_f32_e32 vcc, s1, v79
	s_mov_b32 s1, 0x33800000
	ds_bpermute_b32 v76, v117, v73
	v_cndmask_b32_e32 v66, v67, v66, vcc
	v_mov_b32_e32 v67, 0x7fc00000
	v_cmp_ngt_f32_e32 vcc, -1.0, v79
	s_nop 1
	v_cndmask_b32_e32 v66, v67, v66, vcc
	v_mov_b32_e32 v67, 0xff800000
	v_cmp_neq_f32_e32 vcc, -1.0, v79
	s_nop 1
	v_cndmask_b32_e32 v66, v67, v66, vcc
	v_cmp_lt_f32_e64 vcc, |v79|, s1
	v_max_f32_e32 v67, v99, v99
	s_nop 0
	v_cndmask_b32_e32 v66, v66, v79, vcc
	v_sub_f32_e32 v66, v94, v66
	s_waitcnt vmcnt(12)
	v_add_f32_e32 v66, v115, v66
	v_max_f32_e32 v80, v66, v67
	v_sub_f32_e32 v67, v99, v80
	v_mul_f32_e32 v67, 0x3fb8aa3b, v67
	ds_read_b32 v79, v120 offset:3072
	v_exp_f32_e32 v99, v67
	v_sub_f32_e32 v66, v66, v80
	v_mul_f32_e32 v66, 0x3fb8aa3b, v66
	v_exp_f32_e32 v66, v66
	s_waitcnt lgkmcnt(0)
	v_mul_f32_e32 v82, v99, v79
	v_pk_mul_f32 v[32:33], v[32:33], v[82:83] op_sel_hi:[1,0]
	v_pk_mul_f32 v[34:35], v[34:35], v[82:83] op_sel_hi:[1,0]
	v_pk_fma_f32 v[28:29], v[28:29], v[66:67], v[32:33] op_sel_hi:[1,0,1]
	v_pk_fma_f32 v[30:31], v[30:31], v[66:67], v[34:35] op_sel_hi:[1,0,1]
	global_store_dwordx4 v[64:65], v[28:31], off
	s_nop 1
	v_pk_mul_f32 v[28:29], v[36:37], v[82:83] op_sel_hi:[1,0]
	v_pk_mul_f32 v[30:31], v[38:39], v[82:83] op_sel_hi:[1,0]
	v_pk_fma_f32 v[24:25], v[24:25], v[66:67], v[28:29] op_sel_hi:[1,0,1]
	v_pk_fma_f32 v[26:27], v[26:27], v[66:67], v[30:31] op_sel_hi:[1,0,1]
	global_store_dwordx4 v[64:65], v[24:27], off offset:64
	s_nop 1
	v_pk_mul_f32 v[24:25], v[40:41], v[82:83] op_sel_hi:[1,0]
	v_pk_mul_f32 v[26:27], v[42:43], v[82:83] op_sel_hi:[1,0]
	v_pk_fma_f32 v[20:21], v[20:21], v[66:67], v[24:25] op_sel_hi:[1,0,1]
	v_pk_fma_f32 v[22:23], v[22:23], v[66:67], v[26:27] op_sel_hi:[1,0,1]
	global_store_dwordx4 v[64:65], v[20:23], off offset:128
	s_nop 1
	v_pk_mul_f32 v[20:21], v[44:45], v[82:83] op_sel_hi:[1,0]
	v_pk_mul_f32 v[22:23], v[46:47], v[82:83] op_sel_hi:[1,0]
	v_pk_fma_f32 v[16:17], v[16:17], v[66:67], v[20:21] op_sel_hi:[1,0,1]
	v_pk_fma_f32 v[18:19], v[18:19], v[66:67], v[22:23] op_sel_hi:[1,0,1]
	global_store_dwordx4 v[64:65], v[16:19], off offset:192
	s_nop 1
	v_pk_mul_f32 v[16:17], v[48:49], v[82:83] op_sel_hi:[1,0]
	v_pk_mul_f32 v[18:19], v[50:51], v[82:83] op_sel_hi:[1,0]
	v_pk_fma_f32 v[12:13], v[12:13], v[66:67], v[16:17] op_sel_hi:[1,0,1]
	v_pk_fma_f32 v[14:15], v[14:15], v[66:67], v[18:19] op_sel_hi:[1,0,1]
	global_store_dwordx4 v[64:65], v[12:15], off offset:256
	s_nop 1
	v_pk_mul_f32 v[12:13], v[52:53], v[82:83] op_sel_hi:[1,0]
	v_pk_mul_f32 v[14:15], v[54:55], v[82:83] op_sel_hi:[1,0]
	v_pk_fma_f32 v[8:9], v[8:9], v[66:67], v[12:13] op_sel_hi:[1,0,1]
	v_pk_fma_f32 v[10:11], v[10:11], v[66:67], v[14:15] op_sel_hi:[1,0,1]
	global_store_dwordx4 v[64:65], v[8:11], off offset:320
	s_nop 1
	v_pk_mul_f32 v[8:9], v[56:57], v[82:83] op_sel_hi:[1,0]
	v_pk_mul_f32 v[10:11], v[58:59], v[82:83] op_sel_hi:[1,0]
	v_pk_fma_f32 v[4:5], v[4:5], v[66:67], v[8:9] op_sel_hi:[1,0,1]
	v_pk_fma_f32 v[6:7], v[6:7], v[66:67], v[10:11] op_sel_hi:[1,0,1]
	global_store_dwordx4 v[64:65], v[4:7], off offset:384
	s_nop 1
	v_pk_mul_f32 v[4:5], v[60:61], v[82:83] op_sel_hi:[1,0]
	v_pk_mul_f32 v[6:7], v[62:63], v[82:83] op_sel_hi:[1,0]
	v_pk_fma_f32 v[0:1], v[0:1], v[66:67], v[4:5] op_sel_hi:[1,0,1]
	v_pk_fma_f32 v[2:3], v[2:3], v[66:67], v[6:7] op_sel_hi:[1,0,1]
	global_store_dwordx4 v[64:65], v[0:3], off offset:448
	s_and_saveexec_b64 s[20:21], s[2:3]
	s_cbranch_execz .LBB0_391
	v_lshl_add_u32 v0, v128, 2, 0
	ds_read_b32 v67, v0 offset:2560
	s_add_u32 s2, s26, s58
	s_addc_u32 s3, s27, s59
	v_lshlrev_b32_e32 v0, 2, v128
	v_mov_b32_e32 v1, 0
	v_lshl_add_u64 v[0:1], s[2:3], 0, v[0:1]
	s_waitcnt vmcnt(19) lgkmcnt(0)
	v_pk_mul_f32 v[2:3], v[98:99], v[66:67]
	v_add_co_u32_e32 v0, vcc, 0x761c000, v0
	v_add_f32_e32 v2, v2, v3
	s_nop 0
	v_addc_co_u32_e32 v1, vcc, 0, v1, vcc
	global_store_dword v[0:1], v2, off offset:128

.LBB0_414:
	s_and_b64 vcc, exec, s[0:1]
	s_cbranch_vccz .LBB0_432
	s_lshl_b32 s80, s69, 2
	s_add_u32 s0, s28, s80
	s_addc_u32 s1, s29, 0
	s_add_u32 s23, s0, 0x2fc3000
	s_addc_u32 s33, s1, 0
	s_lshl_b32 s72, s58, 2
	s_or_b32 s0, s72, s69
	s_ashr_i32 s1, s0, 31
	s_ashr_i32 s59, s58, 31
	s_lshl_b64 s[76:77], s[0:1], 16
	s_lshl_b64 s[2:3], s[58:59], 5
	v_readlane_b32 s36, v255, 1
	s_add_u32 s2, s23, s2
	v_readlane_b32 s50, v255, 15
	s_addc_u32 s3, s33, s3
	s_lshl_b64 s[12:13], s[0:1], 2
	v_lshrrev_b32_e32 v101, 2, v128
	v_readlane_b32 s51, v255, 16
	s_add_u32 s12, s50, s12
	v_mov_b32_e32 v65, 0
	v_lshlrev_b32_e32 v64, 9, v101
	v_readlane_b32 s46, v255, 11
	v_readlane_b32 s47, v255, 12
	s_addc_u32 s13, s51, s13
	s_lshl_b64 s[74:75], s[0:1], 9
	s_lshl_b32 s0, s70, 2
	s_waitcnt lgkmcnt(0)
	v_and_b32_e32 v2, 0x7f, v128
	v_lshl_add_u64 v[0:1], s[46:47], 0, v[64:65]
	v_mov_b32_e32 v97, v65
	s_or_b32 s20, s0, s69
	v_readlane_b32 s48, v255, 13
	v_readlane_b32 s49, v255, 14
	v_lshl_add_u64 v[0:1], v[0:1], 0, v[96:97]
	v_lshlrev_b32_e32 v64, 2, v2
	s_ashr_i32 s21, s20, 31
	s_ashr_i32 s71, s70, 31
	v_lshl_add_u64 v[66:67], s[48:49], 0, v[64:65]
	v_lshl_add_u64 v[2:3], v[0:1], 0, s[76:77]
	s_lshl_b64 s[64:65], s[20:21], 16
	s_lshl_b64 s[78:79], s[70:71], 5
	global_load_dwordx4 v[48:51], v[2:3], off offset:192
	global_load_dwordx4 v[52:55], v[2:3], off offset:128
	global_load_dwordx4 v[56:59], v[2:3], off offset:64
	global_load_dwordx4 v[60:63], v[2:3], off
	global_load_dwordx4 v[32:35], v[2:3], off offset:448
	global_load_dwordx4 v[36:39], v[2:3], off offset:384
	global_load_dwordx4 v[40:43], v[2:3], off offset:320
	global_load_dwordx4 v[44:47], v[2:3], off offset:256
	v_lshl_add_u64 v[2:3], v[66:67], 0, s[74:75]
	v_lshl_add_u64 v[12:13], v[0:1], 0, s[64:65]
	s_add_u32 s78, s23, s78
	global_load_dword v100, v[2:3], off
	global_load_dwordx4 v[16:19], v[12:13], off offset:192
	global_load_dwordx4 v[20:23], v[12:13], off offset:128
	global_load_dwordx4 v[24:27], v[12:13], off offset:64
	global_load_dwordx4 v[28:31], v[12:13], off
	s_nop 0
	global_load_dwordx4 v[0:3], v[12:13], off offset:448
	global_load_dwordx4 v[4:7], v[12:13], off offset:384
	global_load_dwordx4 v[8:11], v[12:13], off offset:320
	s_nop 0
	global_load_dwordx4 v[12:15], v[12:13], off offset:256
	s_addc_u32 s79, s33, s79
	s_lshl_b64 s[82:83], s[20:21], 2
	s_add_u32 s82, s50, s82
	s_addc_u32 s83, s51, s83
	global_load_dword v104, v65, s[2:3]
	global_load_dword v118, v65, s[2:3] offset:16
	global_load_dword v105, v65, s[12:13]
	global_load_dword v97, v65, s[78:79]
	global_load_dword v116, v65, s[78:79] offset:16
	global_load_dword v114, v65, s[82:83]
	s_lshl_b64 s[12:13], s[20:21], 9
	v_add_u32_e32 v64, s68, v101
	v_lshl_add_u64 v[66:67], v[66:67], 0, s[12:13]
	v_lshlrev_b32_e32 v106, 1, v64
	global_load_dword v96, v[66:67], off
	global_load_ushort v113, v106, s[4:5] offset:3072
	global_load_ushort v112, v106, s[6:7] offset:3072
	v_lshlrev_b32_e32 v64, 2, v64
	global_load_dword v107, v64, s[66:67]
	s_movk_i32 s1, 0x80
	v_lshlrev_b32_e32 v66, 7, v101
	v_cmp_gt_u32_e64 s[2:3], s1, v128
	v_readlane_b32 s37, v255, 2
	v_readlane_b32 s38, v255, 3
	v_readlane_b32 s39, v255, 4
	v_readlane_b32 s40, v255, 5
	v_readlane_b32 s41, v255, 6
	v_readlane_b32 s42, v255, 7
	v_readlane_b32 s43, v255, 8
	v_readlane_b32 s44, v255, 9
	v_readlane_b32 s45, v255, 10
	s_and_saveexec_b64 s[78:79], s[2:3]
	s_cbranch_execz .LBB0_417
	v_or_b32_e32 v67, s68, v128
	v_lshlrev_b32_e32 v64, 2, v67
	v_lshl_add_u64 v[68:69], s[60:61], 0, v[64:65]
	v_readlane_b32 s36, v255, 1
	v_add_co_u32_e32 v70, vcc, 0x3000, v68
	s_mul_i32 s20, s70, 0x3000
	v_readlane_b32 s44, v255, 9
	v_addc_co_u32_e32 v71, vcc, 0, v69, vcc
	s_mul_hi_i32 s21, s70, 0x3000
	v_readlane_b32 s45, v255, 10
	s_add_u32 s20, s44, s20
	v_add_co_u32_e32 v72, vcc, 0x2000, v68
	s_addc_u32 s21, s45, s21
	s_mul_hi_i32 s33, s58, 0x3000
	s_mulk_i32 s58, 0x3000
	v_addc_co_u32_e32 v73, vcc, 0, v69, vcc
	s_add_u32 s58, s44, s58
	v_add_co_u32_e32 v68, vcc, 0x1000, v68
	s_addc_u32 s59, s45, s33
	s_movk_i32 s1, 0x2000
	v_addc_co_u32_e32 v69, vcc, 0, v69, vcc
	v_lshl_add_u64 v[74:75], s[58:59], 0, v[64:65]
	v_add_co_u32_e32 v76, vcc, s1, v74
	s_movk_i32 s23, 0x1000
	s_nop 0
	v_addc_co_u32_e32 v77, vcc, 0, v75, vcc
	v_add_co_u32_e32 v74, vcc, s23, v74
	v_lshlrev_b32_e32 v67, 1, v67
	s_nop 0
	v_addc_co_u32_e32 v75, vcc, 0, v75, vcc
	global_load_dword v78, v64, s[62:63] offset:2048
	global_load_dword v79, v64, s[60:61] offset:2048
	global_load_dword v80, v64, s[62:63]
	global_load_dword v81, v64, s[58:59] offset:2048
	global_load_dword v82, v64, s[58:59]
	global_load_dword v83, v64, s[20:21]
	global_load_dword v84, v64, s[60:61]
	global_load_ushort v85, v67, s[6:7] offset:2048
	global_load_ushort v86, v67, s[4:5] offset:1024
	global_load_ushort v87, v67, s[4:5]
	global_load_dword v88, v[76:77], off offset:2048
	global_load_dword v89, v[74:75], off offset:2048
	s_nop 0
	global_load_dword v74, v[74:75], off
	s_nop 0
	global_load_dword v75, v[76:77], off
	s_nop 0
	global_load_dword v76, v[68:69], off
	global_load_dword v77, v[68:69], off offset:2048
	global_load_dword v90, v[72:73], off
	s_nop 0
	global_load_dword v72, v[72:73], off offset:2048
	s_nop 0
	global_load_dword v73, v[70:71], off
	global_load_dword v91, v[70:71], off offset:2048
	global_load_ushort v92, v67, s[6:7] offset:1024
	global_load_ushort v93, v67, s[6:7]
	s_nop 0
	global_load_ushort v67, v67, s[4:5] offset:2048
	v_lshl_add_u64 v[68:69], s[20:21], 0, v[64:65]
	v_add_co_u32_e32 v70, vcc, s1, v68
	v_readlane_b32 s37, v255, 2
	s_nop 0
	v_addc_co_u32_e32 v71, vcc, 0, v69, vcc
	v_add_co_u32_e32 v68, vcc, s23, v68
	v_readlane_b32 s38, v255, 3
	s_nop 0
	v_addc_co_u32_e32 v69, vcc, 0, v69, vcc
	global_load_dword v94, v[68:69], off
	global_load_dword v95, v[70:71], off
	s_nop 0
	global_load_dword v64, v64, s[20:21] offset:2048
	s_nop 0
	global_load_dword v68, v[68:69], off offset:2048
	s_nop 0
	global_load_dword v69, v[70:71], off offset:2048
	v_lshl_add_u32 v70, v128, 2, 0
	v_readlane_b32 s39, v255, 4
	v_readlane_b32 s40, v255, 5
	v_readlane_b32 s41, v255, 6
	v_readlane_b32 s42, v255, 7
	v_readlane_b32 s43, v255, 8
	v_readlane_b32 s46, v255, 11
	v_readlane_b32 s47, v255, 12
	v_readlane_b32 s48, v255, 13
	v_readlane_b32 s49, v255, 14
	v_readlane_b32 s50, v255, 15
	v_readlane_b32 s51, v255, 16
	s_waitcnt vmcnt(20)
	v_lshlrev_b32_e32 v71, 16, v85
	s_waitcnt vmcnt(19)
	v_lshlrev_b32_e32 v85, 16, v86
	s_waitcnt vmcnt(18)
	v_lshlrev_b32_e32 v86, 16, v87
	v_fma_f32 v81, v79, v81, v78
	s_waitcnt vmcnt(12)
	v_fmac_f32_e32 v81, v77, v89
	s_waitcnt vmcnt(10)
	v_fmac_f32_e32 v81, v72, v88
	v_fma_f32 v82, v84, v82, v80
	v_fmac_f32_e32 v82, v76, v74
	v_fmac_f32_e32 v82, v90, v75
	s_waitcnt vmcnt(8)
	v_fmac_f32_e32 v81, v91, v85
	v_fmac_f32_e32 v80, v84, v83
	v_fmac_f32_e32 v82, v73, v86
	v_mul_f32_e32 v75, 0xbfb8aa3b, v81
	s_waitcnt vmcnt(7)
	v_lshlrev_b32_e32 v85, 16, v92
	v_mul_f32_e32 v74, 0xbfb8aa3b, v82
	s_waitcnt vmcnt(4)
	v_fmac_f32_e32 v80, v76, v94
	v_exp_f32_e32 v75, v75
	s_waitcnt vmcnt(2)
	v_fmac_f32_e32 v78, v79, v64
	s_waitcnt vmcnt(1)
	v_fmac_f32_e32 v78, v77, v68
	s_waitcnt vmcnt(0)
	v_fmac_f32_e32 v78, v72, v69
	v_lshlrev_b32_e32 v86, 16, v93
	v_fmac_f32_e32 v80, v90, v95
	v_fmac_f32_e32 v78, v91, v85
	v_exp_f32_e32 v74, v74
	v_fmac_f32_e32 v80, v73, v86
	v_mul_f32_e32 v68, 0xbfb8aa3b, v78
	v_mul_f32_e32 v64, 0xbfb8aa3b, v80
	v_exp_f32_e32 v68, v68
	v_exp_f32_e32 v64, v64
	v_add_f32_e32 v75, 1.0, v75
	v_add_f32_e32 v74, 1.0, v74
	v_rcp_f32_e32 v75, v75
	v_rcp_f32_e32 v74, v74
	v_add_f32_e32 v68, 1.0, v68
	v_add_f32_e32 v64, 1.0, v64
	v_rcp_f32_e32 v68, v68
	v_rcp_f32_e32 v64, v64
	v_mul_f32_e32 v75, v81, v75
	v_lshlrev_b32_e32 v67, 16, v67
	v_mul_f32_e32 v74, v82, v74
	v_mul_f32_e32 v69, 0x3db504f3, v75
	ds_write2st64_b32 v70, v74, v69 offset1:2
	ds_write2st64_b32 v70, v67, v100 offset0:4 offset1:6
	v_mul_f32_e32 v67, v78, v68
	v_mul_f32_e32 v64, v80, v64
	v_mul_f32_e32 v67, 0x3db504f3, v67
	ds_write2st64_b32 v70, v64, v67 offset0:8 offset1:10
	ds_write2st64_b32 v70, v71, v96 offset0:12 offset1:14
.LBB0_417:
	s_or_b64 exec, exec, s[78:79]
	v_lshlrev_b32_e32 v64, 2, v66
	v_lshl_add_u64 v[66:67], s[26:27], 0, v[64:65]
	v_lshlrev_b32_e32 v64, 2, v111
	v_lshl_add_u64 v[66:67], v[66:67], 0, v[64:65]
	v_mbcnt_lo_u32_b32 v65, -1, 0
	s_mov_b64 s[4:5], 0x561c080
	v_mbcnt_hi_u32_b32 v119, -1, v65
	s_waitcnt vmcnt(46)
	v_lshl_add_u64 v[98:99], v[66:67], 0, s[4:5]
	v_and_b32_e32 v66, 64, v119
	v_xor_b32_e32 v65, 1, v119
	v_add_u32_e32 v120, 64, v66
	v_cmp_lt_i32_e32 vcc, v65, v120
	s_waitcnt lgkmcnt(0)
	s_barrier
	v_add_u32_e32 v117, 0, v64
	v_cndmask_b32_e32 v65, v119, v65, vcc
	v_lshlrev_b32_e32 v111, 2, v65
	v_xor_b32_e32 v65, 2, v119
	v_cmp_lt_i32_e32 vcc, v65, v120
	s_mov_b32 s1, 0xbfb8aa3b
	s_nop 0
	v_cndmask_b32_e32 v65, v119, v65, vcc
	v_lshlrev_b32_e32 v115, 2, v65
	ds_read_b128 v[72:75], v117
	ds_read_b128 v[76:79], v117 offset:64
	ds_read_b128 v[64:67], v117 offset:512
	s_waitcnt vmcnt(34)
	ds_read_b128 v[80:83], v117 offset:128
	s_waitcnt vmcnt(33)
	ds_read_b128 v[84:87], v117 offset:192
	ds_read_b128 v[88:91], v117 offset:1536
	ds_read_b128 v[68:71], v117 offset:576
	s_waitcnt lgkmcnt(4)
	v_mul_f32_e32 v92, v73, v65
	v_mul_f32_e32 v93, v75, v67
	v_fmac_f32_e32 v92, v72, v64
	v_fmac_f32_e32 v93, v74, v66
	s_waitcnt lgkmcnt(1)
	v_mul_f32_e32 v89, v73, v89
	s_waitcnt vmcnt(23)
	v_mul_f32_e32 v73, v61, v73
	v_add_f32_e32 v92, v92, v93
	v_fmac_f32_e32 v89, v72, v88
	v_fmac_f32_e32 v73, v60, v72
	v_mul_f32_e32 v72, v63, v75
	v_add_f32_e32 v102, 0, v92
	ds_read_b128 v[92:95], v117 offset:1600
	v_mul_f32_e32 v88, v75, v91
	v_fmac_f32_e32 v72, v62, v74
	v_fmac_f32_e32 v88, v74, v90
	v_add_f32_e32 v72, v73, v72
	v_add_f32_e32 v88, v89, v88
	v_add_f32_e32 v89, 0, v72
	s_waitcnt lgkmcnt(1)
	v_mul_f32_e32 v72, v77, v69
	v_mul_f32_e32 v73, v79, v71
	v_fmac_f32_e32 v72, v76, v68
	v_fmac_f32_e32 v73, v78, v70
	v_add_f32_e32 v72, v72, v73
	v_add_f32_e32 v102, v102, v72
	s_waitcnt lgkmcnt(0)
	v_mul_f32_e32 v72, v77, v93
	v_mul_f32_e32 v73, v79, v95
	v_fmac_f32_e32 v72, v76, v92
	v_fmac_f32_e32 v73, v78, v94
	v_mul_f32_e32 v77, v57, v77
	v_add_f32_e32 v88, 0, v88
	v_add_f32_e32 v72, v72, v73
	v_fmac_f32_e32 v77, v56, v76
	v_mul_f32_e32 v76, v59, v79
	v_add_f32_e32 v103, v88, v72
	v_fmac_f32_e32 v76, v58, v78
	ds_read_b128 v[72:75], v117 offset:640
	v_add_f32_e32 v76, v77, v76
	v_add_f32_e32 v121, v89, v76
	ds_read_b128 v[88:91], v117 offset:1664
	ds_read_b128 v[76:79], v117 offset:704
	s_waitcnt lgkmcnt(2)
	v_mul_f32_e32 v92, v81, v73
	v_mul_f32_e32 v93, v83, v75
	v_fmac_f32_e32 v92, v80, v72
	v_fmac_f32_e32 v93, v82, v74
	s_waitcnt lgkmcnt(1)
	v_mul_f32_e32 v89, v81, v89
	v_mul_f32_e32 v81, v53, v81
	v_add_f32_e32 v92, v92, v93
	v_fmac_f32_e32 v89, v80, v88
	v_mul_f32_e32 v88, v83, v91
	v_fmac_f32_e32 v81, v52, v80
	v_mul_f32_e32 v80, v55, v83
	v_add_f32_e32 v102, v102, v92
	ds_read_b128 v[92:95], v117 offset:1728
	v_fmac_f32_e32 v88, v82, v90
	v_fmac_f32_e32 v80, v54, v82
	v_add_f32_e32 v88, v89, v88
	v_add_f32_e32 v80, v81, v80
	v_add_f32_e32 v88, v103, v88
	v_add_f32_e32 v103, v121, v80
	s_waitcnt lgkmcnt(1)
	v_mul_f32_e32 v80, v85, v77
	v_mul_f32_e32 v81, v87, v79
	v_fmac_f32_e32 v80, v84, v76
	v_fmac_f32_e32 v81, v86, v78
	v_add_f32_e32 v80, v80, v81
	v_add_f32_e32 v102, v102, v80
	s_waitcnt lgkmcnt(0)
	v_mul_f32_e32 v80, v85, v93
	v_mul_f32_e32 v81, v87, v95
	v_fmac_f32_e32 v80, v84, v92
	v_fmac_f32_e32 v81, v86, v94
	v_add_f32_e32 v80, v80, v81
	v_add_f32_e32 v121, v88, v80
	v_mul_f32_e32 v80, v49, v85
	v_mul_f32_e32 v81, v51, v87
	v_fmac_f32_e32 v80, v48, v84
	v_fmac_f32_e32 v81, v50, v86
	v_add_f32_e32 v84, v80, v81
	ds_read_b128 v[88:91], v117 offset:256
	ds_read_b128 v[80:83], v117 offset:768
	v_add_f32_e32 v103, v103, v84
	ds_read_b128 v[92:95], v117 offset:1792
	ds_read_b128 v[122:125], v117 offset:320
	ds_read_b128 v[84:87], v117 offset:832
	ds_read_b128 v[130:133], v117 offset:1856
	s_waitcnt lgkmcnt(4)
	v_mul_f32_e32 v126, v89, v81
	s_waitcnt lgkmcnt(3)
	v_mul_f32_e32 v93, v89, v93
	s_waitcnt vmcnt(19)
	v_mul_f32_e32 v89, v45, v89
	v_fmac_f32_e32 v126, v88, v80
	v_fmac_f32_e32 v93, v88, v92
	v_fmac_f32_e32 v89, v44, v88
	v_mul_f32_e32 v88, v47, v91
	v_mul_f32_e32 v92, v91, v95
	v_fmac_f32_e32 v88, v46, v90
	v_mul_f32_e32 v127, v91, v83
	v_fmac_f32_e32 v92, v90, v94
	v_add_f32_e32 v88, v89, v88
	v_fmac_f32_e32 v127, v90, v82
	v_add_f32_e32 v92, v93, v92
	v_add_f32_e32 v93, v103, v88
	s_waitcnt lgkmcnt(1)
	v_mul_f32_e32 v88, v123, v85
	v_mul_f32_e32 v89, v125, v87
	v_add_f32_e32 v126, v126, v127
	v_fmac_f32_e32 v88, v122, v84
	v_fmac_f32_e32 v89, v124, v86
	v_add_f32_e32 v102, v102, v126
	v_add_f32_e32 v88, v88, v89
	v_add_f32_e32 v102, v102, v88
	s_waitcnt lgkmcnt(0)
	v_mul_f32_e32 v88, v123, v131
	v_mul_f32_e32 v89, v125, v133
	v_fmac_f32_e32 v88, v122, v130
	v_fmac_f32_e32 v89, v124, v132
	v_add_f32_e32 v92, v121, v92
	v_add_f32_e32 v88, v88, v89
	v_add_f32_e32 v103, v92, v88
	v_mul_f32_e32 v88, v41, v123
	v_mul_f32_e32 v89, v43, v125
	v_fmac_f32_e32 v88, v40, v122
	v_fmac_f32_e32 v89, v42, v124
	v_add_f32_e32 v92, v88, v89
	ds_read_b128 v[122:125], v117 offset:384
	ds_read_b128 v[88:91], v117 offset:896
	v_add_f32_e32 v121, v93, v92
	ds_read_b128 v[130:133], v117 offset:1920
	ds_read_b128 v[134:137], v117 offset:448
	ds_read_b128 v[92:95], v117 offset:960
	ds_read_b128 v[138:141], v117 offset:1984
	s_waitcnt lgkmcnt(4)
	v_mul_f32_e32 v126, v123, v89
	v_mul_f32_e32 v127, v125, v91
	v_fmac_f32_e32 v126, v122, v88
	v_fmac_f32_e32 v127, v124, v90
	v_add_f32_e32 v126, v126, v127
	v_add_f32_e32 v102, v102, v126
	s_waitcnt lgkmcnt(3)
	v_mul_f32_e32 v126, v123, v131
	v_mul_f32_e32 v123, v37, v123
	v_fmac_f32_e32 v126, v122, v130
	v_fmac_f32_e32 v123, v36, v122
	v_mul_f32_e32 v122, v39, v125
	v_fmac_f32_e32 v122, v38, v124
	v_add_f32_e32 v122, v123, v122
	v_add_f32_e32 v121, v121, v122
	s_waitcnt lgkmcnt(1)
	v_mul_f32_e32 v122, v135, v93
	v_mul_f32_e32 v123, v137, v95
	v_fmac_f32_e32 v122, v134, v92
	v_fmac_f32_e32 v123, v136, v94
	v_mul_f32_e32 v127, v125, v133
	v_add_f32_e32 v122, v122, v123
	v_fmac_f32_e32 v127, v124, v132
	v_add_f32_e32 v122, v102, v122
	s_waitcnt lgkmcnt(0)
	v_mul_f32_e32 v102, v135, v139
	v_mul_f32_e32 v123, v137, v141
	v_add_f32_e32 v126, v126, v127
	v_fmac_f32_e32 v102, v134, v138
	v_fmac_f32_e32 v123, v136, v140
	v_add_f32_e32 v103, v103, v126
	v_add_f32_e32 v102, v102, v123
	v_add_f32_e32 v123, v103, v102
	ds_bpermute_b32 v124, v111, v122
	ds_bpermute_b32 v127, v111, v123
	v_mul_f32_e32 v102, v33, v135
	v_mul_f32_e32 v103, v35, v137
	v_fmac_f32_e32 v102, v32, v134
	v_fmac_f32_e32 v103, v34, v136
	v_add_f32_e32 v102, v102, v103
	v_add_f32_e32 v121, v121, v102
	s_waitcnt lgkmcnt(1)
	v_add_f32_e32 v125, v122, v124
	s_waitcnt vmcnt(8)
	v_mul_f32_e64 v124, |v118|, s1
	ds_bpermute_b32 v130, v111, v121
	s_waitcnt lgkmcnt(1)
	v_add_f32_e32 v122, v123, v127
	v_exp_f32_e32 v127, v124
	s_mov_b32 s1, 0x3f2aaaab
	v_max_f32_e32 v118, v118, v118
	s_waitcnt lgkmcnt(0)
	v_add_f32_e32 v121, v121, v130
	v_add_f32_e32 v132, 1.0, v127
	v_add_f32_e32 v130, -1.0, v132
	v_sub_f32_e32 v131, v130, v132
	v_add_f32_e32 v131, 1.0, v131
	v_sub_f32_e32 v130, v127, v130
	v_add_f32_e32 v133, v130, v131
	v_frexp_mant_f32_e32 v134, v132
	v_cvt_f64_f32_e32 v[130:131], v132
	v_frexp_exp_i32_f64_e32 v130, v[130:131]
	v_cmp_gt_f32_e32 vcc, s1, v134
	s_mov_b32 s1, 0x3f317218
	v_min_f32_e32 v118, 0, v118
	v_subbrev_co_u32_e32 v138, vcc, 0, v130, vcc
	v_sub_u32_e32 v130, 0, v138
	v_ldexp_f32 v131, v132, v130
	v_add_f32_e32 v132, -1.0, v131
	v_add_f32_e32 v134, 1.0, v131
	v_ldexp_f32 v130, v133, v130
	v_add_f32_e32 v133, 1.0, v132
	v_add_f32_e32 v135, -1.0, v134
	v_sub_f32_e32 v133, v131, v133
	v_sub_f32_e32 v131, v131, v135
	v_add_f32_e32 v133, v130, v133
	v_add_f32_e32 v130, v130, v131
	v_add_f32_e32 v139, v134, v130
	v_rcp_f32_e32 v141, v139
	v_sub_f32_e32 v131, v139, v134
	v_sub_f32_e32 v140, v130, v131
	v_add_f32_e32 v131, v132, v133
	v_mul_f32_e32 v143, v131, v141
	v_sub_f32_e32 v130, v131, v132
	v_mul_f32_e32 v132, v139, v143
	v_fma_f32 v134, v143, v139, -v132
	v_fmac_f32_e32 v134, v143, v140
	v_sub_f32_e32 v142, v133, v130
	v_add_f32_e32 v130, v132, v134
	v_sub_f32_e32 v133, v131, v130
	v_pk_add_f32 v[136:137], v[130:131], v[132:133] neg_lo:[0,1] neg_hi:[0,1]
	v_mov_b32_e32 v135, v130
	v_pk_add_f32 v[130:131], v[136:137], v[134:135] neg_lo:[0,1] neg_hi:[0,1]
	v_lshl_add_u64 v[102:103], v[98:99], 0, s[76:77]
	v_add_f32_e32 v131, v142, v131
	v_add_f32_e32 v130, v130, v131
	v_add_f32_e32 v131, v133, v130
	v_mul_f32_e32 v142, v141, v131
	v_mul_f32_e32 v132, v139, v142
	v_fma_f32 v134, v142, v139, -v132
	v_fmac_f32_e32 v134, v142, v140
	v_sub_f32_e32 v133, v133, v131
	v_add_f32_e32 v139, v130, v133
	v_add_f32_e32 v130, v132, v134
	v_sub_f32_e32 v133, v131, v130
	v_pk_add_f32 v[136:137], v[130:131], v[132:133] neg_lo:[0,1] neg_hi:[0,1]
	v_mov_b32_e32 v135, v130
	v_pk_add_f32 v[130:131], v[136:137], v[134:135] neg_lo:[0,1] neg_hi:[0,1]
	v_cvt_f32_i32_e32 v132, v138
	v_add_f32_e32 v131, v139, v131
	v_add_f32_e32 v130, v130, v131
	v_add_f32_e32 v130, v133, v130
	v_add_f32_e32 v133, v143, v142
	v_sub_f32_e32 v131, v133, v143
	v_mul_f32_e32 v130, v141, v130
	v_sub_f32_e32 v131, v142, v131
	v_add_f32_e32 v130, v131, v130
	v_add_f32_e32 v134, v133, v130
	v_mul_f32_e32 v136, v134, v134
	v_mov_b32_e32 v131, 0x3ecc95a3
	v_sub_f32_e32 v133, v134, v133
	v_fmac_f32_e32 v131, 0x3e9b6dac, v136
	v_sub_f32_e32 v130, v130, v133
	v_fmaak_f32 v131, v136, v131, 0x3f2aaada
	v_ldexp_f32 v137, v130, 1
	v_mul_f32_e32 v133, v134, v136
	v_mov_b32_e32 v130, 0x3f317218
	v_pk_mul_f32 v[130:131], v[132:133], v[130:131]
	v_ldexp_f32 v135, v134, 1
	v_fma_f32 v133, v132, s1, -v130
	v_fmamk_f32 v134, v132, 0xb102e308, v133
	v_pk_add_f32 v[132:133], v[130:131], v[134:135]
	v_mov_b32_e32 v136, v130
	v_sub_f32_e32 v135, v133, v135
	v_sub_f32_e32 v135, v131, v135
	v_add_f32_e32 v137, v137, v135
	v_pk_add_f32 v[130:131], v[132:133], v[130:131] neg_lo:[0,1] neg_hi:[0,1]
	v_pk_add_f32 v[138:139], v[132:133], v[136:137]
	v_mov_b32_e32 v135, v132
	v_mov_b32_e32 v131, v139
	v_pk_add_f32 v[140:141], v[134:135], v[130:131] neg_lo:[0,1] neg_hi:[0,1]
	v_pk_add_f32 v[130:131], v[134:135], v[130:131]
	v_mov_b32_e32 v144, v133
	v_pk_add_f32 v[134:135], v[130:131], v[132:133] op_sel:[1,0] op_sel_hi:[0,1] neg_lo:[0,1] neg_hi:[0,1]
	v_pk_add_f32 v[142:143], v[138:139], v[134:135] op_sel_hi:[1,0] neg_lo:[0,1] neg_hi:[0,1]
	v_mov_b32_e32 v138, v139
	v_mov_b32_e32 v139, v131
	v_mov_b32_e32 v145, v134
	v_pk_add_f32 v[134:135], v[138:139], v[144:145] neg_lo:[0,1] neg_hi:[0,1]
	v_mov_b32_e32 v136, v137
	v_mov_b32_e32 v137, v132
	v_pk_add_f32 v[132:133], v[136:137], v[134:135] neg_lo:[0,1] neg_hi:[0,1]
	v_mov_b32_e32 v142, v140
	v_pk_add_f32 v[134:135], v[142:143], v[132:133]
	v_mov_b32_e32 v141, v131
	v_pk_add_f32 v[136:137], v[134:135], v[134:135] op_sel:[0,1] op_sel_hi:[1,0]
	s_mov_b32 s1, 0x7f800000
	v_pk_add_f32 v[130:131], v[130:131], v[136:137] op_sel:[1,0] op_sel_hi:[0,1]
	v_mov_b32_e32 v135, v130
	v_pk_add_f32 v[138:139], v[134:135], v[140:141] neg_lo:[0,1] neg_hi:[0,1]
	v_mov_b32_e32 v133, v136
	v_sub_f32_e32 v131, v134, v138
	v_pk_add_f32 v[132:133], v[132:133], v[138:139] neg_lo:[0,1] neg_hi:[0,1]
	v_sub_f32_e32 v131, v140, v131
	v_add_f32_e32 v131, v132, v131
	v_add_f32_e32 v131, v131, v133
	v_add_f32_e32 v130, v130, v131
	v_mov_b32_e32 v131, 0x7f800000
	v_cmp_neq_f32_e32 vcc, s1, v127
	s_mov_b32 s1, 0x33800000
	ds_bpermute_b32 v126, v115, v125
	v_cndmask_b32_e32 v130, v131, v130, vcc
	v_mov_b32_e32 v131, 0x7fc00000
	v_cmp_ngt_f32_e32 vcc, -1.0, v127
	ds_bpermute_b32 v123, v115, v122
	ds_bpermute_b32 v124, v115, v121
	v_cndmask_b32_e32 v130, v131, v130, vcc
	v_mov_b32_e32 v131, 0xff800000
	v_cmp_neq_f32_e32 vcc, -1.0, v127
	s_nop 1
	v_cndmask_b32_e32 v130, v131, v130, vcc
	v_cmp_lt_f32_e64 vcc, |v127|, s1
	s_nop 1
	v_cndmask_b32_e32 v127, v130, v127, vcc
	v_sub_f32_e32 v118, v118, v127
	s_waitcnt vmcnt(7)
	v_add_f32_e32 v105, v105, v118
	v_max_f32_e32 v118, v104, v104
	v_max_f32_e32 v130, v105, v118
	v_sub_f32_e32 v104, v104, v130
	v_lshl_add_u32 v118, v101, 2, 0
	v_mul_f32_e32 v104, 0x3fb8aa3b, v104
	ds_read_b32 v127, v118 offset:1024
	v_exp_f32_e32 v101, v104
	v_sub_f32_e32 v104, v105, v130
	v_mul_f32_e32 v104, 0x3fb8aa3b, v104
	v_exp_f32_e32 v104, v104
	s_waitcnt lgkmcnt(0)
	v_mul_f32_e32 v132, v101, v127
	v_pk_mul_f32 v[64:65], v[64:65], v[132:133] op_sel_hi:[1,0]
	v_pk_mul_f32 v[66:67], v[66:67], v[132:133] op_sel_hi:[1,0]
	v_pk_fma_f32 v[60:61], v[60:61], v[104:105], v[64:65] op_sel_hi:[1,0,1]
	v_pk_fma_f32 v[62:63], v[62:63], v[104:105], v[66:67] op_sel_hi:[1,0,1]
	global_store_dwordx4 v[102:103], v[60:63], off
	s_nop 1
	v_pk_mul_f32 v[60:61], v[68:69], v[132:133] op_sel_hi:[1,0]
	v_pk_mul_f32 v[62:63], v[70:71], v[132:133] op_sel_hi:[1,0]
	v_pk_fma_f32 v[56:57], v[56:57], v[104:105], v[60:61] op_sel_hi:[1,0,1]
	v_pk_fma_f32 v[58:59], v[58:59], v[104:105], v[62:63] op_sel_hi:[1,0,1]
	global_store_dwordx4 v[102:103], v[56:59], off offset:64
	s_nop 1
	v_pk_mul_f32 v[56:57], v[72:73], v[132:133] op_sel_hi:[1,0]
	v_pk_mul_f32 v[58:59], v[74:75], v[132:133] op_sel_hi:[1,0]
	v_pk_fma_f32 v[52:53], v[52:53], v[104:105], v[56:57] op_sel_hi:[1,0,1]
	v_pk_fma_f32 v[54:55], v[54:55], v[104:105], v[58:59] op_sel_hi:[1,0,1]
	global_store_dwordx4 v[102:103], v[52:55], off offset:128
	s_nop 1
	v_pk_mul_f32 v[52:53], v[76:77], v[132:133] op_sel_hi:[1,0]
	v_pk_mul_f32 v[54:55], v[78:79], v[132:133] op_sel_hi:[1,0]
	v_pk_fma_f32 v[48:49], v[48:49], v[104:105], v[52:53] op_sel_hi:[1,0,1]
	v_pk_fma_f32 v[50:51], v[50:51], v[104:105], v[54:55] op_sel_hi:[1,0,1]
	global_store_dwordx4 v[102:103], v[48:51], off offset:192
	s_nop 1
	v_pk_mul_f32 v[48:49], v[80:81], v[132:133] op_sel_hi:[1,0]
	v_pk_mul_f32 v[50:51], v[82:83], v[132:133] op_sel_hi:[1,0]
	v_pk_fma_f32 v[44:45], v[44:45], v[104:105], v[48:49] op_sel_hi:[1,0,1]
	v_pk_fma_f32 v[46:47], v[46:47], v[104:105], v[50:51] op_sel_hi:[1,0,1]
	global_store_dwordx4 v[102:103], v[44:47], off offset:256
	s_nop 1
	v_pk_mul_f32 v[44:45], v[84:85], v[132:133] op_sel_hi:[1,0]
	v_pk_mul_f32 v[46:47], v[86:87], v[132:133] op_sel_hi:[1,0]
	v_pk_fma_f32 v[40:41], v[40:41], v[104:105], v[44:45] op_sel_hi:[1,0,1]
	v_pk_fma_f32 v[42:43], v[42:43], v[104:105], v[46:47] op_sel_hi:[1,0,1]
	global_store_dwordx4 v[102:103], v[40:43], off offset:320
	s_nop 1
	v_pk_mul_f32 v[40:41], v[88:89], v[132:133] op_sel_hi:[1,0]
	v_pk_mul_f32 v[42:43], v[90:91], v[132:133] op_sel_hi:[1,0]
	v_pk_fma_f32 v[36:37], v[36:37], v[104:105], v[40:41] op_sel_hi:[1,0,1]
	v_pk_fma_f32 v[38:39], v[38:39], v[104:105], v[42:43] op_sel_hi:[1,0,1]
	global_store_dwordx4 v[102:103], v[36:39], off offset:384
	s_nop 1
	v_pk_mul_f32 v[36:37], v[92:93], v[132:133] op_sel_hi:[1,0]
	v_pk_mul_f32 v[38:39], v[94:95], v[132:133] op_sel_hi:[1,0]
	v_pk_fma_f32 v[32:33], v[32:33], v[104:105], v[36:37] op_sel_hi:[1,0,1]
	v_pk_fma_f32 v[34:35], v[34:35], v[104:105], v[38:39] op_sel_hi:[1,0,1]
	global_store_dwordx4 v[102:103], v[32:35], off offset:448
	s_and_saveexec_b64 s[4:5], s[2:3]
	s_cbranch_execz .LBB0_419
	v_lshl_add_u32 v32, v128, 2, 0
	ds_read_b32 v105, v32 offset:512
	s_add_u32 s6, s26, s74
	s_addc_u32 s7, s27, s75
	v_lshlrev_b32_e32 v32, 2, v128
	v_mov_b32_e32 v33, 0
	v_lshl_add_u64 v[32:33], s[6:7], 0, v[32:33]
	s_waitcnt lgkmcnt(0)
	v_pk_mul_f32 v[34:35], v[100:101], v[104:105]
	v_add_co_u32_e32 v32, vcc, 0x761c000, v32
	v_add_f32_e32 v34, v34, v35
	s_nop 0
	v_addc_co_u32_e32 v33, vcc, 0, v33, vcc
	global_store_dword v[32:33], v34, off offset:128

.LBB0_423:
	s_or_b64 exec, exec, s[20:21]
	ds_read_b128 v[40:43], v117 offset:2048
	ds_read_b128 v[44:47], v117 offset:2112
	s_waitcnt lgkmcnt(2)
	ds_read_b128 v[32:35], v117 offset:2560
	ds_read_b128 v[48:51], v117 offset:2176
	ds_read_b128 v[52:55], v117 offset:2240
	ds_read_b128 v[56:59], v117 offset:3584
	ds_read_b128 v[36:39], v117 offset:2624
	s_waitcnt lgkmcnt(4)
	v_mul_f32_e32 v60, v41, v33
	v_mul_f32_e32 v61, v43, v35
	v_fmac_f32_e32 v60, v40, v32
	v_fmac_f32_e32 v61, v42, v34
	s_waitcnt lgkmcnt(1)
	v_mul_f32_e32 v57, v41, v57
	v_mul_f32_e32 v41, v29, v41
	v_add_f32_e32 v60, v60, v61
	v_fmac_f32_e32 v57, v40, v56
	v_fmac_f32_e32 v41, v28, v40
	v_mul_f32_e32 v40, v31, v43
	v_add_f32_e32 v64, 0, v60
	ds_read_b128 v[60:63], v117 offset:3648
	v_mul_f32_e32 v56, v43, v59
	v_fmac_f32_e32 v40, v30, v42
	v_fmac_f32_e32 v56, v42, v58
	v_add_f32_e32 v40, v41, v40
	v_add_f32_e32 v56, v57, v56
	v_add_f32_e32 v57, 0, v40
	s_waitcnt lgkmcnt(1)
	v_mul_f32_e32 v40, v45, v37
	v_mul_f32_e32 v41, v47, v39
	v_fmac_f32_e32 v40, v44, v36
	v_fmac_f32_e32 v41, v46, v38
	v_add_f32_e32 v40, v40, v41
	v_add_f32_e32 v64, v64, v40
	s_waitcnt lgkmcnt(0)
	v_mul_f32_e32 v40, v45, v61
	v_mul_f32_e32 v41, v47, v63
	v_fmac_f32_e32 v40, v44, v60
	v_fmac_f32_e32 v41, v46, v62
	v_mul_f32_e32 v45, v25, v45
	v_add_f32_e32 v56, 0, v56
	v_add_f32_e32 v40, v40, v41
	v_fmac_f32_e32 v45, v24, v44
	v_mul_f32_e32 v44, v27, v47
	v_add_f32_e32 v65, v56, v40
	v_fmac_f32_e32 v44, v26, v46
	ds_read_b128 v[40:43], v117 offset:2688
	v_add_f32_e32 v44, v45, v44
	v_add_f32_e32 v66, v57, v44
	ds_read_b128 v[56:59], v117 offset:3712
	ds_read_b128 v[44:47], v117 offset:2752
	s_waitcnt lgkmcnt(2)
	v_mul_f32_e32 v60, v49, v41
	v_mul_f32_e32 v61, v51, v43
	v_fmac_f32_e32 v60, v48, v40
	v_fmac_f32_e32 v61, v50, v42
	s_waitcnt lgkmcnt(1)
	v_mul_f32_e32 v57, v49, v57
	v_mul_f32_e32 v49, v21, v49
	v_add_f32_e32 v60, v60, v61
	v_fmac_f32_e32 v57, v48, v56
	v_mul_f32_e32 v56, v51, v59
	v_fmac_f32_e32 v49, v20, v48
	v_mul_f32_e32 v48, v23, v51
	v_add_f32_e32 v64, v64, v60
	ds_read_b128 v[60:63], v117 offset:3776
	v_fmac_f32_e32 v56, v50, v58
	v_fmac_f32_e32 v48, v22, v50
	v_add_f32_e32 v56, v57, v56
	v_add_f32_e32 v48, v49, v48
	v_add_f32_e32 v56, v65, v56
	v_add_f32_e32 v65, v66, v48
	s_waitcnt lgkmcnt(1)
	v_mul_f32_e32 v48, v53, v45
	v_mul_f32_e32 v49, v55, v47
	v_fmac_f32_e32 v48, v52, v44
	v_fmac_f32_e32 v49, v54, v46
	v_add_f32_e32 v48, v48, v49
	v_add_f32_e32 v74, v64, v48
	s_waitcnt lgkmcnt(0)
	v_mul_f32_e32 v48, v53, v61
	v_mul_f32_e32 v49, v55, v63
	v_fmac_f32_e32 v48, v52, v60
	v_fmac_f32_e32 v49, v54, v62
	v_add_f32_e32 v48, v48, v49
	v_add_f32_e32 v78, v56, v48
	v_mul_f32_e32 v48, v17, v53
	v_mul_f32_e32 v49, v19, v55
	v_fmac_f32_e32 v48, v16, v52
	v_fmac_f32_e32 v49, v18, v54
	v_add_f32_e32 v52, v48, v49
	ds_read_b128 v[56:59], v117 offset:2304
	ds_read_b128 v[48:51], v117 offset:2816
	v_add_f32_e32 v79, v65, v52
	ds_read_b128 v[60:63], v117 offset:3840
	ds_read_b128 v[64:67], v117 offset:2368
	ds_read_b128 v[52:55], v117 offset:2880
	s_waitcnt lgkmcnt(3)
	v_mul_f32_e32 v75, v57, v49
	v_mul_f32_e32 v76, v59, v51
	v_fmac_f32_e32 v75, v56, v48
	v_fmac_f32_e32 v76, v58, v50
	s_waitcnt lgkmcnt(2)
	v_mul_f32_e32 v61, v57, v61
	v_mul_f32_e32 v57, v13, v57
	v_add_f32_e32 v75, v75, v76
	v_fmac_f32_e32 v61, v56, v60
	v_fmac_f32_e32 v57, v12, v56
	v_mul_f32_e32 v56, v15, v59
	v_add_f32_e32 v80, v74, v75
	ds_read_b128 v[74:77], v117 offset:3904
	v_mul_f32_e32 v60, v59, v63
	v_fmac_f32_e32 v56, v14, v58
	v_fmac_f32_e32 v60, v58, v62
	v_add_f32_e32 v56, v57, v56
	v_add_f32_e32 v60, v61, v60
	v_add_f32_e32 v61, v79, v56
	s_waitcnt lgkmcnt(1)
	v_mul_f32_e32 v56, v65, v53
	v_mul_f32_e32 v57, v67, v55
	v_fmac_f32_e32 v56, v64, v52
	v_fmac_f32_e32 v57, v66, v54
	v_add_f32_e32 v56, v56, v57
	v_add_f32_e32 v82, v80, v56
	s_waitcnt lgkmcnt(0)
	v_mul_f32_e32 v56, v65, v75
	v_mul_f32_e32 v57, v67, v77
	v_fmac_f32_e32 v56, v64, v74
	v_fmac_f32_e32 v57, v66, v76
	v_add_f32_e32 v60, v78, v60
	v_add_f32_e32 v56, v56, v57
	v_add_f32_e32 v86, v60, v56
	v_mul_f32_e32 v56, v9, v65
	v_mul_f32_e32 v57, v11, v67
	v_fmac_f32_e32 v56, v8, v64
	v_fmac_f32_e32 v57, v10, v66
	v_add_f32_e32 v60, v56, v57
	ds_read_b128 v[64:67], v117 offset:2432
	ds_read_b128 v[56:59], v117 offset:2944
	v_add_f32_e32 v87, v61, v60
	ds_read_b128 v[74:77], v117 offset:3968
	ds_read_b128 v[78:81], v117 offset:2496
	ds_read_b128 v[60:63], v117 offset:3008
	s_waitcnt lgkmcnt(3)
	v_mul_f32_e32 v83, v65, v57
	v_mul_f32_e32 v84, v67, v59
	v_fmac_f32_e32 v83, v64, v56
	v_fmac_f32_e32 v84, v66, v58
	v_add_f32_e32 v83, v83, v84
	s_waitcnt lgkmcnt(2)
	v_mul_f32_e32 v75, v65, v75
	v_mul_f32_e32 v65, v5, v65
	v_add_f32_e32 v88, v82, v83
	ds_read_b128 v[82:85], v117 offset:4032
	v_fmac_f32_e32 v75, v64, v74
	v_fmac_f32_e32 v65, v4, v64
	v_mul_f32_e32 v64, v7, v67
	v_mul_f32_e32 v74, v67, v77
	v_fmac_f32_e32 v64, v6, v66
	v_fmac_f32_e32 v74, v66, v76
	v_add_f32_e32 v64, v65, v64
	s_waitcnt lgkmcnt(1)
	v_mul_f32_e32 v65, v79, v61
	v_mul_f32_e32 v66, v81, v63
	v_fmac_f32_e32 v65, v78, v60
	v_fmac_f32_e32 v66, v80, v62
	v_add_f32_e32 v65, v65, v66
	v_add_f32_e32 v66, v88, v65
	s_waitcnt lgkmcnt(0)
	v_mul_f32_e32 v65, v79, v83
	v_mul_f32_e32 v67, v81, v85
	v_add_f32_e32 v74, v75, v74
	v_fmac_f32_e32 v65, v78, v82
	v_fmac_f32_e32 v67, v80, v84
	v_add_f32_e32 v74, v86, v74
	v_add_f32_e32 v65, v65, v67
	v_add_f32_e32 v67, v74, v65
	v_mul_f32_e32 v65, v1, v79
	v_mul_f32_e32 v74, v3, v81
	v_fmac_f32_e32 v65, v0, v78
	v_fmac_f32_e32 v74, v2, v80
	v_add_f32_e32 v65, v65, v74
	ds_bpermute_b32 v74, v111, v66
	v_add_f32_e32 v64, v87, v64
	v_add_f32_e32 v77, v64, v65
	ds_bpermute_b32 v80, v111, v77
	ds_bpermute_b32 v75, v111, v67
	s_waitcnt lgkmcnt(2)
	v_add_f32_e32 v78, v66, v74
	s_waitcnt vmcnt(13)
	v_mul_f32_e64 v66, |v116|, s1
	v_exp_f32_e32 v94, v66
	s_waitcnt lgkmcnt(1)
	v_add_f32_e32 v74, v77, v80
	v_max_f32_e32 v66, v116, v116
	v_min_f32_e32 v95, 0, v66
	v_add_f32_e32 v80, 1.0, v94
	v_add_f32_e32 v66, -1.0, v80
	s_waitcnt lgkmcnt(0)
	v_add_f32_e32 v75, v67, v75
	v_sub_f32_e32 v67, v66, v80
	v_add_f32_e32 v67, 1.0, v67
	v_sub_f32_e32 v66, v94, v66
	v_add_f32_e32 v81, v66, v67
	v_frexp_mant_f32_e32 v82, v80
	s_mov_b32 s1, 0x3f2aaaab
	v_cvt_f64_f32_e32 v[66:67], v80
	v_frexp_exp_i32_f64_e32 v66, v[66:67]
	v_cmp_gt_f32_e32 vcc, s1, v82
	s_mov_b32 s1, 0x3f317218
	v_lshl_add_u64 v[64:65], v[98:99], 0, s[64:65]
	v_subbrev_co_u32_e32 v86, vcc, 0, v66, vcc
	v_sub_u32_e32 v66, 0, v86
	v_ldexp_f32 v67, v80, v66
	v_add_f32_e32 v80, -1.0, v67
	v_add_f32_e32 v82, 1.0, v67
	v_ldexp_f32 v66, v81, v66
	v_add_f32_e32 v81, 1.0, v80
	v_add_f32_e32 v83, -1.0, v82
	v_sub_f32_e32 v81, v67, v81
	v_sub_f32_e32 v67, v67, v83
	v_add_f32_e32 v81, v66, v81
	v_add_f32_e32 v66, v66, v67
	v_add_f32_e32 v87, v82, v66
	v_rcp_f32_e32 v89, v87
	v_sub_f32_e32 v67, v87, v82
	v_sub_f32_e32 v88, v66, v67
	v_add_f32_e32 v67, v80, v81
	v_mul_f32_e32 v91, v67, v89
	v_sub_f32_e32 v66, v67, v80
	v_mul_f32_e32 v80, v87, v91
	v_fma_f32 v82, v91, v87, -v80
	v_fmac_f32_e32 v82, v91, v88
	v_sub_f32_e32 v90, v81, v66
	v_add_f32_e32 v66, v80, v82
	v_sub_f32_e32 v81, v67, v66
	v_pk_add_f32 v[84:85], v[66:67], v[80:81] neg_lo:[0,1] neg_hi:[0,1]
	v_mov_b32_e32 v83, v66
	v_pk_add_f32 v[66:67], v[84:85], v[82:83] neg_lo:[0,1] neg_hi:[0,1]
	ds_bpermute_b32 v79, v115, v78
	v_add_f32_e32 v67, v90, v67
	v_add_f32_e32 v66, v66, v67
	v_add_f32_e32 v67, v81, v66
	v_mul_f32_e32 v90, v89, v67
	v_mul_f32_e32 v80, v87, v90
	v_fma_f32 v82, v90, v87, -v80
	v_fmac_f32_e32 v82, v90, v88
	v_sub_f32_e32 v81, v81, v67
	v_add_f32_e32 v87, v66, v81
	v_add_f32_e32 v66, v80, v82
	v_sub_f32_e32 v81, v67, v66
	v_pk_add_f32 v[84:85], v[66:67], v[80:81] neg_lo:[0,1] neg_hi:[0,1]
	v_mov_b32_e32 v83, v66
	v_pk_add_f32 v[66:67], v[84:85], v[82:83] neg_lo:[0,1] neg_hi:[0,1]
	v_cvt_f32_i32_e32 v80, v86
	v_add_f32_e32 v67, v87, v67
	v_add_f32_e32 v66, v66, v67
	v_add_f32_e32 v66, v81, v66
	v_add_f32_e32 v81, v91, v90
	v_sub_f32_e32 v67, v81, v91
	v_mul_f32_e32 v66, v89, v66
	v_sub_f32_e32 v67, v90, v67
	v_add_f32_e32 v66, v67, v66
	v_add_f32_e32 v82, v81, v66
	v_mul_f32_e32 v84, v82, v82
	v_mov_b32_e32 v67, 0x3ecc95a3
	v_sub_f32_e32 v81, v82, v81
	v_fmac_f32_e32 v67, 0x3e9b6dac, v84
	v_sub_f32_e32 v66, v66, v81
	v_fmaak_f32 v67, v84, v67, 0x3f2aaada
	v_ldexp_f32 v85, v66, 1
	v_mul_f32_e32 v81, v82, v84
	v_mov_b32_e32 v66, 0x3f317218
	v_pk_mul_f32 v[66:67], v[80:81], v[66:67]
	v_ldexp_f32 v83, v82, 1
	v_fma_f32 v81, v80, s1, -v66
	v_fmamk_f32 v82, v80, 0xb102e308, v81
	v_pk_add_f32 v[80:81], v[66:67], v[82:83]
	v_mov_b32_e32 v84, v66
	v_sub_f32_e32 v83, v81, v83
	v_sub_f32_e32 v83, v67, v83
	v_add_f32_e32 v85, v85, v83
	v_pk_add_f32 v[66:67], v[80:81], v[66:67] neg_lo:[0,1] neg_hi:[0,1]
	v_pk_add_f32 v[86:87], v[80:81], v[84:85]
	v_mov_b32_e32 v83, v80
	v_mov_b32_e32 v67, v87
	v_pk_add_f32 v[88:89], v[82:83], v[66:67] neg_lo:[0,1] neg_hi:[0,1]
	v_pk_add_f32 v[66:67], v[82:83], v[66:67]
	v_mov_b32_e32 v92, v81
	v_pk_add_f32 v[82:83], v[66:67], v[80:81] op_sel:[1,0] op_sel_hi:[0,1] neg_lo:[0,1] neg_hi:[0,1]
	v_pk_add_f32 v[90:91], v[86:87], v[82:83] op_sel_hi:[1,0] neg_lo:[0,1] neg_hi:[0,1]
	v_mov_b32_e32 v86, v87
	v_mov_b32_e32 v87, v67
	v_mov_b32_e32 v93, v82
	v_pk_add_f32 v[82:83], v[86:87], v[92:93] neg_lo:[0,1] neg_hi:[0,1]
	v_mov_b32_e32 v84, v85
	v_mov_b32_e32 v85, v80
	v_pk_add_f32 v[80:81], v[84:85], v[82:83] neg_lo:[0,1] neg_hi:[0,1]
	v_mov_b32_e32 v90, v88
	v_pk_add_f32 v[82:83], v[90:91], v[80:81]
	v_mov_b32_e32 v89, v67
	v_pk_add_f32 v[84:85], v[82:83], v[82:83] op_sel:[0,1] op_sel_hi:[1,0]
	s_mov_b32 s1, 0x7f800000
	v_pk_add_f32 v[66:67], v[66:67], v[84:85] op_sel:[1,0] op_sel_hi:[0,1]
	v_mov_b32_e32 v83, v66
	v_pk_add_f32 v[86:87], v[82:83], v[88:89] neg_lo:[0,1] neg_hi:[0,1]
	v_mov_b32_e32 v81, v84
	v_sub_f32_e32 v67, v82, v86
	v_pk_add_f32 v[80:81], v[80:81], v[86:87] neg_lo:[0,1] neg_hi:[0,1]
	v_sub_f32_e32 v67, v88, v67
	v_add_f32_e32 v67, v80, v67
	v_add_f32_e32 v67, v67, v81
	v_add_f32_e32 v66, v66, v67
	v_mov_b32_e32 v67, 0x7f800000
	v_cmp_neq_f32_e32 vcc, s1, v94
	s_mov_b32 s1, 0x33800000
	ds_read_b32 v80, v118 offset:3072
	v_cndmask_b32_e32 v66, v67, v66, vcc
	v_mov_b32_e32 v67, 0x7fc00000
	v_cmp_ngt_f32_e32 vcc, -1.0, v94
	ds_bpermute_b32 v76, v115, v75
	ds_bpermute_b32 v77, v115, v74
	v_cndmask_b32_e32 v66, v67, v66, vcc
	v_mov_b32_e32 v67, 0xff800000
	v_cmp_neq_f32_e32 vcc, -1.0, v94
	s_nop 1
	v_cndmask_b32_e32 v66, v67, v66, vcc
	v_cmp_lt_f32_e64 vcc, |v94|, s1
	v_max_f32_e32 v67, v97, v97
	s_nop 0
	v_cndmask_b32_e32 v66, v66, v94, vcc
	v_sub_f32_e32 v66, v95, v66
	s_waitcnt vmcnt(12)
	v_add_f32_e32 v66, v114, v66
	v_max_f32_e32 v81, v66, v67
	v_sub_f32_e32 v67, v97, v81
	v_mul_f32_e32 v67, 0x3fb8aa3b, v67
	v_exp_f32_e32 v97, v67
	v_sub_f32_e32 v66, v66, v81
	v_mul_f32_e32 v66, 0x3fb8aa3b, v66
	v_exp_f32_e32 v66, v66
	s_waitcnt lgkmcnt(2)
	v_mul_f32_e32 v82, v97, v80
	v_pk_mul_f32 v[32:33], v[32:33], v[82:83] op_sel_hi:[1,0]
	v_pk_mul_f32 v[34:35], v[34:35], v[82:83] op_sel_hi:[1,0]
	v_pk_fma_f32 v[28:29], v[28:29], v[66:67], v[32:33] op_sel_hi:[1,0,1]
	v_pk_fma_f32 v[30:31], v[30:31], v[66:67], v[34:35] op_sel_hi:[1,0,1]
	global_store_dwordx4 v[64:65], v[28:31], off
	s_nop 1
	v_pk_mul_f32 v[28:29], v[36:37], v[82:83] op_sel_hi:[1,0]
	v_pk_mul_f32 v[30:31], v[38:39], v[82:83] op_sel_hi:[1,0]
	v_pk_fma_f32 v[24:25], v[24:25], v[66:67], v[28:29] op_sel_hi:[1,0,1]
	v_pk_fma_f32 v[26:27], v[26:27], v[66:67], v[30:31] op_sel_hi:[1,0,1]
	global_store_dwordx4 v[64:65], v[24:27], off offset:64
	s_nop 1
	v_pk_mul_f32 v[24:25], v[40:41], v[82:83] op_sel_hi:[1,0]
	v_pk_mul_f32 v[26:27], v[42:43], v[82:83] op_sel_hi:[1,0]
	v_pk_fma_f32 v[20:21], v[20:21], v[66:67], v[24:25] op_sel_hi:[1,0,1]
	v_pk_fma_f32 v[22:23], v[22:23], v[66:67], v[26:27] op_sel_hi:[1,0,1]
	global_store_dwordx4 v[64:65], v[20:23], off offset:128
	s_nop 1
	v_pk_mul_f32 v[20:21], v[44:45], v[82:83] op_sel_hi:[1,0]
	v_pk_mul_f32 v[22:23], v[46:47], v[82:83] op_sel_hi:[1,0]
	v_pk_fma_f32 v[16:17], v[16:17], v[66:67], v[20:21] op_sel_hi:[1,0,1]
	v_pk_fma_f32 v[18:19], v[18:19], v[66:67], v[22:23] op_sel_hi:[1,0,1]
	global_store_dwordx4 v[64:65], v[16:19], off offset:192
	s_nop 1
	v_pk_mul_f32 v[16:17], v[48:49], v[82:83] op_sel_hi:[1,0]
	v_pk_mul_f32 v[18:19], v[50:51], v[82:83] op_sel_hi:[1,0]
	v_pk_fma_f32 v[12:13], v[12:13], v[66:67], v[16:17] op_sel_hi:[1,0,1]
	v_pk_fma_f32 v[14:15], v[14:15], v[66:67], v[18:19] op_sel_hi:[1,0,1]
	global_store_dwordx4 v[64:65], v[12:15], off offset:256
	s_nop 1
	v_pk_mul_f32 v[12:13], v[52:53], v[82:83] op_sel_hi:[1,0]
	v_pk_mul_f32 v[14:15], v[54:55], v[82:83] op_sel_hi:[1,0]
	v_pk_fma_f32 v[8:9], v[8:9], v[66:67], v[12:13] op_sel_hi:[1,0,1]
	v_pk_fma_f32 v[10:11], v[10:11], v[66:67], v[14:15] op_sel_hi:[1,0,1]
	global_store_dwordx4 v[64:65], v[8:11], off offset:320
	s_nop 1
	v_pk_mul_f32 v[8:9], v[56:57], v[82:83] op_sel_hi:[1,0]
	v_pk_mul_f32 v[10:11], v[58:59], v[82:83] op_sel_hi:[1,0]
	v_pk_fma_f32 v[4:5], v[4:5], v[66:67], v[8:9] op_sel_hi:[1,0,1]
	v_pk_fma_f32 v[6:7], v[6:7], v[66:67], v[10:11] op_sel_hi:[1,0,1]
	global_store_dwordx4 v[64:65], v[4:7], off offset:384
	s_nop 1
	v_pk_mul_f32 v[4:5], v[60:61], v[82:83] op_sel_hi:[1,0]
	v_pk_mul_f32 v[6:7], v[62:63], v[82:83] op_sel_hi:[1,0]
	v_pk_fma_f32 v[0:1], v[0:1], v[66:67], v[4:5] op_sel_hi:[1,0,1]
	v_pk_fma_f32 v[2:3], v[2:3], v[66:67], v[6:7] op_sel_hi:[1,0,1]
	global_store_dwordx4 v[64:65], v[0:3], off offset:448
	s_and_saveexec_b64 s[20:21], s[2:3]
	s_cbranch_execz .LBB0_425
	v_lshl_add_u32 v0, v128, 2, 0
	ds_read_b32 v67, v0 offset:2560
	s_add_u32 s2, s26, s12
	s_addc_u32 s3, s27, s13
	v_lshlrev_b32_e32 v0, 2, v128
	v_mov_b32_e32 v1, 0
	v_lshl_add_u64 v[0:1], s[2:3], 0, v[0:1]
	s_waitcnt vmcnt(19) lgkmcnt(0)
	v_pk_mul_f32 v[2:3], v[96:97], v[66:67]
	v_add_co_u32_e32 v0, vcc, 0x761c000, v0
	v_add_f32_e32 v2, v2, v3
	s_nop 0
	v_addc_co_u32_e32 v1, vcc, 0, v1, vcc
	global_store_dword v[0:1], v2, off offset:128

.LBB0_567:
	s_and_b64 vcc, exec, s[2:3]
	v_lshrrev_b32_e32 v111, 2, v128
	s_waitcnt vmcnt(16)
	v_lshlrev_b32_e32 v112, 2, v109
	v_lshlrev_b32_e32 v96, 4, v109
	s_cbranch_vccz .LBB0_585
	s_lshl_b32 s76, s21, 2
	s_add_u32 s0, s28, s76
	s_addc_u32 s1, s29, 0
	s_add_u32 s23, s0, 0x2fc3000
	s_addc_u32 s33, s1, 0
	s_lshl_b32 s58, s16, 2
	s_or_b32 s0, s58, s21
	s_ashr_i32 s1, s0, 31
	s_ashr_i32 s17, s16, 31
	s_lshl_b64 s[70:71], s[0:1], 16
	s_lshl_b64 s[2:3], s[16:17], 5
	v_readlane_b32 s36, v255, 1
	s_add_u32 s2, s23, s2
	v_readlane_b32 s50, v255, 15
	s_addc_u32 s3, s33, s3
	s_lshl_b64 s[14:15], s[0:1], 2
	v_readlane_b32 s51, v255, 16
	s_add_u32 s14, s50, s14
	v_mov_b32_e32 v65, 0
	v_lshlrev_b32_e32 v64, 9, v111
	v_readlane_b32 s46, v255, 11
	v_readlane_b32 s47, v255, 12
	s_addc_u32 s15, s51, s15
	s_lshl_b64 s[64:65], s[0:1], 9
	s_lshl_b32 s0, s54, 2
	s_waitcnt lgkmcnt(0)
	v_and_b32_e32 v2, 0x7f, v128
	v_lshl_add_u64 v[0:1], s[46:47], 0, v[64:65]
	v_mov_b32_e32 v97, v65
	s_or_b32 s72, s0, s21
	v_readlane_b32 s48, v255, 13
	v_readlane_b32 s49, v255, 14
	v_lshl_add_u64 v[0:1], v[0:1], 0, v[96:97]
	v_lshlrev_b32_e32 v64, 2, v2
	s_ashr_i32 s73, s72, 31
	s_ashr_i32 s55, s54, 31
	v_lshl_add_u64 v[66:67], s[48:49], 0, v[64:65]
	v_lshl_add_u64 v[2:3], v[0:1], 0, s[70:71]
	s_lshl_b64 s[56:57], s[72:73], 16
	s_lshl_b64 s[78:79], s[54:55], 5
	global_load_dwordx4 v[48:51], v[2:3], off offset:192
	global_load_dwordx4 v[52:55], v[2:3], off offset:128
	global_load_dwordx4 v[56:59], v[2:3], off offset:64
	global_load_dwordx4 v[60:63], v[2:3], off
	global_load_dwordx4 v[32:35], v[2:3], off offset:448
	global_load_dwordx4 v[36:39], v[2:3], off offset:384
	global_load_dwordx4 v[40:43], v[2:3], off offset:320
	global_load_dwordx4 v[44:47], v[2:3], off offset:256
	v_lshl_add_u64 v[2:3], v[66:67], 0, s[64:65]
	v_lshl_add_u64 v[12:13], v[0:1], 0, s[56:57]
	s_add_u32 s78, s23, s78
	global_load_dword v102, v[2:3], off
	global_load_dwordx4 v[16:19], v[12:13], off offset:192
	global_load_dwordx4 v[20:23], v[12:13], off offset:128
	global_load_dwordx4 v[24:27], v[12:13], off offset:64
	global_load_dwordx4 v[28:31], v[12:13], off
	s_nop 0
	global_load_dwordx4 v[0:3], v[12:13], off offset:448
	global_load_dwordx4 v[4:7], v[12:13], off offset:384
	global_load_dwordx4 v[8:11], v[12:13], off offset:320
	s_nop 0
	global_load_dwordx4 v[12:15], v[12:13], off offset:256
	s_addc_u32 s79, s33, s79
	s_lshl_b64 s[80:81], s[72:73], 2
	s_add_u32 s80, s50, s80
	s_addc_u32 s81, s51, s81
	global_load_dword v103, v65, s[2:3]
	global_load_dword v107, v65, s[2:3] offset:16
	global_load_dword v106, v65, s[14:15]
	global_load_dword v99, v65, s[78:79]
	global_load_dword v119, v65, s[78:79] offset:16
	global_load_dword v116, v65, s[80:81]
	s_lshl_b64 s[14:15], s[72:73], 9
	v_add_u32_e32 v64, s20, v111
	v_lshl_add_u64 v[66:67], v[66:67], 0, s[14:15]
	v_lshlrev_b32_e32 v97, 1, v64
	global_load_dword v98, v[66:67], off
	global_load_ushort v115, v97, s[4:5] offset:3072
	global_load_ushort v114, v97, s[6:7] offset:3072
	v_lshlrev_b32_e32 v64, 2, v64
	global_load_dword v113, v64, s[66:67]
	s_movk_i32 s1, 0x80
	v_lshlrev_b32_e32 v66, 7, v111
	v_cmp_gt_u32_e64 s[2:3], s1, v128
	v_readlane_b32 s37, v255, 2
	v_readlane_b32 s38, v255, 3
	v_readlane_b32 s39, v255, 4
	v_readlane_b32 s40, v255, 5
	v_readlane_b32 s41, v255, 6
	v_readlane_b32 s42, v255, 7
	v_readlane_b32 s43, v255, 8
	v_readlane_b32 s44, v255, 9
	v_readlane_b32 s45, v255, 10
	s_and_saveexec_b64 s[72:73], s[2:3]
	s_cbranch_execz .LBB0_570
	v_or_b32_e32 v67, s20, v128
	v_lshlrev_b32_e32 v64, 2, v67
	v_lshl_add_u64 v[68:69], s[60:61], 0, v[64:65]
	v_readlane_b32 s36, v255, 1
	v_add_co_u32_e32 v70, vcc, 0x3000, v68
	s_mul_i32 s33, s54, 0x3000
	v_readlane_b32 s44, v255, 9
	v_addc_co_u32_e32 v71, vcc, 0, v69, vcc
	s_mul_hi_i32 s17, s54, 0x3000
	v_readlane_b32 s45, v255, 10
	s_add_u32 s54, s44, s33
	v_add_co_u32_e32 v72, vcc, 0x2000, v68
	s_addc_u32 s55, s45, s17
	s_mul_hi_i32 s17, s16, 0x3000
	s_mulk_i32 s16, 0x3000
	v_addc_co_u32_e32 v73, vcc, 0, v69, vcc
	s_add_u32 s16, s44, s16
	v_add_co_u32_e32 v68, vcc, 0x1000, v68
	s_addc_u32 s17, s45, s17
	s_movk_i32 s1, 0x2000
	v_addc_co_u32_e32 v69, vcc, 0, v69, vcc
	v_lshl_add_u64 v[74:75], s[16:17], 0, v[64:65]
	v_add_co_u32_e32 v76, vcc, s1, v74
	s_movk_i32 s23, 0x1000
	s_nop 0
	v_addc_co_u32_e32 v77, vcc, 0, v75, vcc
	v_add_co_u32_e32 v74, vcc, s23, v74
	v_lshlrev_b32_e32 v67, 1, v67
	s_nop 0
	v_addc_co_u32_e32 v75, vcc, 0, v75, vcc
	global_load_dword v78, v64, s[62:63] offset:2048
	global_load_dword v79, v64, s[60:61] offset:2048
	global_load_dword v80, v64, s[62:63]
	global_load_dword v81, v64, s[16:17] offset:2048
	global_load_dword v82, v64, s[16:17]
	global_load_dword v83, v64, s[54:55]
	global_load_dword v84, v64, s[60:61]
	global_load_ushort v85, v67, s[6:7] offset:2048
	global_load_ushort v86, v67, s[4:5] offset:1024
	global_load_ushort v87, v67, s[4:5]
	global_load_dword v88, v[76:77], off offset:2048
	global_load_dword v89, v[74:75], off offset:2048
	s_nop 0
	global_load_dword v74, v[74:75], off
	s_nop 0
	global_load_dword v75, v[76:77], off
	s_nop 0
	global_load_dword v76, v[68:69], off
	global_load_dword v77, v[68:69], off offset:2048
	global_load_dword v90, v[72:73], off
	s_nop 0
	global_load_dword v72, v[72:73], off offset:2048
	s_nop 0
	global_load_dword v73, v[70:71], off
	global_load_dword v91, v[70:71], off offset:2048
	global_load_ushort v92, v67, s[6:7] offset:1024
	global_load_ushort v93, v67, s[6:7]
	s_nop 0
	global_load_ushort v67, v67, s[4:5] offset:2048
	v_lshl_add_u64 v[68:69], s[54:55], 0, v[64:65]
	v_add_co_u32_e32 v70, vcc, s1, v68
	v_readlane_b32 s37, v255, 2
	s_nop 0
	v_addc_co_u32_e32 v71, vcc, 0, v69, vcc
	v_add_co_u32_e32 v68, vcc, s23, v68
	v_readlane_b32 s38, v255, 3
	s_nop 0
	v_addc_co_u32_e32 v69, vcc, 0, v69, vcc
	global_load_dword v94, v[68:69], off
	global_load_dword v95, v[70:71], off
	s_nop 0
	global_load_dword v64, v64, s[54:55] offset:2048
	s_nop 0
	global_load_dword v68, v[68:69], off offset:2048
	s_nop 0
	global_load_dword v69, v[70:71], off offset:2048
	v_lshl_add_u32 v70, v128, 2, 0
	v_readlane_b32 s39, v255, 4
	v_readlane_b32 s40, v255, 5
	v_readlane_b32 s41, v255, 6
	v_readlane_b32 s42, v255, 7
	v_readlane_b32 s43, v255, 8
	v_readlane_b32 s46, v255, 11
	v_readlane_b32 s47, v255, 12
	v_readlane_b32 s48, v255, 13
	v_readlane_b32 s49, v255, 14
	v_readlane_b32 s50, v255, 15
	v_readlane_b32 s51, v255, 16
	s_waitcnt vmcnt(20)
	v_lshlrev_b32_e32 v71, 16, v85
	s_waitcnt vmcnt(19)
	v_lshlrev_b32_e32 v85, 16, v86
	s_waitcnt vmcnt(18)
	v_lshlrev_b32_e32 v86, 16, v87
	v_fma_f32 v81, v79, v81, v78
	s_waitcnt vmcnt(12)
	v_fmac_f32_e32 v81, v77, v89
	s_waitcnt vmcnt(10)
	v_fmac_f32_e32 v81, v72, v88
	v_fma_f32 v82, v84, v82, v80
	v_fmac_f32_e32 v82, v76, v74
	v_fmac_f32_e32 v82, v90, v75
	s_waitcnt vmcnt(8)
	v_fmac_f32_e32 v81, v91, v85
	v_fmac_f32_e32 v80, v84, v83
	v_fmac_f32_e32 v82, v73, v86
	v_mul_f32_e32 v75, 0xbfb8aa3b, v81
	s_waitcnt vmcnt(7)
	v_lshlrev_b32_e32 v85, 16, v92
	v_mul_f32_e32 v74, 0xbfb8aa3b, v82
	s_waitcnt vmcnt(4)
	v_fmac_f32_e32 v80, v76, v94
	v_exp_f32_e32 v75, v75
	s_waitcnt vmcnt(2)
	v_fmac_f32_e32 v78, v79, v64
	s_waitcnt vmcnt(1)
	v_fmac_f32_e32 v78, v77, v68
	s_waitcnt vmcnt(0)
	v_fmac_f32_e32 v78, v72, v69
	v_lshlrev_b32_e32 v86, 16, v93
	v_fmac_f32_e32 v80, v90, v95
	v_fmac_f32_e32 v78, v91, v85
	v_exp_f32_e32 v74, v74
	v_fmac_f32_e32 v80, v73, v86
	v_mul_f32_e32 v68, 0xbfb8aa3b, v78
	v_mul_f32_e32 v64, 0xbfb8aa3b, v80
	v_exp_f32_e32 v68, v68
	v_exp_f32_e32 v64, v64
	v_add_f32_e32 v75, 1.0, v75
	v_add_f32_e32 v74, 1.0, v74
	v_rcp_f32_e32 v75, v75
	v_rcp_f32_e32 v74, v74
	v_add_f32_e32 v68, 1.0, v68
	v_add_f32_e32 v64, 1.0, v64
	v_rcp_f32_e32 v68, v68
	v_rcp_f32_e32 v64, v64
	v_mul_f32_e32 v75, v81, v75
	v_lshlrev_b32_e32 v67, 16, v67
	v_mul_f32_e32 v74, v82, v74
	v_mul_f32_e32 v69, 0x3db504f3, v75
	ds_write2st64_b32 v70, v74, v69 offset1:2
	ds_write2st64_b32 v70, v67, v102 offset0:4 offset1:6
	v_mul_f32_e32 v67, v78, v68
	v_mul_f32_e32 v64, v80, v64
	v_mul_f32_e32 v67, 0x3db504f3, v67
	ds_write2st64_b32 v70, v64, v67 offset0:8 offset1:10
	ds_write2st64_b32 v70, v71, v98 offset0:12 offset1:14
.LBB0_570:
	s_or_b64 exec, exec, s[72:73]
	v_lshlrev_b32_e32 v64, 2, v66
	v_lshl_add_u64 v[66:67], s[26:27], 0, v[64:65]
	v_lshlrev_b32_e32 v64, 2, v112
	v_lshl_add_u64 v[66:67], v[66:67], 0, v[64:65]
	v_mbcnt_lo_u32_b32 v65, -1, 0
	s_mov_b64 s[4:5], 0x561c080
	v_mbcnt_hi_u32_b32 v122, -1, v65
	v_lshl_add_u64 v[100:101], v[66:67], 0, s[4:5]
	v_and_b32_e32 v66, 64, v122
	v_xor_b32_e32 v65, 1, v122
	v_add_u32_e32 v123, 64, v66
	v_cmp_lt_i32_e32 vcc, v65, v123
	s_waitcnt lgkmcnt(0)
	s_barrier
	v_add_u32_e32 v120, 0, v64
	v_cndmask_b32_e32 v65, v122, v65, vcc
	v_lshlrev_b32_e32 v117, 2, v65
	v_xor_b32_e32 v65, 2, v122
	v_cmp_lt_i32_e32 vcc, v65, v123
	s_mov_b32 s1, 0xbfb8aa3b
	s_nop 0
	v_cndmask_b32_e32 v65, v122, v65, vcc
	v_lshlrev_b32_e32 v118, 2, v65
	ds_read_b128 v[72:75], v120
	ds_read_b128 v[76:79], v120 offset:64
	ds_read_b128 v[64:67], v120 offset:512
	s_waitcnt vmcnt(34)
	ds_read_b128 v[80:83], v120 offset:128
	s_waitcnt vmcnt(33)
	ds_read_b128 v[84:87], v120 offset:192
	ds_read_b128 v[88:91], v120 offset:1536
	ds_read_b128 v[68:71], v120 offset:576
	s_waitcnt lgkmcnt(4)
	v_mul_f32_e32 v92, v73, v65
	v_mul_f32_e32 v93, v75, v67
	v_fmac_f32_e32 v92, v72, v64
	v_fmac_f32_e32 v93, v74, v66
	s_waitcnt lgkmcnt(1)
	v_mul_f32_e32 v89, v73, v89
	s_waitcnt vmcnt(23)
	v_mul_f32_e32 v73, v61, v73
	v_add_f32_e32 v92, v92, v93
	v_fmac_f32_e32 v89, v72, v88
	v_fmac_f32_e32 v73, v60, v72
	v_mul_f32_e32 v72, v63, v75
	v_add_f32_e32 v104, 0, v92
	ds_read_b128 v[92:95], v120 offset:1600
	v_mul_f32_e32 v88, v75, v91
	v_fmac_f32_e32 v72, v62, v74
	v_fmac_f32_e32 v88, v74, v90
	v_add_f32_e32 v72, v73, v72
	v_add_f32_e32 v88, v89, v88
	v_add_f32_e32 v89, 0, v72
	s_waitcnt lgkmcnt(1)
	v_mul_f32_e32 v72, v77, v69
	v_mul_f32_e32 v73, v79, v71
	v_fmac_f32_e32 v72, v76, v68
	v_fmac_f32_e32 v73, v78, v70
	v_add_f32_e32 v72, v72, v73
	v_add_f32_e32 v104, v104, v72
	s_waitcnt lgkmcnt(0)
	v_mul_f32_e32 v72, v77, v93
	v_mul_f32_e32 v73, v79, v95
	v_fmac_f32_e32 v72, v76, v92
	v_fmac_f32_e32 v73, v78, v94
	v_mul_f32_e32 v77, v57, v77
	v_add_f32_e32 v88, 0, v88
	v_add_f32_e32 v72, v72, v73
	v_fmac_f32_e32 v77, v56, v76
	v_mul_f32_e32 v76, v59, v79
	v_add_f32_e32 v105, v88, v72
	v_fmac_f32_e32 v76, v58, v78
	ds_read_b128 v[72:75], v120 offset:640
	v_add_f32_e32 v76, v77, v76
	v_add_f32_e32 v121, v89, v76
	ds_read_b128 v[88:91], v120 offset:1664
	ds_read_b128 v[76:79], v120 offset:704
	s_waitcnt lgkmcnt(2)
	v_mul_f32_e32 v92, v81, v73
	v_mul_f32_e32 v93, v83, v75
	v_fmac_f32_e32 v92, v80, v72
	v_fmac_f32_e32 v93, v82, v74
	s_waitcnt lgkmcnt(1)
	v_mul_f32_e32 v89, v81, v89
	v_mul_f32_e32 v81, v53, v81
	v_add_f32_e32 v92, v92, v93
	v_fmac_f32_e32 v89, v80, v88
	v_mul_f32_e32 v88, v83, v91
	v_fmac_f32_e32 v81, v52, v80
	v_mul_f32_e32 v80, v55, v83
	v_add_f32_e32 v104, v104, v92
	ds_read_b128 v[92:95], v120 offset:1728
	v_fmac_f32_e32 v88, v82, v90
	v_fmac_f32_e32 v80, v54, v82
	v_add_f32_e32 v88, v89, v88
	v_add_f32_e32 v80, v81, v80
	v_add_f32_e32 v88, v105, v88
	v_add_f32_e32 v105, v121, v80
	s_waitcnt lgkmcnt(1)
	v_mul_f32_e32 v80, v85, v77
	v_mul_f32_e32 v81, v87, v79
	v_fmac_f32_e32 v80, v84, v76
	v_fmac_f32_e32 v81, v86, v78
	v_add_f32_e32 v80, v80, v81
	v_add_f32_e32 v104, v104, v80
	s_waitcnt lgkmcnt(0)
	v_mul_f32_e32 v80, v85, v93
	v_mul_f32_e32 v81, v87, v95
	v_fmac_f32_e32 v80, v84, v92
	v_fmac_f32_e32 v81, v86, v94
	v_add_f32_e32 v80, v80, v81
	v_add_f32_e32 v121, v88, v80
	v_mul_f32_e32 v80, v49, v85
	v_mul_f32_e32 v81, v51, v87
	v_fmac_f32_e32 v80, v48, v84
	v_fmac_f32_e32 v81, v50, v86
	v_add_f32_e32 v84, v80, v81
	ds_read_b128 v[88:91], v120 offset:256
	ds_read_b128 v[80:83], v120 offset:768
	v_add_f32_e32 v105, v105, v84
	ds_read_b128 v[92:95], v120 offset:1792
	ds_read_b128 v[124:127], v120 offset:320
	ds_read_b128 v[84:87], v120 offset:832
	s_waitcnt lgkmcnt(3)
	v_mul_f32_e32 v130, v89, v81
	v_mul_f32_e32 v131, v91, v83
	v_fmac_f32_e32 v130, v88, v80
	v_fmac_f32_e32 v131, v90, v82
	s_waitcnt lgkmcnt(2)
	v_mul_f32_e32 v93, v89, v93
	s_waitcnt vmcnt(19)
	v_mul_f32_e32 v89, v45, v89
	v_add_f32_e32 v130, v130, v131
	v_fmac_f32_e32 v93, v88, v92
	v_fmac_f32_e32 v89, v44, v88
	v_mul_f32_e32 v88, v47, v91
	v_add_f32_e32 v104, v104, v130
	ds_read_b128 v[130:133], v120 offset:1856
	v_mul_f32_e32 v92, v91, v95
	v_fmac_f32_e32 v88, v46, v90
	v_fmac_f32_e32 v92, v90, v94
	v_add_f32_e32 v88, v89, v88
	v_add_f32_e32 v92, v93, v92
	v_add_f32_e32 v93, v105, v88
	s_waitcnt lgkmcnt(1)
	v_mul_f32_e32 v88, v125, v85
	v_mul_f32_e32 v89, v127, v87
	v_fmac_f32_e32 v88, v124, v84
	v_fmac_f32_e32 v89, v126, v86
	v_add_f32_e32 v88, v88, v89
	v_add_f32_e32 v104, v104, v88
	s_waitcnt lgkmcnt(0)
	v_mul_f32_e32 v88, v125, v131
	v_mul_f32_e32 v89, v127, v133
	v_fmac_f32_e32 v88, v124, v130
	v_fmac_f32_e32 v89, v126, v132
	v_add_f32_e32 v92, v121, v92
	v_add_f32_e32 v88, v88, v89
	v_add_f32_e32 v105, v92, v88
	v_mul_f32_e32 v88, v41, v125
	v_mul_f32_e32 v89, v43, v127
	v_fmac_f32_e32 v88, v40, v124
	v_fmac_f32_e32 v89, v42, v126
	v_add_f32_e32 v92, v88, v89
	ds_read_b128 v[124:127], v120 offset:384
	ds_read_b128 v[88:91], v120 offset:896
	v_add_f32_e32 v121, v93, v92
	ds_read_b128 v[130:133], v120 offset:1920
	ds_read_b128 v[134:137], v120 offset:448
	ds_read_b128 v[92:95], v120 offset:960
	s_waitcnt lgkmcnt(3)
	v_mul_f32_e32 v138, v125, v89
	v_mul_f32_e32 v139, v127, v91
	v_fmac_f32_e32 v138, v124, v88
	v_fmac_f32_e32 v139, v126, v90
	s_waitcnt lgkmcnt(2)
	v_mul_f32_e32 v131, v125, v131
	v_mul_f32_e32 v125, v37, v125
	v_add_f32_e32 v138, v138, v139
	v_fmac_f32_e32 v131, v124, v130
	v_fmac_f32_e32 v125, v36, v124
	v_mul_f32_e32 v124, v39, v127
	v_add_f32_e32 v104, v104, v138
	ds_read_b128 v[138:141], v120 offset:1984
	v_fmac_f32_e32 v124, v38, v126
	v_add_f32_e32 v124, v125, v124
	v_add_f32_e32 v121, v121, v124
	s_waitcnt lgkmcnt(1)
	v_mul_f32_e32 v124, v135, v93
	v_mul_f32_e32 v125, v137, v95
	v_fmac_f32_e32 v124, v134, v92
	v_fmac_f32_e32 v125, v136, v94
	v_mul_f32_e32 v130, v127, v133
	v_add_f32_e32 v124, v124, v125
	v_fmac_f32_e32 v130, v126, v132
	v_add_f32_e32 v124, v104, v124
	s_waitcnt lgkmcnt(0)
	v_mul_f32_e32 v104, v135, v139
	v_mul_f32_e32 v125, v137, v141
	v_add_f32_e32 v130, v131, v130
	v_fmac_f32_e32 v104, v134, v138
	v_fmac_f32_e32 v125, v136, v140
	v_add_f32_e32 v105, v105, v130
	v_add_f32_e32 v104, v104, v125
	v_add_f32_e32 v125, v105, v104
	v_mul_f32_e32 v104, v33, v135
	v_mul_f32_e32 v105, v35, v137
	v_fmac_f32_e32 v104, v32, v134
	v_fmac_f32_e32 v105, v34, v136
	v_add_f32_e32 v104, v104, v105
	v_add_f32_e32 v121, v121, v104
	ds_bpermute_b32 v126, v117, v124
	ds_bpermute_b32 v132, v117, v121
	v_lshl_add_u64 v[104:105], v[100:101], 0, s[70:71]
	ds_bpermute_b32 v127, v117, v125
	s_waitcnt lgkmcnt(2)
	v_add_f32_e32 v130, v124, v126
	s_waitcnt lgkmcnt(1)
	v_add_f32_e32 v124, v121, v132
	s_waitcnt vmcnt(8)
	v_mul_f32_e64 v121, |v107|, s1
	v_exp_f32_e32 v121, v121
	s_mov_b32 s1, 0x3f2aaaab
	v_max_f32_e32 v107, v107, v107
	v_min_f32_e32 v107, 0, v107
	v_add_f32_e32 v134, 1.0, v121
	v_add_f32_e32 v132, -1.0, v134
	v_sub_f32_e32 v133, v132, v134
	v_add_f32_e32 v133, 1.0, v133
	v_sub_f32_e32 v132, v121, v132
	v_add_f32_e32 v135, v132, v133
	v_frexp_mant_f32_e32 v136, v134
	v_cvt_f64_f32_e32 v[132:133], v134
	v_frexp_exp_i32_f64_e32 v132, v[132:133]
	v_cmp_gt_f32_e32 vcc, s1, v136
	s_mov_b32 s1, 0x3f317218
	s_waitcnt lgkmcnt(0)
	v_add_f32_e32 v125, v125, v127
	v_subbrev_co_u32_e32 v140, vcc, 0, v132, vcc
	v_sub_u32_e32 v132, 0, v140
	v_ldexp_f32 v133, v134, v132
	v_add_f32_e32 v134, -1.0, v133
	v_add_f32_e32 v136, 1.0, v133
	v_ldexp_f32 v132, v135, v132
	v_add_f32_e32 v135, 1.0, v134
	v_add_f32_e32 v137, -1.0, v136
	v_sub_f32_e32 v135, v133, v135
	v_sub_f32_e32 v133, v133, v137
	v_add_f32_e32 v135, v132, v135
	v_add_f32_e32 v132, v132, v133
	v_add_f32_e32 v141, v136, v132
	v_rcp_f32_e32 v143, v141
	v_sub_f32_e32 v133, v141, v136
	v_sub_f32_e32 v142, v132, v133
	v_add_f32_e32 v133, v134, v135
	v_mul_f32_e32 v145, v133, v143
	v_sub_f32_e32 v132, v133, v134
	v_mul_f32_e32 v134, v141, v145
	v_fma_f32 v136, v145, v141, -v134
	v_fmac_f32_e32 v136, v145, v142
	v_sub_f32_e32 v144, v135, v132
	v_add_f32_e32 v132, v134, v136
	v_sub_f32_e32 v135, v133, v132
	v_pk_add_f32 v[138:139], v[132:133], v[134:135] neg_lo:[0,1] neg_hi:[0,1]
	v_mov_b32_e32 v137, v132
	v_pk_add_f32 v[132:133], v[138:139], v[136:137] neg_lo:[0,1] neg_hi:[0,1]
	ds_bpermute_b32 v131, v118, v130
	v_add_f32_e32 v133, v144, v133
	v_add_f32_e32 v132, v132, v133
	v_add_f32_e32 v133, v135, v132
	v_mul_f32_e32 v144, v143, v133
	v_mul_f32_e32 v134, v141, v144
	v_fma_f32 v136, v144, v141, -v134
	v_fmac_f32_e32 v136, v144, v142
	v_sub_f32_e32 v135, v135, v133
	v_add_f32_e32 v141, v132, v135
	v_add_f32_e32 v132, v134, v136
	v_sub_f32_e32 v135, v133, v132
	v_pk_add_f32 v[138:139], v[132:133], v[134:135] neg_lo:[0,1] neg_hi:[0,1]
	v_mov_b32_e32 v137, v132
	v_pk_add_f32 v[132:133], v[138:139], v[136:137] neg_lo:[0,1] neg_hi:[0,1]
	v_cvt_f32_i32_e32 v134, v140
	v_add_f32_e32 v133, v141, v133
	v_add_f32_e32 v132, v132, v133
	v_add_f32_e32 v132, v135, v132
	v_add_f32_e32 v135, v145, v144
	v_sub_f32_e32 v133, v135, v145
	v_mul_f32_e32 v132, v143, v132
	v_sub_f32_e32 v133, v144, v133
	v_add_f32_e32 v132, v133, v132
	v_add_f32_e32 v136, v135, v132
	v_mul_f32_e32 v138, v136, v136
	v_mov_b32_e32 v133, 0x3ecc95a3
	v_sub_f32_e32 v135, v136, v135
	v_fmac_f32_e32 v133, 0x3e9b6dac, v138
	v_sub_f32_e32 v132, v132, v135
	v_fmaak_f32 v133, v138, v133, 0x3f2aaada
	v_ldexp_f32 v139, v132, 1
	v_mul_f32_e32 v135, v136, v138
	v_mov_b32_e32 v132, 0x3f317218
	v_pk_mul_f32 v[132:133], v[134:135], v[132:133]
	v_ldexp_f32 v137, v136, 1
	v_fma_f32 v135, v134, s1, -v132
	v_fmamk_f32 v136, v134, 0xb102e308, v135
	v_pk_add_f32 v[134:135], v[132:133], v[136:137]
	v_mov_b32_e32 v138, v132
	v_sub_f32_e32 v137, v135, v137
	v_sub_f32_e32 v137, v133, v137
	v_add_f32_e32 v139, v139, v137
	v_pk_add_f32 v[132:133], v[134:135], v[132:133] neg_lo:[0,1] neg_hi:[0,1]
	v_pk_add_f32 v[140:141], v[134:135], v[138:139]
	v_mov_b32_e32 v137, v134
	v_mov_b32_e32 v133, v141
	v_pk_add_f32 v[142:143], v[136:137], v[132:133] neg_lo:[0,1] neg_hi:[0,1]
	v_pk_add_f32 v[132:133], v[136:137], v[132:133]
	v_mov_b32_e32 v146, v135
	v_pk_add_f32 v[136:137], v[132:133], v[134:135] op_sel:[1,0] op_sel_hi:[0,1] neg_lo:[0,1] neg_hi:[0,1]
	v_pk_add_f32 v[144:145], v[140:141], v[136:137] op_sel_hi:[1,0] neg_lo:[0,1] neg_hi:[0,1]
	v_mov_b32_e32 v140, v141
	v_mov_b32_e32 v141, v133
	v_mov_b32_e32 v147, v136
	v_pk_add_f32 v[136:137], v[140:141], v[146:147] neg_lo:[0,1] neg_hi:[0,1]
	v_mov_b32_e32 v138, v139
	v_mov_b32_e32 v139, v134
	v_pk_add_f32 v[134:135], v[138:139], v[136:137] neg_lo:[0,1] neg_hi:[0,1]
	v_mov_b32_e32 v144, v142
	v_pk_add_f32 v[136:137], v[144:145], v[134:135]
	v_mov_b32_e32 v143, v133
	v_pk_add_f32 v[138:139], v[136:137], v[136:137] op_sel:[0,1] op_sel_hi:[1,0]
	s_mov_b32 s1, 0x7f800000
	v_pk_add_f32 v[132:133], v[132:133], v[138:139] op_sel:[1,0] op_sel_hi:[0,1]
	v_mov_b32_e32 v137, v132
	v_pk_add_f32 v[140:141], v[136:137], v[142:143] neg_lo:[0,1] neg_hi:[0,1]
	v_mov_b32_e32 v135, v138
	v_sub_f32_e32 v133, v136, v140
	v_pk_add_f32 v[134:135], v[134:135], v[140:141] neg_lo:[0,1] neg_hi:[0,1]
	v_sub_f32_e32 v133, v142, v133
	v_add_f32_e32 v133, v134, v133
	v_add_f32_e32 v133, v133, v135
	v_add_f32_e32 v132, v132, v133
	v_mov_b32_e32 v133, 0x7f800000
	v_cmp_neq_f32_e32 vcc, s1, v121
	s_mov_b32 s1, 0x33800000
	ds_bpermute_b32 v126, v118, v125
	v_cndmask_b32_e32 v132, v133, v132, vcc
	v_mov_b32_e32 v133, 0x7fc00000
	v_cmp_ngt_f32_e32 vcc, -1.0, v121
	ds_bpermute_b32 v127, v118, v124
	s_nop 0
	v_cndmask_b32_e32 v132, v133, v132, vcc
	v_mov_b32_e32 v133, 0xff800000
	v_cmp_neq_f32_e32 vcc, -1.0, v121
	s_nop 1
	v_cndmask_b32_e32 v132, v133, v132, vcc
	v_cmp_lt_f32_e64 vcc, |v121|, s1
	s_nop 1
	v_cndmask_b32_e32 v121, v132, v121, vcc
	v_sub_f32_e32 v107, v107, v121
	s_waitcnt vmcnt(7)
	v_add_f32_e32 v106, v106, v107
	v_max_f32_e32 v107, v103, v103
	v_max_f32_e32 v133, v106, v107
	v_sub_f32_e32 v103, v103, v133
	v_lshl_add_u32 v121, v111, 2, 0
	v_mul_f32_e32 v103, 0x3fb8aa3b, v103
	ds_read_b32 v132, v121 offset:1024
	v_exp_f32_e32 v103, v103
	v_sub_f32_e32 v106, v106, v133
	v_mul_f32_e32 v106, 0x3fb8aa3b, v106
	v_exp_f32_e32 v106, v106
	s_waitcnt lgkmcnt(0)
	v_mul_f32_e32 v134, v103, v132
	v_pk_mul_f32 v[64:65], v[64:65], v[134:135] op_sel_hi:[1,0]
	v_pk_mul_f32 v[66:67], v[66:67], v[134:135] op_sel_hi:[1,0]
	v_pk_fma_f32 v[60:61], v[60:61], v[106:107], v[64:65] op_sel_hi:[1,0,1]
	v_pk_fma_f32 v[62:63], v[62:63], v[106:107], v[66:67] op_sel_hi:[1,0,1]
	global_store_dwordx4 v[104:105], v[60:63], off
	s_nop 1
	v_pk_mul_f32 v[60:61], v[68:69], v[134:135] op_sel_hi:[1,0]
	v_pk_mul_f32 v[62:63], v[70:71], v[134:135] op_sel_hi:[1,0]
	v_pk_fma_f32 v[56:57], v[56:57], v[106:107], v[60:61] op_sel_hi:[1,0,1]
	v_pk_fma_f32 v[58:59], v[58:59], v[106:107], v[62:63] op_sel_hi:[1,0,1]
	global_store_dwordx4 v[104:105], v[56:59], off offset:64
	s_nop 1
	v_pk_mul_f32 v[56:57], v[72:73], v[134:135] op_sel_hi:[1,0]
	v_pk_mul_f32 v[58:59], v[74:75], v[134:135] op_sel_hi:[1,0]
	v_pk_fma_f32 v[52:53], v[52:53], v[106:107], v[56:57] op_sel_hi:[1,0,1]
	v_pk_fma_f32 v[54:55], v[54:55], v[106:107], v[58:59] op_sel_hi:[1,0,1]
	global_store_dwordx4 v[104:105], v[52:55], off offset:128
	s_nop 1
	v_pk_mul_f32 v[52:53], v[76:77], v[134:135] op_sel_hi:[1,0]
	v_pk_mul_f32 v[54:55], v[78:79], v[134:135] op_sel_hi:[1,0]
	v_pk_fma_f32 v[48:49], v[48:49], v[106:107], v[52:53] op_sel_hi:[1,0,1]
	v_pk_fma_f32 v[50:51], v[50:51], v[106:107], v[54:55] op_sel_hi:[1,0,1]
	global_store_dwordx4 v[104:105], v[48:51], off offset:192
	s_nop 1
	v_pk_mul_f32 v[48:49], v[80:81], v[134:135] op_sel_hi:[1,0]
	v_pk_mul_f32 v[50:51], v[82:83], v[134:135] op_sel_hi:[1,0]
	v_pk_fma_f32 v[44:45], v[44:45], v[106:107], v[48:49] op_sel_hi:[1,0,1]
	v_pk_fma_f32 v[46:47], v[46:47], v[106:107], v[50:51] op_sel_hi:[1,0,1]
	global_store_dwordx4 v[104:105], v[44:47], off offset:256
	s_nop 1
	v_pk_mul_f32 v[44:45], v[84:85], v[134:135] op_sel_hi:[1,0]
	v_pk_mul_f32 v[46:47], v[86:87], v[134:135] op_sel_hi:[1,0]
	v_pk_fma_f32 v[40:41], v[40:41], v[106:107], v[44:45] op_sel_hi:[1,0,1]
	v_pk_fma_f32 v[42:43], v[42:43], v[106:107], v[46:47] op_sel_hi:[1,0,1]
	global_store_dwordx4 v[104:105], v[40:43], off offset:320
	s_nop 1
	v_pk_mul_f32 v[40:41], v[88:89], v[134:135] op_sel_hi:[1,0]
	v_pk_mul_f32 v[42:43], v[90:91], v[134:135] op_sel_hi:[1,0]
	v_pk_fma_f32 v[36:37], v[36:37], v[106:107], v[40:41] op_sel_hi:[1,0,1]
	v_pk_fma_f32 v[38:39], v[38:39], v[106:107], v[42:43] op_sel_hi:[1,0,1]
	global_store_dwordx4 v[104:105], v[36:39], off offset:384
	s_nop 1
	v_pk_mul_f32 v[36:37], v[92:93], v[134:135] op_sel_hi:[1,0]
	v_pk_mul_f32 v[38:39], v[94:95], v[134:135] op_sel_hi:[1,0]
	v_pk_fma_f32 v[32:33], v[32:33], v[106:107], v[36:37] op_sel_hi:[1,0,1]
	v_pk_fma_f32 v[34:35], v[34:35], v[106:107], v[38:39] op_sel_hi:[1,0,1]
	global_store_dwordx4 v[104:105], v[32:35], off offset:448
	s_and_saveexec_b64 s[4:5], s[2:3]
	s_cbranch_execz .LBB0_572
	v_lshl_add_u32 v32, v128, 2, 0
	ds_read_b32 v107, v32 offset:512
	s_add_u32 s6, s26, s64
	s_addc_u32 s7, s27, s65
	v_lshlrev_b32_e32 v32, 2, v128
	v_mov_b32_e32 v33, 0
	v_lshl_add_u64 v[32:33], s[6:7], 0, v[32:33]
	s_waitcnt lgkmcnt(0)
	v_pk_mul_f32 v[34:35], v[102:103], v[106:107]
	v_add_co_u32_e32 v32, vcc, 0x761c000, v32
	v_add_f32_e32 v34, v34, v35
	s_nop 0
	v_addc_co_u32_e32 v33, vcc, 0, v33, vcc
	global_store_dword v[32:33], v34, off offset:128

.LBB0_576:
	s_or_b64 exec, exec, s[16:17]
	ds_read_b128 v[40:43], v120 offset:2048
	ds_read_b128 v[44:47], v120 offset:2112
	s_waitcnt lgkmcnt(2)
	ds_read_b128 v[32:35], v120 offset:2560
	ds_read_b128 v[48:51], v120 offset:2176
	ds_read_b128 v[52:55], v120 offset:2240
	ds_read_b128 v[56:59], v120 offset:3584
	ds_read_b128 v[36:39], v120 offset:2624
	s_waitcnt lgkmcnt(4)
	v_mul_f32_e32 v60, v41, v33
	v_mul_f32_e32 v61, v43, v35
	v_fmac_f32_e32 v60, v40, v32
	v_fmac_f32_e32 v61, v42, v34
	s_waitcnt lgkmcnt(1)
	v_mul_f32_e32 v57, v41, v57
	v_mul_f32_e32 v41, v29, v41
	v_add_f32_e32 v60, v60, v61
	v_fmac_f32_e32 v57, v40, v56
	v_fmac_f32_e32 v41, v28, v40
	v_mul_f32_e32 v40, v31, v43
	v_add_f32_e32 v64, 0, v60
	ds_read_b128 v[60:63], v120 offset:3648
	v_mul_f32_e32 v56, v43, v59
	v_fmac_f32_e32 v40, v30, v42
	v_fmac_f32_e32 v56, v42, v58
	v_add_f32_e32 v40, v41, v40
	v_add_f32_e32 v56, v57, v56
	v_add_f32_e32 v57, 0, v40
	s_waitcnt lgkmcnt(1)
	v_mul_f32_e32 v40, v45, v37
	v_mul_f32_e32 v41, v47, v39
	v_fmac_f32_e32 v40, v44, v36
	v_fmac_f32_e32 v41, v46, v38
	v_add_f32_e32 v40, v40, v41
	v_add_f32_e32 v64, v64, v40
	s_waitcnt lgkmcnt(0)
	v_mul_f32_e32 v40, v45, v61
	v_mul_f32_e32 v41, v47, v63
	v_fmac_f32_e32 v40, v44, v60
	v_fmac_f32_e32 v41, v46, v62
	v_mul_f32_e32 v45, v25, v45
	v_add_f32_e32 v56, 0, v56
	v_add_f32_e32 v40, v40, v41
	v_fmac_f32_e32 v45, v24, v44
	v_mul_f32_e32 v44, v27, v47
	v_add_f32_e32 v65, v56, v40
	v_fmac_f32_e32 v44, v26, v46
	ds_read_b128 v[40:43], v120 offset:2688
	v_add_f32_e32 v44, v45, v44
	v_add_f32_e32 v66, v57, v44
	ds_read_b128 v[56:59], v120 offset:3712
	ds_read_b128 v[44:47], v120 offset:2752
	s_waitcnt lgkmcnt(2)
	v_mul_f32_e32 v60, v49, v41
	v_mul_f32_e32 v61, v51, v43
	v_fmac_f32_e32 v60, v48, v40
	v_fmac_f32_e32 v61, v50, v42
	s_waitcnt lgkmcnt(1)
	v_mul_f32_e32 v57, v49, v57
	v_mul_f32_e32 v49, v21, v49
	v_add_f32_e32 v60, v60, v61
	v_fmac_f32_e32 v57, v48, v56
	v_mul_f32_e32 v56, v51, v59
	v_fmac_f32_e32 v49, v20, v48
	v_mul_f32_e32 v48, v23, v51
	v_add_f32_e32 v64, v64, v60
	ds_read_b128 v[60:63], v120 offset:3776
	v_fmac_f32_e32 v56, v50, v58
	v_fmac_f32_e32 v48, v22, v50
	v_add_f32_e32 v56, v57, v56
	v_add_f32_e32 v48, v49, v48
	v_add_f32_e32 v56, v65, v56
	v_add_f32_e32 v65, v66, v48
	s_waitcnt lgkmcnt(1)
	v_mul_f32_e32 v48, v53, v45
	v_mul_f32_e32 v49, v55, v47
	v_fmac_f32_e32 v48, v52, v44
	v_fmac_f32_e32 v49, v54, v46
	v_add_f32_e32 v48, v48, v49
	v_add_f32_e32 v73, v64, v48
	s_waitcnt lgkmcnt(0)
	v_mul_f32_e32 v48, v53, v61
	v_mul_f32_e32 v49, v55, v63
	v_fmac_f32_e32 v48, v52, v60
	v_fmac_f32_e32 v49, v54, v62
	v_add_f32_e32 v48, v48, v49
	v_add_f32_e32 v78, v56, v48
	v_mul_f32_e32 v48, v17, v53
	v_mul_f32_e32 v49, v19, v55
	v_fmac_f32_e32 v48, v16, v52
	v_fmac_f32_e32 v49, v18, v54
	v_add_f32_e32 v52, v48, v49
	ds_read_b128 v[56:59], v120 offset:2304
	ds_read_b128 v[48:51], v120 offset:2816
	v_add_f32_e32 v79, v65, v52
	ds_read_b128 v[60:63], v120 offset:3840
	ds_read_b128 v[64:67], v120 offset:2368
	ds_read_b128 v[52:55], v120 offset:2880
	s_waitcnt lgkmcnt(3)
	v_mul_f32_e32 v74, v57, v49
	v_mul_f32_e32 v75, v59, v51
	v_fmac_f32_e32 v74, v56, v48
	v_fmac_f32_e32 v75, v58, v50
	s_waitcnt lgkmcnt(2)
	v_mul_f32_e32 v61, v57, v61
	v_mul_f32_e32 v57, v13, v57
	v_add_f32_e32 v74, v74, v75
	v_fmac_f32_e32 v61, v56, v60
	v_fmac_f32_e32 v57, v12, v56
	v_mul_f32_e32 v56, v15, v59
	v_add_f32_e32 v73, v73, v74
	ds_read_b128 v[74:77], v120 offset:3904
	v_mul_f32_e32 v60, v59, v63
	v_fmac_f32_e32 v56, v14, v58
	v_fmac_f32_e32 v60, v58, v62
	v_add_f32_e32 v56, v57, v56
	v_add_f32_e32 v60, v61, v60
	v_add_f32_e32 v61, v79, v56
	s_waitcnt lgkmcnt(1)
	v_mul_f32_e32 v56, v65, v53
	v_mul_f32_e32 v57, v67, v55
	v_fmac_f32_e32 v56, v64, v52
	v_fmac_f32_e32 v57, v66, v54
	v_add_f32_e32 v56, v56, v57
	v_add_f32_e32 v73, v73, v56
	s_waitcnt lgkmcnt(0)
	v_mul_f32_e32 v56, v65, v75
	v_mul_f32_e32 v57, v67, v77
	v_fmac_f32_e32 v56, v64, v74
	v_fmac_f32_e32 v57, v66, v76
	v_add_f32_e32 v60, v78, v60
	v_add_f32_e32 v56, v56, v57
	v_add_f32_e32 v86, v60, v56
	v_mul_f32_e32 v56, v9, v65
	v_mul_f32_e32 v57, v11, v67
	v_fmac_f32_e32 v56, v8, v64
	v_fmac_f32_e32 v57, v10, v66
	v_add_f32_e32 v60, v56, v57
	ds_read_b128 v[64:67], v120 offset:2432
	ds_read_b128 v[56:59], v120 offset:2944
	v_add_f32_e32 v87, v61, v60
	ds_read_b128 v[74:77], v120 offset:3968
	ds_read_b128 v[78:81], v120 offset:2496
	ds_read_b128 v[60:63], v120 offset:3008
	s_waitcnt lgkmcnt(3)
	v_mul_f32_e32 v82, v65, v57
	v_mul_f32_e32 v83, v67, v59
	v_fmac_f32_e32 v82, v64, v56
	v_fmac_f32_e32 v83, v66, v58
	v_add_f32_e32 v82, v82, v83
	s_waitcnt lgkmcnt(2)
	v_mul_f32_e32 v75, v65, v75
	v_mul_f32_e32 v65, v5, v65
	v_add_f32_e32 v73, v73, v82
	ds_read_b128 v[82:85], v120 offset:4032
	v_fmac_f32_e32 v75, v64, v74
	v_fmac_f32_e32 v65, v4, v64
	v_mul_f32_e32 v64, v7, v67
	v_mul_f32_e32 v74, v67, v77
	v_fmac_f32_e32 v64, v6, v66
	v_fmac_f32_e32 v74, v66, v76
	v_add_f32_e32 v64, v65, v64
	s_waitcnt lgkmcnt(1)
	v_mul_f32_e32 v65, v79, v61
	v_mul_f32_e32 v66, v81, v63
	v_fmac_f32_e32 v65, v78, v60
	v_fmac_f32_e32 v66, v80, v62
	v_add_f32_e32 v65, v65, v66
	v_add_f32_e32 v66, v73, v65
	s_waitcnt lgkmcnt(0)
	v_mul_f32_e32 v65, v79, v83
	v_mul_f32_e32 v67, v81, v85
	v_add_f32_e32 v74, v75, v74
	v_fmac_f32_e32 v65, v78, v82
	v_fmac_f32_e32 v67, v80, v84
	v_add_f32_e32 v74, v86, v74
	v_add_f32_e32 v65, v65, v67
	v_add_f32_e32 v67, v74, v65
	v_mul_f32_e32 v65, v1, v79
	v_mul_f32_e32 v73, v3, v81
	v_fmac_f32_e32 v65, v0, v78
	v_fmac_f32_e32 v73, v2, v80
	v_add_f32_e32 v64, v87, v64
	v_add_f32_e32 v65, v65, v73
	ds_bpermute_b32 v73, v117, v66
	v_add_f32_e32 v76, v64, v65
	ds_bpermute_b32 v79, v117, v76
	ds_bpermute_b32 v74, v117, v67
	v_lshl_add_u64 v[64:65], v[100:101], 0, s[56:57]
	s_waitcnt lgkmcnt(2)
	v_add_f32_e32 v77, v66, v73
	s_waitcnt vmcnt(13)
	v_mul_f32_e64 v66, |v119|, s1
	s_waitcnt lgkmcnt(1)
	v_add_f32_e32 v73, v76, v79
	v_exp_f32_e32 v79, v66
	v_max_f32_e32 v66, v119, v119
	v_min_f32_e32 v94, 0, v66
	s_waitcnt lgkmcnt(0)
	v_add_f32_e32 v74, v67, v74
	v_add_f32_e32 v80, 1.0, v79
	v_add_f32_e32 v66, -1.0, v80
	v_sub_f32_e32 v67, v66, v80
	v_add_f32_e32 v67, 1.0, v67
	v_sub_f32_e32 v66, v79, v66
	v_add_f32_e32 v81, v66, v67
	v_frexp_mant_f32_e32 v82, v80
	s_mov_b32 s1, 0x3f2aaaab
	v_cvt_f64_f32_e32 v[66:67], v80
	v_frexp_exp_i32_f64_e32 v66, v[66:67]
	v_cmp_gt_f32_e32 vcc, s1, v82
	s_mov_b32 s1, 0x3f317218
	ds_bpermute_b32 v78, v118, v77
	v_subbrev_co_u32_e32 v86, vcc, 0, v66, vcc
	v_sub_u32_e32 v66, 0, v86
	v_ldexp_f32 v67, v80, v66
	v_add_f32_e32 v80, -1.0, v67
	v_add_f32_e32 v82, 1.0, v67
	v_ldexp_f32 v66, v81, v66
	v_add_f32_e32 v81, 1.0, v80
	v_add_f32_e32 v83, -1.0, v82
	v_sub_f32_e32 v81, v67, v81
	v_sub_f32_e32 v67, v67, v83
	v_add_f32_e32 v81, v66, v81
	v_add_f32_e32 v66, v66, v67
	v_add_f32_e32 v87, v82, v66
	v_rcp_f32_e32 v89, v87
	v_sub_f32_e32 v67, v87, v82
	v_sub_f32_e32 v88, v66, v67
	v_add_f32_e32 v67, v80, v81
	v_mul_f32_e32 v91, v67, v89
	v_sub_f32_e32 v66, v67, v80
	v_mul_f32_e32 v80, v87, v91
	v_fma_f32 v82, v91, v87, -v80
	v_fmac_f32_e32 v82, v91, v88
	v_sub_f32_e32 v90, v81, v66
	v_add_f32_e32 v66, v80, v82
	v_sub_f32_e32 v81, v67, v66
	v_pk_add_f32 v[84:85], v[66:67], v[80:81] neg_lo:[0,1] neg_hi:[0,1]
	v_mov_b32_e32 v83, v66
	v_pk_add_f32 v[66:67], v[84:85], v[82:83] neg_lo:[0,1] neg_hi:[0,1]
	ds_bpermute_b32 v75, v118, v74
	v_add_f32_e32 v67, v90, v67
	v_add_f32_e32 v66, v66, v67
	v_add_f32_e32 v67, v81, v66
	v_mul_f32_e32 v90, v89, v67
	v_mul_f32_e32 v80, v87, v90
	v_fma_f32 v82, v90, v87, -v80
	v_fmac_f32_e32 v82, v90, v88
	v_sub_f32_e32 v81, v81, v67
	v_add_f32_e32 v87, v66, v81
	v_add_f32_e32 v66, v80, v82
	v_sub_f32_e32 v81, v67, v66
	v_pk_add_f32 v[84:85], v[66:67], v[80:81] neg_lo:[0,1] neg_hi:[0,1]
	v_mov_b32_e32 v83, v66
	v_pk_add_f32 v[66:67], v[84:85], v[82:83] neg_lo:[0,1] neg_hi:[0,1]
	v_cvt_f32_i32_e32 v80, v86
	v_add_f32_e32 v67, v87, v67
	v_add_f32_e32 v66, v66, v67
	v_add_f32_e32 v66, v81, v66
	v_add_f32_e32 v81, v91, v90
	v_sub_f32_e32 v67, v81, v91
	v_mul_f32_e32 v66, v89, v66
	v_sub_f32_e32 v67, v90, v67
	v_add_f32_e32 v66, v67, v66
	v_add_f32_e32 v82, v81, v66
	v_mul_f32_e32 v84, v82, v82
	v_mov_b32_e32 v67, 0x3ecc95a3
	v_sub_f32_e32 v81, v82, v81
	v_fmac_f32_e32 v67, 0x3e9b6dac, v84
	v_sub_f32_e32 v66, v66, v81
	v_fmaak_f32 v67, v84, v67, 0x3f2aaada
	v_ldexp_f32 v85, v66, 1
	v_mul_f32_e32 v81, v82, v84
	v_mov_b32_e32 v66, 0x3f317218
	v_pk_mul_f32 v[66:67], v[80:81], v[66:67]
	v_ldexp_f32 v83, v82, 1
	v_fma_f32 v81, v80, s1, -v66
	v_fmamk_f32 v82, v80, 0xb102e308, v81
	v_pk_add_f32 v[80:81], v[66:67], v[82:83]
	v_mov_b32_e32 v84, v66
	v_sub_f32_e32 v83, v81, v83
	v_sub_f32_e32 v83, v67, v83
	v_add_f32_e32 v85, v85, v83
	v_pk_add_f32 v[66:67], v[80:81], v[66:67] neg_lo:[0,1] neg_hi:[0,1]
	v_pk_add_f32 v[86:87], v[80:81], v[84:85]
	v_mov_b32_e32 v83, v80
	v_mov_b32_e32 v67, v87
	v_pk_add_f32 v[88:89], v[82:83], v[66:67] neg_lo:[0,1] neg_hi:[0,1]
	v_pk_add_f32 v[66:67], v[82:83], v[66:67]
	v_mov_b32_e32 v92, v81
	v_pk_add_f32 v[82:83], v[66:67], v[80:81] op_sel:[1,0] op_sel_hi:[0,1] neg_lo:[0,1] neg_hi:[0,1]
	v_pk_add_f32 v[90:91], v[86:87], v[82:83] op_sel_hi:[1,0] neg_lo:[0,1] neg_hi:[0,1]
	v_mov_b32_e32 v86, v87
	v_mov_b32_e32 v87, v67
	v_mov_b32_e32 v93, v82
	v_pk_add_f32 v[82:83], v[86:87], v[92:93] neg_lo:[0,1] neg_hi:[0,1]
	v_mov_b32_e32 v84, v85
	v_mov_b32_e32 v85, v80
	v_pk_add_f32 v[80:81], v[84:85], v[82:83] neg_lo:[0,1] neg_hi:[0,1]
	v_mov_b32_e32 v90, v88
	v_pk_add_f32 v[82:83], v[90:91], v[80:81]
	v_mov_b32_e32 v89, v67
	v_pk_add_f32 v[84:85], v[82:83], v[82:83] op_sel:[0,1] op_sel_hi:[1,0]
	s_mov_b32 s1, 0x7f800000
	v_pk_add_f32 v[66:67], v[66:67], v[84:85] op_sel:[1,0] op_sel_hi:[0,1]
	v_mov_b32_e32 v83, v66
	v_pk_add_f32 v[86:87], v[82:83], v[88:89] neg_lo:[0,1] neg_hi:[0,1]
	v_mov_b32_e32 v81, v84
	v_sub_f32_e32 v67, v82, v86
	v_pk_add_f32 v[80:81], v[80:81], v[86:87] neg_lo:[0,1] neg_hi:[0,1]
	v_sub_f32_e32 v67, v88, v67
	v_add_f32_e32 v67, v80, v67
	v_add_f32_e32 v67, v67, v81
	v_add_f32_e32 v66, v66, v67
	v_mov_b32_e32 v67, 0x7f800000
	v_cmp_neq_f32_e32 vcc, s1, v79
	s_mov_b32 s1, 0x33800000
	ds_bpermute_b32 v76, v118, v73
	v_cndmask_b32_e32 v66, v67, v66, vcc
	v_mov_b32_e32 v67, 0x7fc00000
	v_cmp_ngt_f32_e32 vcc, -1.0, v79
	s_nop 1
	v_cndmask_b32_e32 v66, v67, v66, vcc
	v_mov_b32_e32 v67, 0xff800000
	v_cmp_neq_f32_e32 vcc, -1.0, v79
	s_nop 1
	v_cndmask_b32_e32 v66, v67, v66, vcc
	v_cmp_lt_f32_e64 vcc, |v79|, s1
	v_max_f32_e32 v67, v99, v99
	s_nop 0
	v_cndmask_b32_e32 v66, v66, v79, vcc
	v_sub_f32_e32 v66, v94, v66
	s_waitcnt vmcnt(12)
	v_add_f32_e32 v66, v116, v66
	v_max_f32_e32 v80, v66, v67
	v_sub_f32_e32 v67, v99, v80
	v_mul_f32_e32 v67, 0x3fb8aa3b, v67
	ds_read_b32 v79, v121 offset:3072
	v_exp_f32_e32 v99, v67
	v_sub_f32_e32 v66, v66, v80
	v_mul_f32_e32 v66, 0x3fb8aa3b, v66
	v_exp_f32_e32 v66, v66
	s_waitcnt lgkmcnt(0)
	v_mul_f32_e32 v82, v99, v79
	v_pk_mul_f32 v[32:33], v[32:33], v[82:83] op_sel_hi:[1,0]
	v_pk_mul_f32 v[34:35], v[34:35], v[82:83] op_sel_hi:[1,0]
	v_pk_fma_f32 v[28:29], v[28:29], v[66:67], v[32:33] op_sel_hi:[1,0,1]
	v_pk_fma_f32 v[30:31], v[30:31], v[66:67], v[34:35] op_sel_hi:[1,0,1]
	global_store_dwordx4 v[64:65], v[28:31], off
	s_nop 1
	v_pk_mul_f32 v[28:29], v[36:37], v[82:83] op_sel_hi:[1,0]
	v_pk_mul_f32 v[30:31], v[38:39], v[82:83] op_sel_hi:[1,0]
	v_pk_fma_f32 v[24:25], v[24:25], v[66:67], v[28:29] op_sel_hi:[1,0,1]
	v_pk_fma_f32 v[26:27], v[26:27], v[66:67], v[30:31] op_sel_hi:[1,0,1]
	global_store_dwordx4 v[64:65], v[24:27], off offset:64
	s_nop 1
	v_pk_mul_f32 v[24:25], v[40:41], v[82:83] op_sel_hi:[1,0]
	v_pk_mul_f32 v[26:27], v[42:43], v[82:83] op_sel_hi:[1,0]
	v_pk_fma_f32 v[20:21], v[20:21], v[66:67], v[24:25] op_sel_hi:[1,0,1]
	v_pk_fma_f32 v[22:23], v[22:23], v[66:67], v[26:27] op_sel_hi:[1,0,1]
	global_store_dwordx4 v[64:65], v[20:23], off offset:128
	s_nop 1
	v_pk_mul_f32 v[20:21], v[44:45], v[82:83] op_sel_hi:[1,0]
	v_pk_mul_f32 v[22:23], v[46:47], v[82:83] op_sel_hi:[1,0]
	v_pk_fma_f32 v[16:17], v[16:17], v[66:67], v[20:21] op_sel_hi:[1,0,1]
	v_pk_fma_f32 v[18:19], v[18:19], v[66:67], v[22:23] op_sel_hi:[1,0,1]
	global_store_dwordx4 v[64:65], v[16:19], off offset:192
	s_nop 1
	v_pk_mul_f32 v[16:17], v[48:49], v[82:83] op_sel_hi:[1,0]
	v_pk_mul_f32 v[18:19], v[50:51], v[82:83] op_sel_hi:[1,0]
	v_pk_fma_f32 v[12:13], v[12:13], v[66:67], v[16:17] op_sel_hi:[1,0,1]
	v_pk_fma_f32 v[14:15], v[14:15], v[66:67], v[18:19] op_sel_hi:[1,0,1]
	global_store_dwordx4 v[64:65], v[12:15], off offset:256
	s_nop 1
	v_pk_mul_f32 v[12:13], v[52:53], v[82:83] op_sel_hi:[1,0]
	v_pk_mul_f32 v[14:15], v[54:55], v[82:83] op_sel_hi:[1,0]
	v_pk_fma_f32 v[8:9], v[8:9], v[66:67], v[12:13] op_sel_hi:[1,0,1]
	v_pk_fma_f32 v[10:11], v[10:11], v[66:67], v[14:15] op_sel_hi:[1,0,1]
	global_store_dwordx4 v[64:65], v[8:11], off offset:320
	s_nop 1
	v_pk_mul_f32 v[8:9], v[56:57], v[82:83] op_sel_hi:[1,0]
	v_pk_mul_f32 v[10:11], v[58:59], v[82:83] op_sel_hi:[1,0]
	v_pk_fma_f32 v[4:5], v[4:5], v[66:67], v[8:9] op_sel_hi:[1,0,1]
	v_pk_fma_f32 v[6:7], v[6:7], v[66:67], v[10:11] op_sel_hi:[1,0,1]
	global_store_dwordx4 v[64:65], v[4:7], off offset:384
	s_nop 1
	v_pk_mul_f32 v[4:5], v[60:61], v[82:83] op_sel_hi:[1,0]
	v_pk_mul_f32 v[6:7], v[62:63], v[82:83] op_sel_hi:[1,0]
	v_pk_fma_f32 v[0:1], v[0:1], v[66:67], v[4:5] op_sel_hi:[1,0,1]
	v_pk_fma_f32 v[2:3], v[2:3], v[66:67], v[6:7] op_sel_hi:[1,0,1]
	global_store_dwordx4 v[64:65], v[0:3], off offset:448
	s_and_saveexec_b64 s[16:17], s[2:3]
	s_cbranch_execz .LBB0_578
	v_lshl_add_u32 v0, v128, 2, 0
	ds_read_b32 v67, v0 offset:2560
	s_add_u32 s2, s26, s14
	s_addc_u32 s3, s27, s15
	v_lshlrev_b32_e32 v0, 2, v128
	v_mov_b32_e32 v1, 0
	v_lshl_add_u64 v[0:1], s[2:3], 0, v[0:1]
	s_waitcnt vmcnt(19) lgkmcnt(0)
	v_pk_mul_f32 v[2:3], v[98:99], v[66:67]
	v_add_co_u32_e32 v0, vcc, 0x761c000, v0
	v_add_f32_e32 v2, v2, v3
	s_nop 0
	v_addc_co_u32_e32 v1, vcc, 0, v1, vcc
	global_store_dword v[0:1], v2, off offset:128

.LBB0_601:
	s_and_b64 vcc, exec, s[0:1]
	s_cbranch_vccz .LBB0_619
	s_lshl_b32 s56, s21, 2
	s_add_u32 s0, s28, s56
	v_readlane_b32 s36, v255, 1
	s_addc_u32 s1, s29, 0
	v_mov_b32_e32 v65, 0
	v_lshlrev_b32_e32 v64, 9, v111
	v_readlane_b32 s46, v255, 11
	v_readlane_b32 s47, v255, 12
	s_add_u32 s23, s0, 0x2fc3000
	s_addc_u32 s33, s1, 0
	v_lshl_add_u64 v[0:1], s[46:47], 0, v[64:65]
	s_lshl_b32 s46, s14, 2
	s_or_b32 s0, s46, s21
	s_ashr_i32 s1, s0, 31
	s_ashr_i32 s15, s14, 31
	s_lshl_b64 s[52:53], s[0:1], 16
	s_lshl_b64 s[2:3], s[14:15], 5
	s_add_u32 s2, s23, s2
	s_waitcnt lgkmcnt(0)
	v_and_b32_e32 v2, 0x7f, v128
	v_readlane_b32 s50, v255, 15
	s_addc_u32 s3, s33, s3
	s_lshl_b64 s[8:9], s[0:1], 2
	v_readlane_b32 s48, v255, 13
	v_readlane_b32 s49, v255, 14
	v_readlane_b32 s51, v255, 16
	v_lshlrev_b32_e32 v64, 2, v2
	s_add_u32 s8, s50, s8
	v_lshl_add_u64 v[66:67], s[48:49], 0, v[64:65]
	s_addc_u32 s9, s51, s9
	s_lshl_b64 s[48:49], s[0:1], 9
	s_lshl_b32 s0, s54, 2
	v_mov_b32_e32 v97, v65
	s_or_b32 s58, s0, s21
	v_lshl_add_u64 v[0:1], v[0:1], 0, v[96:97]
	s_ashr_i32 s59, s58, 31
	s_ashr_i32 s55, s54, 31
	v_lshl_add_u64 v[2:3], v[0:1], 0, s[52:53]
	s_lshl_b64 s[16:17], s[58:59], 16
	s_lshl_b64 s[64:65], s[54:55], 5
	global_load_dwordx4 v[48:51], v[2:3], off offset:192
	global_load_dwordx4 v[52:55], v[2:3], off offset:128
	global_load_dwordx4 v[56:59], v[2:3], off offset:64
	global_load_dwordx4 v[60:63], v[2:3], off
	global_load_dwordx4 v[32:35], v[2:3], off offset:448
	global_load_dwordx4 v[36:39], v[2:3], off offset:384
	global_load_dwordx4 v[40:43], v[2:3], off offset:320
	global_load_dwordx4 v[44:47], v[2:3], off offset:256
	v_lshl_add_u64 v[2:3], v[66:67], 0, s[48:49]
	v_lshl_add_u64 v[12:13], v[0:1], 0, s[16:17]
	s_add_u32 s64, s23, s64
	global_load_dword v100, v[2:3], off
	global_load_dwordx4 v[16:19], v[12:13], off offset:192
	global_load_dwordx4 v[20:23], v[12:13], off offset:128
	global_load_dwordx4 v[24:27], v[12:13], off offset:64
	global_load_dwordx4 v[28:31], v[12:13], off
	s_nop 0
	global_load_dwordx4 v[0:3], v[12:13], off offset:448
	global_load_dwordx4 v[4:7], v[12:13], off offset:384
	global_load_dwordx4 v[8:11], v[12:13], off offset:320
	s_nop 0
	global_load_dwordx4 v[12:15], v[12:13], off offset:256
	s_addc_u32 s65, s33, s65
	s_lshl_b64 s[68:69], s[58:59], 2
	s_add_u32 s50, s50, s68
	s_addc_u32 s51, s51, s69
	global_load_dword v101, v65, s[2:3]
	global_load_dword v105, v65, s[2:3] offset:16
	global_load_dword v104, v65, s[8:9]
	global_load_dword v97, v65, s[64:65]
	global_load_dword v117, v65, s[64:65] offset:16
	global_load_dword v115, v65, s[50:51]
	s_lshl_b64 s[8:9], s[58:59], 9
	v_add_u32_e32 v64, s20, v111
	v_lshl_add_u64 v[66:67], v[66:67], 0, s[8:9]
	v_lshlrev_b32_e32 v106, 1, v64
	global_load_dword v96, v[66:67], off
	global_load_ushort v114, v106, s[4:5] offset:3072
	global_load_ushort v113, v106, s[6:7] offset:3072
	v_lshlrev_b32_e32 v64, 2, v64
	global_load_dword v107, v64, s[66:67]
	s_movk_i32 s1, 0x80
	v_lshlrev_b32_e32 v66, 7, v111
	v_cmp_gt_u32_e64 s[2:3], s1, v128
	v_readlane_b32 s37, v255, 2
	v_readlane_b32 s38, v255, 3
	v_readlane_b32 s39, v255, 4
	v_readlane_b32 s40, v255, 5
	v_readlane_b32 s41, v255, 6
	v_readlane_b32 s42, v255, 7
	v_readlane_b32 s43, v255, 8
	v_readlane_b32 s44, v255, 9
	v_readlane_b32 s45, v255, 10
	s_and_saveexec_b64 s[50:51], s[2:3]
	s_cbranch_execz .LBB0_604
	v_or_b32_e32 v67, s20, v128
	v_readlane_b32 s68, v255, 1
	v_lshlrev_b32_e32 v64, 2, v67
	v_readlane_b32 s69, v255, 2
	v_lshl_add_u64 v[68:69], s[60:61], 0, v[64:65]
	v_readlane_b32 s70, v255, 3
	v_readlane_b32 s71, v255, 4
	v_readlane_b32 s72, v255, 5
	v_readlane_b32 s73, v255, 6
	v_readlane_b32 s74, v255, 7
	v_readlane_b32 s75, v255, 8
	v_readlane_b32 s76, v255, 9
	v_readlane_b32 s77, v255, 10
	s_mov_b64 s[36:37], s[68:69]
	v_add_co_u32_e32 v70, vcc, 0x3000, v68
	s_mul_i32 s20, s54, 0x3000
	s_mov_b64 s[44:45], s[76:77]
	v_addc_co_u32_e32 v71, vcc, 0, v69, vcc
	s_mul_hi_i32 s15, s54, 0x3000
	s_add_u32 s20, s44, s20
	v_add_co_u32_e32 v72, vcc, 0x2000, v68
	s_addc_u32 s21, s45, s15
	s_mul_hi_i32 s15, s14, 0x3000
	s_mulk_i32 s14, 0x3000
	v_addc_co_u32_e32 v73, vcc, 0, v69, vcc
	s_add_u32 s14, s44, s14
	v_add_co_u32_e32 v68, vcc, 0x1000, v68
	s_addc_u32 s15, s45, s15
	s_movk_i32 s1, 0x2000
	v_addc_co_u32_e32 v69, vcc, 0, v69, vcc
	v_lshl_add_u64 v[74:75], s[14:15], 0, v[64:65]
	v_add_co_u32_e32 v76, vcc, s1, v74
	s_movk_i32 s23, 0x1000
	s_nop 0
	v_addc_co_u32_e32 v77, vcc, 0, v75, vcc
	v_add_co_u32_e32 v74, vcc, s23, v74
	v_lshlrev_b32_e32 v67, 1, v67
	s_nop 0
	v_addc_co_u32_e32 v75, vcc, 0, v75, vcc
	global_load_dword v78, v64, s[62:63] offset:2048
	global_load_dword v79, v64, s[60:61] offset:2048
	global_load_dword v80, v64, s[62:63]
	global_load_dword v81, v64, s[14:15] offset:2048
	global_load_dword v82, v64, s[14:15]
	global_load_dword v83, v64, s[20:21]
	global_load_dword v84, v64, s[60:61]
	global_load_ushort v85, v67, s[6:7] offset:2048
	global_load_ushort v86, v67, s[4:5] offset:1024
	global_load_ushort v87, v67, s[4:5]
	global_load_dword v88, v[76:77], off offset:2048
	global_load_dword v89, v[74:75], off offset:2048
	s_nop 0
	global_load_dword v74, v[74:75], off
	s_nop 0
	global_load_dword v75, v[76:77], off
	s_nop 0
	global_load_dword v76, v[68:69], off
	global_load_dword v77, v[68:69], off offset:2048
	global_load_dword v90, v[72:73], off
	s_nop 0
	global_load_dword v72, v[72:73], off offset:2048
	s_nop 0
	global_load_dword v73, v[70:71], off
	global_load_dword v91, v[70:71], off offset:2048
	global_load_ushort v92, v67, s[6:7] offset:1024
	global_load_ushort v93, v67, s[6:7]
	s_nop 0
	global_load_ushort v67, v67, s[4:5] offset:2048
	v_lshl_add_u64 v[68:69], s[20:21], 0, v[64:65]
	v_add_co_u32_e32 v70, vcc, s1, v68
	v_readlane_b32 s78, v255, 11
	s_nop 0
	v_addc_co_u32_e32 v71, vcc, 0, v69, vcc
	v_add_co_u32_e32 v68, vcc, s23, v68
	v_readlane_b32 s79, v255, 12
	s_nop 0
	v_addc_co_u32_e32 v69, vcc, 0, v69, vcc
	global_load_dword v94, v[68:69], off
	global_load_dword v95, v[70:71], off
	s_nop 0
	global_load_dword v64, v64, s[20:21] offset:2048
	s_nop 0
	global_load_dword v68, v[68:69], off offset:2048
	s_nop 0
	global_load_dword v69, v[70:71], off offset:2048
	v_lshl_add_u32 v70, v128, 2, 0
	v_readlane_b32 s80, v255, 13
	v_readlane_b32 s81, v255, 14
	v_readlane_b32 s82, v255, 15
	v_readlane_b32 s83, v255, 16
	s_mov_b64 s[38:39], s[70:71]
	s_mov_b64 s[40:41], s[72:73]
	s_mov_b64 s[42:43], s[74:75]
	s_waitcnt vmcnt(20)
	v_lshlrev_b32_e32 v71, 16, v85
	s_waitcnt vmcnt(19)
	v_lshlrev_b32_e32 v85, 16, v86
	s_waitcnt vmcnt(18)
	v_lshlrev_b32_e32 v86, 16, v87
	v_fma_f32 v81, v79, v81, v78
	s_waitcnt vmcnt(12)
	v_fmac_f32_e32 v81, v77, v89
	s_waitcnt vmcnt(10)
	v_fmac_f32_e32 v81, v72, v88
	v_fma_f32 v82, v84, v82, v80
	v_fmac_f32_e32 v82, v76, v74
	v_fmac_f32_e32 v82, v90, v75
	s_waitcnt vmcnt(8)
	v_fmac_f32_e32 v81, v91, v85
	v_fmac_f32_e32 v80, v84, v83
	v_fmac_f32_e32 v82, v73, v86
	v_mul_f32_e32 v75, 0xbfb8aa3b, v81
	s_waitcnt vmcnt(7)
	v_lshlrev_b32_e32 v85, 16, v92
	v_mul_f32_e32 v74, 0xbfb8aa3b, v82
	s_waitcnt vmcnt(4)
	v_fmac_f32_e32 v80, v76, v94
	v_exp_f32_e32 v75, v75
	s_waitcnt vmcnt(2)
	v_fmac_f32_e32 v78, v79, v64
	s_waitcnt vmcnt(1)
	v_fmac_f32_e32 v78, v77, v68
	s_waitcnt vmcnt(0)
	v_fmac_f32_e32 v78, v72, v69
	v_lshlrev_b32_e32 v86, 16, v93
	v_fmac_f32_e32 v80, v90, v95
	v_fmac_f32_e32 v78, v91, v85
	v_exp_f32_e32 v74, v74
	v_fmac_f32_e32 v80, v73, v86
	v_mul_f32_e32 v68, 0xbfb8aa3b, v78
	v_mul_f32_e32 v64, 0xbfb8aa3b, v80
	v_exp_f32_e32 v68, v68
	v_exp_f32_e32 v64, v64
	v_add_f32_e32 v75, 1.0, v75
	v_add_f32_e32 v74, 1.0, v74
	v_rcp_f32_e32 v75, v75
	v_rcp_f32_e32 v74, v74
	v_add_f32_e32 v68, 1.0, v68
	v_add_f32_e32 v64, 1.0, v64
	v_rcp_f32_e32 v68, v68
	v_rcp_f32_e32 v64, v64
	v_mul_f32_e32 v75, v81, v75
	v_lshlrev_b32_e32 v67, 16, v67
	v_mul_f32_e32 v74, v82, v74
	v_mul_f32_e32 v69, 0x3db504f3, v75
	ds_write2st64_b32 v70, v74, v69 offset1:2
	ds_write2st64_b32 v70, v67, v100 offset0:4 offset1:6
	v_mul_f32_e32 v67, v78, v68
	v_mul_f32_e32 v64, v80, v64
	v_mul_f32_e32 v67, 0x3db504f3, v67
	ds_write2st64_b32 v70, v64, v67 offset0:8 offset1:10
	ds_write2st64_b32 v70, v71, v96 offset0:12 offset1:14
.LBB0_604:
	s_or_b64 exec, exec, s[50:51]
	v_lshlrev_b32_e32 v64, 2, v66
	v_lshl_add_u64 v[66:67], s[26:27], 0, v[64:65]
	v_lshlrev_b32_e32 v64, 2, v112
	v_lshl_add_u64 v[66:67], v[66:67], 0, v[64:65]
	v_mbcnt_lo_u32_b32 v65, -1, 0
	s_mov_b64 s[4:5], 0x561c080
	v_mbcnt_hi_u32_b32 v119, -1, v65
	s_waitcnt vmcnt(46)
	v_lshl_add_u64 v[98:99], v[66:67], 0, s[4:5]
	v_and_b32_e32 v66, 64, v119
	v_xor_b32_e32 v65, 1, v119
	v_add_u32_e32 v120, 64, v66
	v_cmp_lt_i32_e32 vcc, v65, v120
	s_waitcnt lgkmcnt(0)
	s_barrier
	v_add_u32_e32 v118, 0, v64
	v_cndmask_b32_e32 v65, v119, v65, vcc
	v_lshlrev_b32_e32 v112, 2, v65
	v_xor_b32_e32 v65, 2, v119
	v_cmp_lt_i32_e32 vcc, v65, v120
	s_mov_b32 s1, 0xbfb8aa3b
	v_lshl_add_u32 v111, v111, 2, 0
	v_cndmask_b32_e32 v65, v119, v65, vcc
	v_lshlrev_b32_e32 v116, 2, v65
	ds_read_b128 v[72:75], v118
	ds_read_b128 v[76:79], v118 offset:64
	ds_read_b128 v[64:67], v118 offset:512
	s_waitcnt vmcnt(34)
	ds_read_b128 v[80:83], v118 offset:128
	s_waitcnt vmcnt(33)
	ds_read_b128 v[84:87], v118 offset:192
	ds_read_b128 v[88:91], v118 offset:1536
	ds_read_b128 v[68:71], v118 offset:576
	s_waitcnt lgkmcnt(4)
	v_mul_f32_e32 v92, v73, v65
	v_mul_f32_e32 v93, v75, v67
	v_fmac_f32_e32 v92, v72, v64
	v_fmac_f32_e32 v93, v74, v66
	s_waitcnt lgkmcnt(1)
	v_mul_f32_e32 v89, v73, v89
	s_waitcnt vmcnt(23)
	v_mul_f32_e32 v73, v61, v73
	v_add_f32_e32 v92, v92, v93
	v_fmac_f32_e32 v89, v72, v88
	v_fmac_f32_e32 v73, v60, v72
	v_mul_f32_e32 v72, v63, v75
	v_add_f32_e32 v102, 0, v92
	ds_read_b128 v[92:95], v118 offset:1600
	v_mul_f32_e32 v88, v75, v91
	v_fmac_f32_e32 v72, v62, v74
	v_fmac_f32_e32 v88, v74, v90
	v_add_f32_e32 v72, v73, v72
	v_add_f32_e32 v88, v89, v88
	v_add_f32_e32 v89, 0, v72
	s_waitcnt lgkmcnt(1)
	v_mul_f32_e32 v72, v77, v69
	v_mul_f32_e32 v73, v79, v71
	v_fmac_f32_e32 v72, v76, v68
	v_fmac_f32_e32 v73, v78, v70
	v_add_f32_e32 v72, v72, v73
	v_add_f32_e32 v102, v102, v72
	s_waitcnt lgkmcnt(0)
	v_mul_f32_e32 v72, v77, v93
	v_mul_f32_e32 v73, v79, v95
	v_fmac_f32_e32 v72, v76, v92
	v_fmac_f32_e32 v73, v78, v94
	v_mul_f32_e32 v77, v57, v77
	v_add_f32_e32 v88, 0, v88
	v_add_f32_e32 v72, v72, v73
	v_fmac_f32_e32 v77, v56, v76
	v_mul_f32_e32 v76, v59, v79
	v_add_f32_e32 v103, v88, v72
	v_fmac_f32_e32 v76, v58, v78
	ds_read_b128 v[72:75], v118 offset:640
	v_add_f32_e32 v76, v77, v76
	v_add_f32_e32 v121, v89, v76
	ds_read_b128 v[88:91], v118 offset:1664
	ds_read_b128 v[76:79], v118 offset:704
	s_waitcnt lgkmcnt(2)
	v_mul_f32_e32 v92, v81, v73
	v_mul_f32_e32 v93, v83, v75
	v_fmac_f32_e32 v92, v80, v72
	v_fmac_f32_e32 v93, v82, v74
	s_waitcnt lgkmcnt(1)
	v_mul_f32_e32 v89, v81, v89
	v_mul_f32_e32 v81, v53, v81
	v_add_f32_e32 v92, v92, v93
	v_fmac_f32_e32 v89, v80, v88
	v_mul_f32_e32 v88, v83, v91
	v_fmac_f32_e32 v81, v52, v80
	v_mul_f32_e32 v80, v55, v83
	v_add_f32_e32 v102, v102, v92
	ds_read_b128 v[92:95], v118 offset:1728
	v_fmac_f32_e32 v88, v82, v90
	v_fmac_f32_e32 v80, v54, v82
	v_add_f32_e32 v88, v89, v88
	v_add_f32_e32 v80, v81, v80
	v_add_f32_e32 v88, v103, v88
	v_add_f32_e32 v103, v121, v80
	s_waitcnt lgkmcnt(1)
	v_mul_f32_e32 v80, v85, v77
	v_mul_f32_e32 v81, v87, v79
	v_fmac_f32_e32 v80, v84, v76
	v_fmac_f32_e32 v81, v86, v78
	v_add_f32_e32 v80, v80, v81
	v_add_f32_e32 v102, v102, v80
	s_waitcnt lgkmcnt(0)
	v_mul_f32_e32 v80, v85, v93
	v_mul_f32_e32 v81, v87, v95
	v_fmac_f32_e32 v80, v84, v92
	v_fmac_f32_e32 v81, v86, v94
	v_add_f32_e32 v80, v80, v81
	v_add_f32_e32 v121, v88, v80
	v_mul_f32_e32 v80, v49, v85
	v_mul_f32_e32 v81, v51, v87
	v_fmac_f32_e32 v80, v48, v84
	v_fmac_f32_e32 v81, v50, v86
	v_add_f32_e32 v84, v80, v81
	ds_read_b128 v[88:91], v118 offset:256
	ds_read_b128 v[80:83], v118 offset:768
	v_add_f32_e32 v103, v103, v84
	ds_read_b128 v[92:95], v118 offset:1792
	ds_read_b128 v[122:125], v118 offset:320
	ds_read_b128 v[84:87], v118 offset:832
	ds_read_b128 v[130:133], v118 offset:1856
	s_waitcnt lgkmcnt(4)
	v_mul_f32_e32 v126, v89, v81
	s_waitcnt lgkmcnt(3)
	v_mul_f32_e32 v93, v89, v93
	s_waitcnt vmcnt(19)
	v_mul_f32_e32 v89, v45, v89
	v_fmac_f32_e32 v126, v88, v80
	v_fmac_f32_e32 v93, v88, v92
	v_fmac_f32_e32 v89, v44, v88
	v_mul_f32_e32 v88, v47, v91
	v_mul_f32_e32 v92, v91, v95
	v_fmac_f32_e32 v88, v46, v90
	v_mul_f32_e32 v127, v91, v83
	v_fmac_f32_e32 v92, v90, v94
	v_add_f32_e32 v88, v89, v88
	v_fmac_f32_e32 v127, v90, v82
	v_add_f32_e32 v92, v93, v92
	v_add_f32_e32 v93, v103, v88
	s_waitcnt lgkmcnt(1)
	v_mul_f32_e32 v88, v123, v85
	v_mul_f32_e32 v89, v125, v87
	v_add_f32_e32 v126, v126, v127
	v_fmac_f32_e32 v88, v122, v84
	v_fmac_f32_e32 v89, v124, v86
	v_add_f32_e32 v102, v102, v126
	v_add_f32_e32 v88, v88, v89
	v_add_f32_e32 v102, v102, v88
	s_waitcnt lgkmcnt(0)
	v_mul_f32_e32 v88, v123, v131
	v_mul_f32_e32 v89, v125, v133
	v_fmac_f32_e32 v88, v122, v130
	v_fmac_f32_e32 v89, v124, v132
	v_add_f32_e32 v92, v121, v92
	v_add_f32_e32 v88, v88, v89
	v_add_f32_e32 v103, v92, v88
	v_mul_f32_e32 v88, v41, v123
	v_mul_f32_e32 v89, v43, v125
	v_fmac_f32_e32 v88, v40, v122
	v_fmac_f32_e32 v89, v42, v124
	v_add_f32_e32 v92, v88, v89
	ds_read_b128 v[122:125], v118 offset:384
	ds_read_b128 v[88:91], v118 offset:896
	v_add_f32_e32 v121, v93, v92
	ds_read_b128 v[130:133], v118 offset:1920
	ds_read_b128 v[134:137], v118 offset:448
	ds_read_b128 v[92:95], v118 offset:960
	ds_read_b128 v[138:141], v118 offset:1984
	s_waitcnt lgkmcnt(4)
	v_mul_f32_e32 v126, v123, v89
	v_mul_f32_e32 v127, v125, v91
	v_fmac_f32_e32 v126, v122, v88
	v_fmac_f32_e32 v127, v124, v90
	v_add_f32_e32 v126, v126, v127
	v_add_f32_e32 v102, v102, v126
	s_waitcnt lgkmcnt(3)
	v_mul_f32_e32 v126, v123, v131
	v_mul_f32_e32 v123, v37, v123
	v_fmac_f32_e32 v126, v122, v130
	v_fmac_f32_e32 v123, v36, v122
	v_mul_f32_e32 v122, v39, v125
	v_fmac_f32_e32 v122, v38, v124
	v_add_f32_e32 v122, v123, v122
	v_add_f32_e32 v121, v121, v122
	s_waitcnt lgkmcnt(1)
	v_mul_f32_e32 v122, v135, v93
	v_mul_f32_e32 v123, v137, v95
	v_fmac_f32_e32 v122, v134, v92
	v_fmac_f32_e32 v123, v136, v94
	v_mul_f32_e32 v127, v125, v133
	v_add_f32_e32 v122, v122, v123
	v_fmac_f32_e32 v127, v124, v132
	v_add_f32_e32 v122, v102, v122
	s_waitcnt lgkmcnt(0)
	v_mul_f32_e32 v102, v135, v139
	v_mul_f32_e32 v123, v137, v141
	v_add_f32_e32 v126, v126, v127
	v_fmac_f32_e32 v102, v134, v138
	v_fmac_f32_e32 v123, v136, v140
	v_add_f32_e32 v103, v103, v126
	v_add_f32_e32 v102, v102, v123
	v_add_f32_e32 v123, v103, v102
	ds_bpermute_b32 v124, v112, v122
	ds_bpermute_b32 v127, v112, v123
	v_mul_f32_e32 v102, v33, v135
	v_mul_f32_e32 v103, v35, v137
	v_fmac_f32_e32 v102, v32, v134
	v_fmac_f32_e32 v103, v34, v136
	v_add_f32_e32 v102, v102, v103
	v_add_f32_e32 v121, v121, v102
	s_waitcnt lgkmcnt(1)
	v_add_f32_e32 v125, v122, v124
	s_waitcnt vmcnt(8)
	v_mul_f32_e64 v124, |v105|, s1
	ds_bpermute_b32 v130, v112, v121
	s_waitcnt lgkmcnt(1)
	v_add_f32_e32 v122, v123, v127
	v_exp_f32_e32 v127, v124
	s_mov_b32 s1, 0x3f2aaaab
	v_max_f32_e32 v105, v105, v105
	s_waitcnt lgkmcnt(0)
	v_add_f32_e32 v121, v121, v130
	v_add_f32_e32 v132, 1.0, v127
	v_add_f32_e32 v130, -1.0, v132
	v_sub_f32_e32 v131, v130, v132
	v_add_f32_e32 v131, 1.0, v131
	v_sub_f32_e32 v130, v127, v130
	v_add_f32_e32 v133, v130, v131
	v_frexp_mant_f32_e32 v134, v132
	v_cvt_f64_f32_e32 v[130:131], v132
	v_frexp_exp_i32_f64_e32 v130, v[130:131]
	v_cmp_gt_f32_e32 vcc, s1, v134
	s_mov_b32 s1, 0x3f317218
	v_min_f32_e32 v105, 0, v105
	v_subbrev_co_u32_e32 v138, vcc, 0, v130, vcc
	v_sub_u32_e32 v130, 0, v138
	v_ldexp_f32 v131, v132, v130
	v_add_f32_e32 v132, -1.0, v131
	v_add_f32_e32 v134, 1.0, v131
	v_ldexp_f32 v130, v133, v130
	v_add_f32_e32 v133, 1.0, v132
	v_add_f32_e32 v135, -1.0, v134
	v_sub_f32_e32 v133, v131, v133
	v_sub_f32_e32 v131, v131, v135
	v_add_f32_e32 v133, v130, v133
	v_add_f32_e32 v130, v130, v131
	v_add_f32_e32 v139, v134, v130
	v_rcp_f32_e32 v141, v139
	v_sub_f32_e32 v131, v139, v134
	v_sub_f32_e32 v140, v130, v131
	v_add_f32_e32 v131, v132, v133
	v_mul_f32_e32 v143, v131, v141
	v_sub_f32_e32 v130, v131, v132
	v_mul_f32_e32 v132, v139, v143
	v_fma_f32 v134, v143, v139, -v132
	v_fmac_f32_e32 v134, v143, v140
	v_sub_f32_e32 v142, v133, v130
	v_add_f32_e32 v130, v132, v134
	v_sub_f32_e32 v133, v131, v130
	v_pk_add_f32 v[136:137], v[130:131], v[132:133] neg_lo:[0,1] neg_hi:[0,1]
	v_mov_b32_e32 v135, v130
	v_pk_add_f32 v[130:131], v[136:137], v[134:135] neg_lo:[0,1] neg_hi:[0,1]
	v_lshl_add_u64 v[102:103], v[98:99], 0, s[52:53]
	v_add_f32_e32 v131, v142, v131
	v_add_f32_e32 v130, v130, v131
	v_add_f32_e32 v131, v133, v130
	v_mul_f32_e32 v142, v141, v131
	v_mul_f32_e32 v132, v139, v142
	v_fma_f32 v134, v142, v139, -v132
	v_fmac_f32_e32 v134, v142, v140
	v_sub_f32_e32 v133, v133, v131
	v_add_f32_e32 v139, v130, v133
	v_add_f32_e32 v130, v132, v134
	v_sub_f32_e32 v133, v131, v130
	v_pk_add_f32 v[136:137], v[130:131], v[132:133] neg_lo:[0,1] neg_hi:[0,1]
	v_mov_b32_e32 v135, v130
	v_pk_add_f32 v[130:131], v[136:137], v[134:135] neg_lo:[0,1] neg_hi:[0,1]
	v_cvt_f32_i32_e32 v132, v138
	v_add_f32_e32 v131, v139, v131
	v_add_f32_e32 v130, v130, v131
	v_add_f32_e32 v130, v133, v130
	v_add_f32_e32 v133, v143, v142
	v_sub_f32_e32 v131, v133, v143
	v_mul_f32_e32 v130, v141, v130
	v_sub_f32_e32 v131, v142, v131
	v_add_f32_e32 v130, v131, v130
	v_add_f32_e32 v134, v133, v130
	v_mul_f32_e32 v136, v134, v134
	v_mov_b32_e32 v131, 0x3ecc95a3
	v_sub_f32_e32 v133, v134, v133
	v_fmac_f32_e32 v131, 0x3e9b6dac, v136
	v_sub_f32_e32 v130, v130, v133
	v_fmaak_f32 v131, v136, v131, 0x3f2aaada
	v_ldexp_f32 v137, v130, 1
	v_mul_f32_e32 v133, v134, v136
	v_mov_b32_e32 v130, 0x3f317218
	v_pk_mul_f32 v[130:131], v[132:133], v[130:131]
	v_ldexp_f32 v135, v134, 1
	v_fma_f32 v133, v132, s1, -v130
	v_fmamk_f32 v134, v132, 0xb102e308, v133
	v_pk_add_f32 v[132:133], v[130:131], v[134:135]
	v_mov_b32_e32 v136, v130
	v_sub_f32_e32 v135, v133, v135
	v_sub_f32_e32 v135, v131, v135
	v_add_f32_e32 v137, v137, v135
	v_pk_add_f32 v[130:131], v[132:133], v[130:131] neg_lo:[0,1] neg_hi:[0,1]
	v_pk_add_f32 v[138:139], v[132:133], v[136:137]
	v_mov_b32_e32 v135, v132
	v_mov_b32_e32 v131, v139
	v_pk_add_f32 v[140:141], v[134:135], v[130:131] neg_lo:[0,1] neg_hi:[0,1]
	v_pk_add_f32 v[130:131], v[134:135], v[130:131]
	v_mov_b32_e32 v144, v133
	v_pk_add_f32 v[134:135], v[130:131], v[132:133] op_sel:[1,0] op_sel_hi:[0,1] neg_lo:[0,1] neg_hi:[0,1]
	v_pk_add_f32 v[142:143], v[138:139], v[134:135] op_sel_hi:[1,0] neg_lo:[0,1] neg_hi:[0,1]
	v_mov_b32_e32 v138, v139
	v_mov_b32_e32 v139, v131
	v_mov_b32_e32 v145, v134
	v_pk_add_f32 v[134:135], v[138:139], v[144:145] neg_lo:[0,1] neg_hi:[0,1]
	v_mov_b32_e32 v136, v137
	v_mov_b32_e32 v137, v132
	v_pk_add_f32 v[132:133], v[136:137], v[134:135] neg_lo:[0,1] neg_hi:[0,1]
	v_mov_b32_e32 v142, v140
	v_pk_add_f32 v[134:135], v[142:143], v[132:133]
	v_mov_b32_e32 v141, v131
	v_pk_add_f32 v[136:137], v[134:135], v[134:135] op_sel:[0,1] op_sel_hi:[1,0]
	s_mov_b32 s1, 0x7f800000
	v_pk_add_f32 v[130:131], v[130:131], v[136:137] op_sel:[1,0] op_sel_hi:[0,1]
	v_mov_b32_e32 v135, v130
	v_pk_add_f32 v[138:139], v[134:135], v[140:141] neg_lo:[0,1] neg_hi:[0,1]
	v_mov_b32_e32 v133, v136
	v_sub_f32_e32 v131, v134, v138
	v_pk_add_f32 v[132:133], v[132:133], v[138:139] neg_lo:[0,1] neg_hi:[0,1]
	v_sub_f32_e32 v131, v140, v131
	v_add_f32_e32 v131, v132, v131
	v_add_f32_e32 v131, v131, v133
	v_add_f32_e32 v130, v130, v131
	v_mov_b32_e32 v131, 0x7f800000
	v_cmp_neq_f32_e32 vcc, s1, v127
	s_mov_b32 s1, 0x33800000
	ds_bpermute_b32 v126, v116, v125
	v_cndmask_b32_e32 v130, v131, v130, vcc
	v_mov_b32_e32 v131, 0x7fc00000
	v_cmp_ngt_f32_e32 vcc, -1.0, v127
	ds_bpermute_b32 v123, v116, v122
	ds_bpermute_b32 v124, v116, v121
	v_cndmask_b32_e32 v130, v131, v130, vcc
	v_mov_b32_e32 v131, 0xff800000
	v_cmp_neq_f32_e32 vcc, -1.0, v127
	s_nop 1
	v_cndmask_b32_e32 v130, v131, v130, vcc
	v_cmp_lt_f32_e64 vcc, |v127|, s1
	s_nop 1
	v_cndmask_b32_e32 v127, v130, v127, vcc
	v_sub_f32_e32 v105, v105, v127
	s_waitcnt vmcnt(7)
	v_add_f32_e32 v104, v104, v105
	v_max_f32_e32 v105, v101, v101
	v_max_f32_e32 v130, v104, v105
	v_sub_f32_e32 v101, v101, v130
	v_mul_f32_e32 v101, 0x3fb8aa3b, v101
	ds_read_b32 v127, v111 offset:1024
	v_exp_f32_e32 v101, v101
	v_sub_f32_e32 v104, v104, v130
	v_mul_f32_e32 v104, 0x3fb8aa3b, v104
	v_exp_f32_e32 v104, v104
	s_waitcnt lgkmcnt(0)
	v_mul_f32_e32 v132, v101, v127
	v_pk_mul_f32 v[64:65], v[64:65], v[132:133] op_sel_hi:[1,0]
	v_pk_mul_f32 v[66:67], v[66:67], v[132:133] op_sel_hi:[1,0]
	v_pk_fma_f32 v[60:61], v[60:61], v[104:105], v[64:65] op_sel_hi:[1,0,1]
	v_pk_fma_f32 v[62:63], v[62:63], v[104:105], v[66:67] op_sel_hi:[1,0,1]
	global_store_dwordx4 v[102:103], v[60:63], off
	s_nop 1
	v_pk_mul_f32 v[60:61], v[68:69], v[132:133] op_sel_hi:[1,0]
	v_pk_mul_f32 v[62:63], v[70:71], v[132:133] op_sel_hi:[1,0]
	v_pk_fma_f32 v[56:57], v[56:57], v[104:105], v[60:61] op_sel_hi:[1,0,1]
	v_pk_fma_f32 v[58:59], v[58:59], v[104:105], v[62:63] op_sel_hi:[1,0,1]
	global_store_dwordx4 v[102:103], v[56:59], off offset:64
	s_nop 1
	v_pk_mul_f32 v[56:57], v[72:73], v[132:133] op_sel_hi:[1,0]
	v_pk_mul_f32 v[58:59], v[74:75], v[132:133] op_sel_hi:[1,0]
	v_pk_fma_f32 v[52:53], v[52:53], v[104:105], v[56:57] op_sel_hi:[1,0,1]
	v_pk_fma_f32 v[54:55], v[54:55], v[104:105], v[58:59] op_sel_hi:[1,0,1]
	global_store_dwordx4 v[102:103], v[52:55], off offset:128
	s_nop 1
	v_pk_mul_f32 v[52:53], v[76:77], v[132:133] op_sel_hi:[1,0]
	v_pk_mul_f32 v[54:55], v[78:79], v[132:133] op_sel_hi:[1,0]
	v_pk_fma_f32 v[48:49], v[48:49], v[104:105], v[52:53] op_sel_hi:[1,0,1]
	v_pk_fma_f32 v[50:51], v[50:51], v[104:105], v[54:55] op_sel_hi:[1,0,1]
	global_store_dwordx4 v[102:103], v[48:51], off offset:192
	s_nop 1
	v_pk_mul_f32 v[48:49], v[80:81], v[132:133] op_sel_hi:[1,0]
	v_pk_mul_f32 v[50:51], v[82:83], v[132:133] op_sel_hi:[1,0]
	v_pk_fma_f32 v[44:45], v[44:45], v[104:105], v[48:49] op_sel_hi:[1,0,1]
	v_pk_fma_f32 v[46:47], v[46:47], v[104:105], v[50:51] op_sel_hi:[1,0,1]
	global_store_dwordx4 v[102:103], v[44:47], off offset:256
	s_nop 1
	v_pk_mul_f32 v[44:45], v[84:85], v[132:133] op_sel_hi:[1,0]
	v_pk_mul_f32 v[46:47], v[86:87], v[132:133] op_sel_hi:[1,0]
	v_pk_fma_f32 v[40:41], v[40:41], v[104:105], v[44:45] op_sel_hi:[1,0,1]
	v_pk_fma_f32 v[42:43], v[42:43], v[104:105], v[46:47] op_sel_hi:[1,0,1]
	global_store_dwordx4 v[102:103], v[40:43], off offset:320
	s_nop 1
	v_pk_mul_f32 v[40:41], v[88:89], v[132:133] op_sel_hi:[1,0]
	v_pk_mul_f32 v[42:43], v[90:91], v[132:133] op_sel_hi:[1,0]
	v_pk_fma_f32 v[36:37], v[36:37], v[104:105], v[40:41] op_sel_hi:[1,0,1]
	v_pk_fma_f32 v[38:39], v[38:39], v[104:105], v[42:43] op_sel_hi:[1,0,1]
	global_store_dwordx4 v[102:103], v[36:39], off offset:384
	s_nop 1
	v_pk_mul_f32 v[36:37], v[92:93], v[132:133] op_sel_hi:[1,0]
	v_pk_mul_f32 v[38:39], v[94:95], v[132:133] op_sel_hi:[1,0]
	v_pk_fma_f32 v[32:33], v[32:33], v[104:105], v[36:37] op_sel_hi:[1,0,1]
	v_pk_fma_f32 v[34:35], v[34:35], v[104:105], v[38:39] op_sel_hi:[1,0,1]
	global_store_dwordx4 v[102:103], v[32:35], off offset:448
	s_and_saveexec_b64 s[4:5], s[2:3]
	s_cbranch_execz .LBB0_606
	v_lshl_add_u32 v32, v128, 2, 0
	ds_read_b32 v105, v32 offset:512
	s_add_u32 s6, s26, s48
	s_addc_u32 s7, s27, s49
	v_lshlrev_b32_e32 v32, 2, v128
	v_mov_b32_e32 v33, 0
	v_lshl_add_u64 v[32:33], s[6:7], 0, v[32:33]
	s_waitcnt lgkmcnt(0)
	v_pk_mul_f32 v[34:35], v[100:101], v[104:105]
	v_add_co_u32_e32 v32, vcc, 0x761c000, v32
	v_add_f32_e32 v34, v34, v35
	s_nop 0
	v_addc_co_u32_e32 v33, vcc, 0, v33, vcc
	global_store_dword v[32:33], v34, off offset:128

.LBB0_610:
	s_or_b64 exec, exec, s[14:15]
	ds_read_b128 v[40:43], v118 offset:2048
	ds_read_b128 v[44:47], v118 offset:2112
	s_waitcnt lgkmcnt(2)
	ds_read_b128 v[32:35], v118 offset:2560
	ds_read_b128 v[48:51], v118 offset:2176
	ds_read_b128 v[52:55], v118 offset:2240
	ds_read_b128 v[56:59], v118 offset:3584
	ds_read_b128 v[36:39], v118 offset:2624
	s_waitcnt lgkmcnt(4)
	v_mul_f32_e32 v60, v41, v33
	v_mul_f32_e32 v61, v43, v35
	v_fmac_f32_e32 v60, v40, v32
	v_fmac_f32_e32 v61, v42, v34
	s_waitcnt lgkmcnt(1)
	v_mul_f32_e32 v57, v41, v57
	v_mul_f32_e32 v41, v29, v41
	v_add_f32_e32 v60, v60, v61
	v_fmac_f32_e32 v57, v40, v56
	v_fmac_f32_e32 v41, v28, v40
	v_mul_f32_e32 v40, v31, v43
	v_add_f32_e32 v64, 0, v60
	ds_read_b128 v[60:63], v118 offset:3648
	v_mul_f32_e32 v56, v43, v59
	v_fmac_f32_e32 v40, v30, v42
	v_fmac_f32_e32 v56, v42, v58
	v_add_f32_e32 v40, v41, v40
	v_add_f32_e32 v56, v57, v56
	v_add_f32_e32 v57, 0, v40
	s_waitcnt lgkmcnt(1)
	v_mul_f32_e32 v40, v45, v37
	v_mul_f32_e32 v41, v47, v39
	v_fmac_f32_e32 v40, v44, v36
	v_fmac_f32_e32 v41, v46, v38
	v_add_f32_e32 v40, v40, v41
	v_add_f32_e32 v64, v64, v40
	s_waitcnt lgkmcnt(0)
	v_mul_f32_e32 v40, v45, v61
	v_mul_f32_e32 v41, v47, v63
	v_fmac_f32_e32 v40, v44, v60
	v_fmac_f32_e32 v41, v46, v62
	v_mul_f32_e32 v45, v25, v45
	v_add_f32_e32 v56, 0, v56
	v_add_f32_e32 v40, v40, v41
	v_fmac_f32_e32 v45, v24, v44
	v_mul_f32_e32 v44, v27, v47
	v_add_f32_e32 v65, v56, v40
	v_fmac_f32_e32 v44, v26, v46
	ds_read_b128 v[40:43], v118 offset:2688
	v_add_f32_e32 v44, v45, v44
	v_add_f32_e32 v66, v57, v44
	ds_read_b128 v[56:59], v118 offset:3712
	ds_read_b128 v[44:47], v118 offset:2752
	s_waitcnt lgkmcnt(2)
	v_mul_f32_e32 v60, v49, v41
	v_mul_f32_e32 v61, v51, v43
	v_fmac_f32_e32 v60, v48, v40
	v_fmac_f32_e32 v61, v50, v42
	s_waitcnt lgkmcnt(1)
	v_mul_f32_e32 v57, v49, v57
	v_mul_f32_e32 v49, v21, v49
	v_add_f32_e32 v60, v60, v61
	v_fmac_f32_e32 v57, v48, v56
	v_mul_f32_e32 v56, v51, v59
	v_fmac_f32_e32 v49, v20, v48
	v_mul_f32_e32 v48, v23, v51
	v_add_f32_e32 v64, v64, v60
	ds_read_b128 v[60:63], v118 offset:3776
	v_fmac_f32_e32 v56, v50, v58
	v_fmac_f32_e32 v48, v22, v50
	v_add_f32_e32 v56, v57, v56
	v_add_f32_e32 v48, v49, v48
	v_add_f32_e32 v56, v65, v56
	v_add_f32_e32 v65, v66, v48
	s_waitcnt lgkmcnt(1)
	v_mul_f32_e32 v48, v53, v45
	v_mul_f32_e32 v49, v55, v47
	v_fmac_f32_e32 v48, v52, v44
	v_fmac_f32_e32 v49, v54, v46
	v_add_f32_e32 v48, v48, v49
	v_add_f32_e32 v74, v64, v48
	s_waitcnt lgkmcnt(0)
	v_mul_f32_e32 v48, v53, v61
	v_mul_f32_e32 v49, v55, v63
	v_fmac_f32_e32 v48, v52, v60
	v_fmac_f32_e32 v49, v54, v62
	v_add_f32_e32 v48, v48, v49
	v_add_f32_e32 v78, v56, v48
	v_mul_f32_e32 v48, v17, v53
	v_mul_f32_e32 v49, v19, v55
	v_fmac_f32_e32 v48, v16, v52
	v_fmac_f32_e32 v49, v18, v54
	v_add_f32_e32 v52, v48, v49
	ds_read_b128 v[56:59], v118 offset:2304
	ds_read_b128 v[48:51], v118 offset:2816
	v_add_f32_e32 v79, v65, v52
	ds_read_b128 v[60:63], v118 offset:3840
	ds_read_b128 v[64:67], v118 offset:2368
	ds_read_b128 v[52:55], v118 offset:2880
	s_waitcnt lgkmcnt(3)
	v_mul_f32_e32 v75, v57, v49
	v_mul_f32_e32 v76, v59, v51
	v_fmac_f32_e32 v75, v56, v48
	v_fmac_f32_e32 v76, v58, v50
	s_waitcnt lgkmcnt(2)
	v_mul_f32_e32 v61, v57, v61
	v_mul_f32_e32 v57, v13, v57
	v_add_f32_e32 v75, v75, v76
	v_fmac_f32_e32 v61, v56, v60
	v_fmac_f32_e32 v57, v12, v56
	v_mul_f32_e32 v56, v15, v59
	v_add_f32_e32 v80, v74, v75
	ds_read_b128 v[74:77], v118 offset:3904
	v_mul_f32_e32 v60, v59, v63
	v_fmac_f32_e32 v56, v14, v58
	v_fmac_f32_e32 v60, v58, v62
	v_add_f32_e32 v56, v57, v56
	v_add_f32_e32 v60, v61, v60
	v_add_f32_e32 v61, v79, v56
	s_waitcnt lgkmcnt(1)
	v_mul_f32_e32 v56, v65, v53
	v_mul_f32_e32 v57, v67, v55
	v_fmac_f32_e32 v56, v64, v52
	v_fmac_f32_e32 v57, v66, v54
	v_add_f32_e32 v56, v56, v57
	v_add_f32_e32 v82, v80, v56
	s_waitcnt lgkmcnt(0)
	v_mul_f32_e32 v56, v65, v75
	v_mul_f32_e32 v57, v67, v77
	v_fmac_f32_e32 v56, v64, v74
	v_fmac_f32_e32 v57, v66, v76
	v_add_f32_e32 v60, v78, v60
	v_add_f32_e32 v56, v56, v57
	v_add_f32_e32 v86, v60, v56
	v_mul_f32_e32 v56, v9, v65
	v_mul_f32_e32 v57, v11, v67
	v_fmac_f32_e32 v56, v8, v64
	v_fmac_f32_e32 v57, v10, v66
	v_add_f32_e32 v60, v56, v57
	ds_read_b128 v[64:67], v118 offset:2432
	ds_read_b128 v[56:59], v118 offset:2944
	v_add_f32_e32 v87, v61, v60
	ds_read_b128 v[74:77], v118 offset:3968
	ds_read_b128 v[78:81], v118 offset:2496
	ds_read_b128 v[60:63], v118 offset:3008
	s_waitcnt lgkmcnt(3)
	v_mul_f32_e32 v83, v65, v57
	v_mul_f32_e32 v84, v67, v59
	v_fmac_f32_e32 v83, v64, v56
	v_fmac_f32_e32 v84, v66, v58
	v_add_f32_e32 v83, v83, v84
	s_waitcnt lgkmcnt(2)
	v_mul_f32_e32 v75, v65, v75
	v_mul_f32_e32 v65, v5, v65
	v_add_f32_e32 v88, v82, v83
	ds_read_b128 v[82:85], v118 offset:4032
	v_fmac_f32_e32 v75, v64, v74
	v_fmac_f32_e32 v65, v4, v64
	v_mul_f32_e32 v64, v7, v67
	v_mul_f32_e32 v74, v67, v77
	v_fmac_f32_e32 v64, v6, v66
	v_fmac_f32_e32 v74, v66, v76
	v_add_f32_e32 v64, v65, v64
	s_waitcnt lgkmcnt(1)
	v_mul_f32_e32 v65, v79, v61
	v_mul_f32_e32 v66, v81, v63
	v_fmac_f32_e32 v65, v78, v60
	v_fmac_f32_e32 v66, v80, v62
	v_add_f32_e32 v65, v65, v66
	v_add_f32_e32 v66, v88, v65
	s_waitcnt lgkmcnt(0)
	v_mul_f32_e32 v65, v79, v83
	v_mul_f32_e32 v67, v81, v85
	v_add_f32_e32 v74, v75, v74
	v_fmac_f32_e32 v65, v78, v82
	v_fmac_f32_e32 v67, v80, v84
	v_add_f32_e32 v74, v86, v74
	v_add_f32_e32 v65, v65, v67
	v_add_f32_e32 v67, v74, v65
	v_mul_f32_e32 v65, v1, v79
	v_mul_f32_e32 v74, v3, v81
	v_fmac_f32_e32 v65, v0, v78
	v_fmac_f32_e32 v74, v2, v80
	v_add_f32_e32 v65, v65, v74
	ds_bpermute_b32 v74, v112, v66
	v_add_f32_e32 v64, v87, v64
	v_add_f32_e32 v77, v64, v65
	ds_bpermute_b32 v80, v112, v77
	ds_bpermute_b32 v75, v112, v67
	s_waitcnt lgkmcnt(2)
	v_add_f32_e32 v78, v66, v74
	s_waitcnt vmcnt(13)
	v_mul_f32_e64 v66, |v117|, s1
	v_exp_f32_e32 v94, v66
	s_waitcnt lgkmcnt(1)
	v_add_f32_e32 v74, v77, v80
	v_max_f32_e32 v66, v117, v117
	v_min_f32_e32 v95, 0, v66
	v_add_f32_e32 v80, 1.0, v94
	v_add_f32_e32 v66, -1.0, v80
	s_waitcnt lgkmcnt(0)
	v_add_f32_e32 v75, v67, v75
	v_sub_f32_e32 v67, v66, v80
	v_add_f32_e32 v67, 1.0, v67
	v_sub_f32_e32 v66, v94, v66
	v_add_f32_e32 v81, v66, v67
	v_frexp_mant_f32_e32 v82, v80
	s_mov_b32 s1, 0x3f2aaaab
	v_cvt_f64_f32_e32 v[66:67], v80
	v_frexp_exp_i32_f64_e32 v66, v[66:67]
	v_cmp_gt_f32_e32 vcc, s1, v82
	s_mov_b32 s1, 0x3f317218
	v_lshl_add_u64 v[64:65], v[98:99], 0, s[16:17]
	v_subbrev_co_u32_e32 v86, vcc, 0, v66, vcc
	v_sub_u32_e32 v66, 0, v86
	v_ldexp_f32 v67, v80, v66
	v_add_f32_e32 v80, -1.0, v67
	v_add_f32_e32 v82, 1.0, v67
	v_ldexp_f32 v66, v81, v66
	v_add_f32_e32 v81, 1.0, v80
	v_add_f32_e32 v83, -1.0, v82
	v_sub_f32_e32 v81, v67, v81
	v_sub_f32_e32 v67, v67, v83
	v_add_f32_e32 v81, v66, v81
	v_add_f32_e32 v66, v66, v67
	v_add_f32_e32 v87, v82, v66
	v_rcp_f32_e32 v89, v87
	v_sub_f32_e32 v67, v87, v82
	v_sub_f32_e32 v88, v66, v67
	v_add_f32_e32 v67, v80, v81
	v_mul_f32_e32 v91, v67, v89
	v_sub_f32_e32 v66, v67, v80
	v_mul_f32_e32 v80, v87, v91
	v_fma_f32 v82, v91, v87, -v80
	v_fmac_f32_e32 v82, v91, v88
	v_sub_f32_e32 v90, v81, v66
	v_add_f32_e32 v66, v80, v82
	v_sub_f32_e32 v81, v67, v66
	v_pk_add_f32 v[84:85], v[66:67], v[80:81] neg_lo:[0,1] neg_hi:[0,1]
	v_mov_b32_e32 v83, v66
	v_pk_add_f32 v[66:67], v[84:85], v[82:83] neg_lo:[0,1] neg_hi:[0,1]
	ds_bpermute_b32 v79, v116, v78
	v_add_f32_e32 v67, v90, v67
	v_add_f32_e32 v66, v66, v67
	v_add_f32_e32 v67, v81, v66
	v_mul_f32_e32 v90, v89, v67
	v_mul_f32_e32 v80, v87, v90
	v_fma_f32 v82, v90, v87, -v80
	v_fmac_f32_e32 v82, v90, v88
	v_sub_f32_e32 v81, v81, v67
	v_add_f32_e32 v87, v66, v81
	v_add_f32_e32 v66, v80, v82
	v_sub_f32_e32 v81, v67, v66
	v_pk_add_f32 v[84:85], v[66:67], v[80:81] neg_lo:[0,1] neg_hi:[0,1]
	v_mov_b32_e32 v83, v66
	v_pk_add_f32 v[66:67], v[84:85], v[82:83] neg_lo:[0,1] neg_hi:[0,1]
	v_cvt_f32_i32_e32 v80, v86
	v_add_f32_e32 v67, v87, v67
	v_add_f32_e32 v66, v66, v67
	v_add_f32_e32 v66, v81, v66
	v_add_f32_e32 v81, v91, v90
	v_sub_f32_e32 v67, v81, v91
	v_mul_f32_e32 v66, v89, v66
	v_sub_f32_e32 v67, v90, v67
	v_add_f32_e32 v66, v67, v66
	v_add_f32_e32 v82, v81, v66
	v_mul_f32_e32 v84, v82, v82
	v_mov_b32_e32 v67, 0x3ecc95a3
	v_sub_f32_e32 v81, v82, v81
	v_fmac_f32_e32 v67, 0x3e9b6dac, v84
	v_sub_f32_e32 v66, v66, v81
	v_fmaak_f32 v67, v84, v67, 0x3f2aaada
	v_ldexp_f32 v85, v66, 1
	v_mul_f32_e32 v81, v82, v84
	v_mov_b32_e32 v66, 0x3f317218
	v_pk_mul_f32 v[66:67], v[80:81], v[66:67]
	v_ldexp_f32 v83, v82, 1
	v_fma_f32 v81, v80, s1, -v66
	v_fmamk_f32 v82, v80, 0xb102e308, v81
	v_pk_add_f32 v[80:81], v[66:67], v[82:83]
	v_mov_b32_e32 v84, v66
	v_sub_f32_e32 v83, v81, v83
	v_sub_f32_e32 v83, v67, v83
	v_add_f32_e32 v85, v85, v83
	v_pk_add_f32 v[66:67], v[80:81], v[66:67] neg_lo:[0,1] neg_hi:[0,1]
	v_pk_add_f32 v[86:87], v[80:81], v[84:85]
	v_mov_b32_e32 v83, v80
	v_mov_b32_e32 v67, v87
	v_pk_add_f32 v[88:89], v[82:83], v[66:67] neg_lo:[0,1] neg_hi:[0,1]
	v_pk_add_f32 v[66:67], v[82:83], v[66:67]
	v_mov_b32_e32 v92, v81
	v_pk_add_f32 v[82:83], v[66:67], v[80:81] op_sel:[1,0] op_sel_hi:[0,1] neg_lo:[0,1] neg_hi:[0,1]
	v_pk_add_f32 v[90:91], v[86:87], v[82:83] op_sel_hi:[1,0] neg_lo:[0,1] neg_hi:[0,1]
	v_mov_b32_e32 v86, v87
	v_mov_b32_e32 v87, v67
	v_mov_b32_e32 v93, v82
	v_pk_add_f32 v[82:83], v[86:87], v[92:93] neg_lo:[0,1] neg_hi:[0,1]
	v_mov_b32_e32 v84, v85
	v_mov_b32_e32 v85, v80
	v_pk_add_f32 v[80:81], v[84:85], v[82:83] neg_lo:[0,1] neg_hi:[0,1]
	v_mov_b32_e32 v90, v88
	v_pk_add_f32 v[82:83], v[90:91], v[80:81]
	v_mov_b32_e32 v89, v67
	v_pk_add_f32 v[84:85], v[82:83], v[82:83] op_sel:[0,1] op_sel_hi:[1,0]
	s_mov_b32 s1, 0x7f800000
	v_pk_add_f32 v[66:67], v[66:67], v[84:85] op_sel:[1,0] op_sel_hi:[0,1]
	v_mov_b32_e32 v83, v66
	v_pk_add_f32 v[86:87], v[82:83], v[88:89] neg_lo:[0,1] neg_hi:[0,1]
	v_mov_b32_e32 v81, v84
	v_sub_f32_e32 v67, v82, v86
	v_pk_add_f32 v[80:81], v[80:81], v[86:87] neg_lo:[0,1] neg_hi:[0,1]
	v_sub_f32_e32 v67, v88, v67
	v_add_f32_e32 v67, v80, v67
	v_add_f32_e32 v67, v67, v81
	v_add_f32_e32 v66, v66, v67
	v_mov_b32_e32 v67, 0x7f800000
	v_cmp_neq_f32_e32 vcc, s1, v94
	s_mov_b32 s1, 0x33800000
	ds_read_b32 v80, v111 offset:3072
	v_cndmask_b32_e32 v66, v67, v66, vcc
	v_mov_b32_e32 v67, 0x7fc00000
	v_cmp_ngt_f32_e32 vcc, -1.0, v94
	ds_bpermute_b32 v76, v116, v75
	ds_bpermute_b32 v77, v116, v74
	v_cndmask_b32_e32 v66, v67, v66, vcc
	v_mov_b32_e32 v67, 0xff800000
	v_cmp_neq_f32_e32 vcc, -1.0, v94
	s_nop 1
	v_cndmask_b32_e32 v66, v67, v66, vcc
	v_cmp_lt_f32_e64 vcc, |v94|, s1
	v_max_f32_e32 v67, v97, v97
	s_nop 0
	v_cndmask_b32_e32 v66, v66, v94, vcc
	v_sub_f32_e32 v66, v95, v66
	s_waitcnt vmcnt(12)
	v_add_f32_e32 v66, v115, v66
	v_max_f32_e32 v81, v66, v67
	v_sub_f32_e32 v67, v97, v81
	v_mul_f32_e32 v67, 0x3fb8aa3b, v67
	v_exp_f32_e32 v97, v67
	v_sub_f32_e32 v66, v66, v81
	v_mul_f32_e32 v66, 0x3fb8aa3b, v66
	v_exp_f32_e32 v66, v66
	s_waitcnt lgkmcnt(2)
	v_mul_f32_e32 v82, v97, v80
	v_pk_mul_f32 v[32:33], v[32:33], v[82:83] op_sel_hi:[1,0]
	v_pk_mul_f32 v[34:35], v[34:35], v[82:83] op_sel_hi:[1,0]
	v_pk_fma_f32 v[28:29], v[28:29], v[66:67], v[32:33] op_sel_hi:[1,0,1]
	v_pk_fma_f32 v[30:31], v[30:31], v[66:67], v[34:35] op_sel_hi:[1,0,1]
	global_store_dwordx4 v[64:65], v[28:31], off
	s_nop 1
	v_pk_mul_f32 v[28:29], v[36:37], v[82:83] op_sel_hi:[1,0]
	v_pk_mul_f32 v[30:31], v[38:39], v[82:83] op_sel_hi:[1,0]
	v_pk_fma_f32 v[24:25], v[24:25], v[66:67], v[28:29] op_sel_hi:[1,0,1]
	v_pk_fma_f32 v[26:27], v[26:27], v[66:67], v[30:31] op_sel_hi:[1,0,1]
	global_store_dwordx4 v[64:65], v[24:27], off offset:64
	s_nop 1
	v_pk_mul_f32 v[24:25], v[40:41], v[82:83] op_sel_hi:[1,0]
	v_pk_mul_f32 v[26:27], v[42:43], v[82:83] op_sel_hi:[1,0]
	v_pk_fma_f32 v[20:21], v[20:21], v[66:67], v[24:25] op_sel_hi:[1,0,1]
	v_pk_fma_f32 v[22:23], v[22:23], v[66:67], v[26:27] op_sel_hi:[1,0,1]
	global_store_dwordx4 v[64:65], v[20:23], off offset:128
	s_nop 1
	v_pk_mul_f32 v[20:21], v[44:45], v[82:83] op_sel_hi:[1,0]
	v_pk_mul_f32 v[22:23], v[46:47], v[82:83] op_sel_hi:[1,0]
	v_pk_fma_f32 v[16:17], v[16:17], v[66:67], v[20:21] op_sel_hi:[1,0,1]
	v_pk_fma_f32 v[18:19], v[18:19], v[66:67], v[22:23] op_sel_hi:[1,0,1]
	global_store_dwordx4 v[64:65], v[16:19], off offset:192
	s_nop 1
	v_pk_mul_f32 v[16:17], v[48:49], v[82:83] op_sel_hi:[1,0]
	v_pk_mul_f32 v[18:19], v[50:51], v[82:83] op_sel_hi:[1,0]
	v_pk_fma_f32 v[12:13], v[12:13], v[66:67], v[16:17] op_sel_hi:[1,0,1]
	v_pk_fma_f32 v[14:15], v[14:15], v[66:67], v[18:19] op_sel_hi:[1,0,1]
	global_store_dwordx4 v[64:65], v[12:15], off offset:256
	s_nop 1
	v_pk_mul_f32 v[12:13], v[52:53], v[82:83] op_sel_hi:[1,0]
	v_pk_mul_f32 v[14:15], v[54:55], v[82:83] op_sel_hi:[1,0]
	v_pk_fma_f32 v[8:9], v[8:9], v[66:67], v[12:13] op_sel_hi:[1,0,1]
	v_pk_fma_f32 v[10:11], v[10:11], v[66:67], v[14:15] op_sel_hi:[1,0,1]
	global_store_dwordx4 v[64:65], v[8:11], off offset:320
	s_nop 1
	v_pk_mul_f32 v[8:9], v[56:57], v[82:83] op_sel_hi:[1,0]
	v_pk_mul_f32 v[10:11], v[58:59], v[82:83] op_sel_hi:[1,0]
	v_pk_fma_f32 v[4:5], v[4:5], v[66:67], v[8:9] op_sel_hi:[1,0,1]
	v_pk_fma_f32 v[6:7], v[6:7], v[66:67], v[10:11] op_sel_hi:[1,0,1]
	global_store_dwordx4 v[64:65], v[4:7], off offset:384
	s_nop 1
	v_pk_mul_f32 v[4:5], v[60:61], v[82:83] op_sel_hi:[1,0]
	v_pk_mul_f32 v[6:7], v[62:63], v[82:83] op_sel_hi:[1,0]
	v_pk_fma_f32 v[0:1], v[0:1], v[66:67], v[4:5] op_sel_hi:[1,0,1]
	v_pk_fma_f32 v[2:3], v[2:3], v[66:67], v[6:7] op_sel_hi:[1,0,1]
	global_store_dwordx4 v[64:65], v[0:3], off offset:448
	s_and_saveexec_b64 s[14:15], s[2:3]
	s_cbranch_execz .LBB0_612
	v_lshl_add_u32 v0, v128, 2, 0
	ds_read_b32 v67, v0 offset:2560
	s_add_u32 s2, s26, s8
	s_addc_u32 s3, s27, s9
	v_lshlrev_b32_e32 v0, 2, v128
	v_mov_b32_e32 v1, 0
	v_lshl_add_u64 v[0:1], s[2:3], 0, v[0:1]
	s_waitcnt vmcnt(19) lgkmcnt(0)
	v_pk_mul_f32 v[2:3], v[96:97], v[66:67]
	v_add_co_u32_e32 v0, vcc, 0x761c000, v0
	v_add_f32_e32 v2, v2, v3
	s_nop 0
	v_addc_co_u32_e32 v1, vcc, 0, v1, vcc
	global_store_dword v[0:1], v2, off offset:128
